# previous but every 32-MFMA block padded to start 64-byte aligned (padding skipped by a branch in the load segment)
# baseline (speedup 1.0000x reference)
.LBB0_287:
	ds_read_b128 v[160:163], v156
	ds_read_b128 v[164:167], v156 offset:1024
	ds_read_b128 v[168:171], v156 offset:2048
	ds_read_b128 v[172:175], v156 offset:3072
	ds_read_b128 v[176:179], v157
	ds_read_b128 v[180:183], v157 offset:1024
	ds_read_b128 v[184:187], v157 offset:2048
	ds_read_b128 v[188:191], v157 offset:3072
	s_add_u32 s28, s26, 0xfff00080
	s_addc_u32 s29, s27, -1
	s_cmp_eq_u32 s58, 60
	s_cselect_b32 s31, s21, s29
	s_cselect_b32 s30, s54, s28
	s_cselect_b32 s29, s19, s57
	s_cselect_b32 s28, s55, s56
	v_lshl_add_u64 v[192:193], s[26:27], 0, v[138:139]
	s_add_i32 m0, s17, 0xc000
	ds_read_b128 v[196:199], v158
	ds_read_b128 v[200:203], v158 offset:1024
	ds_read_b128 v[204:207], v158 offset:2048
	ds_read_b128 v[208:211], v158 offset:3072
	ds_read_b128 v[212:215], v158 offset:4096
	ds_read_b128 v[216:219], v158 offset:5120
	ds_read_b128 v[220:223], v158 offset:6144
	ds_read_b128 v[224:227], v158 offset:7168
	global_load_lds_dwordx4 v[192:193], off
	v_lshl_add_u64 v[192:193], s[26:27], 0, v[140:141]
	s_add_i32 m0, s17, 0xe000
	s_nop 0
	global_load_lds_dwordx4 v[192:193], off
	s_branch .Lal64_0
	s_nop 0
	s_nop 0
	s_nop 0
	s_nop 0
	s_nop 0
	s_nop 0
	s_nop 0
	s_nop 0
.Lal64_0:
	s_waitcnt vmcnt(8)
	s_waitcnt lgkmcnt(0)
	s_barrier
	s_setprio 1
	v_mfma_f32_16x16x32_bf16 v[126:129], v[160:163], v[196:199], v[126:129]
	v_mfma_f32_16x16x32_bf16 v[122:125], v[168:171], v[196:199], v[122:125]
	v_mfma_f32_16x16x32_bf16 v[118:121], v[160:163], v[204:207], v[118:121]
	v_mfma_f32_16x16x32_bf16 v[114:117], v[168:171], v[204:207], v[114:117]
	v_mfma_f32_16x16x32_bf16 v[102:105], v[160:163], v[212:215], v[102:105]
	v_mfma_f32_16x16x32_bf16 v[98:101], v[168:171], v[212:215], v[98:101]
	v_mfma_f32_16x16x32_bf16 v[86:89], v[160:163], v[220:223], v[86:89]
	v_mfma_f32_16x16x32_bf16 v[82:85], v[168:171], v[220:223], v[82:85]
	v_mfma_f32_16x16x32_bf16 v[126:129], v[164:167], v[200:203], v[126:129]
	v_mfma_f32_16x16x32_bf16 v[122:125], v[172:175], v[200:203], v[122:125]
	v_mfma_f32_16x16x32_bf16 v[118:121], v[164:167], v[208:211], v[118:121]
	v_mfma_f32_16x16x32_bf16 v[114:117], v[172:175], v[208:211], v[114:117]
	v_mfma_f32_16x16x32_bf16 v[102:105], v[164:167], v[216:219], v[102:105]
	v_mfma_f32_16x16x32_bf16 v[98:101], v[172:175], v[216:219], v[98:101]
	v_mfma_f32_16x16x32_bf16 v[86:89], v[164:167], v[224:227], v[86:89]
	v_mfma_f32_16x16x32_bf16 v[82:85], v[172:175], v[224:227], v[82:85]
	v_mfma_f32_16x16x32_bf16 v[110:113], v[176:179], v[196:199], v[110:113]
	v_mfma_f32_16x16x32_bf16 v[106:109], v[184:187], v[196:199], v[106:109]
	v_mfma_f32_16x16x32_bf16 v[94:97], v[176:179], v[204:207], v[94:97]
	v_mfma_f32_16x16x32_bf16 v[90:93], v[184:187], v[204:207], v[90:93]
	v_mfma_f32_16x16x32_bf16 v[78:81], v[176:179], v[212:215], v[78:81]
	v_mfma_f32_16x16x32_bf16 v[74:77], v[184:187], v[212:215], v[74:77]
	v_mfma_f32_16x16x32_bf16 v[70:73], v[176:179], v[220:223], v[70:73]
	v_mfma_f32_16x16x32_bf16 v[66:69], v[184:187], v[220:223], v[66:69]
	v_mfma_f32_16x16x32_bf16 v[110:113], v[180:183], v[200:203], v[110:113]
	v_mfma_f32_16x16x32_bf16 v[106:109], v[188:191], v[200:203], v[106:109]
	v_mfma_f32_16x16x32_bf16 v[94:97], v[180:183], v[208:211], v[94:97]
	v_mfma_f32_16x16x32_bf16 v[90:93], v[188:191], v[208:211], v[90:93]
	v_mfma_f32_16x16x32_bf16 v[78:81], v[180:183], v[216:219], v[78:81]
	v_mfma_f32_16x16x32_bf16 v[74:77], v[188:191], v[216:219], v[74:77]
	v_mfma_f32_16x16x32_bf16 v[70:73], v[180:183], v[224:227], v[70:73]
	v_mfma_f32_16x16x32_bf16 v[66:69], v[188:191], v[224:227], v[66:69]
	s_setprio 0
	s_barrier
	s_add_i32 s59, s50, s41
	v_lshl_add_u64 v[192:193], s[28:29], 0, v[134:135]
	s_mov_b32 m0, s59
	ds_read_b128 v[196:199], v158 offset:16384
	ds_read_b128 v[200:203], v158 offset:17408
	ds_read_b128 v[204:207], v158 offset:18432
	ds_read_b128 v[208:211], v158 offset:19456
	ds_read_b128 v[212:215], v158 offset:20480
	ds_read_b128 v[216:219], v158 offset:21504
	ds_read_b128 v[220:223], v158 offset:22528
	ds_read_b128 v[224:227], v158 offset:23552
	global_load_lds_dwordx4 v[192:193], off
	s_add_i32 m0, s59, 0x2000
	s_add_u32 s60, s28, 0x100000
	v_lshl_add_u64 v[228:229], s[28:29], 0, v[136:137]
	s_addc_u32 s61, s29, 0
	s_add_i32 s59, s51, s41
	global_load_lds_dwordx4 v[228:229], off
	v_lshl_add_u64 v[230:231], s[60:61], 0, v[134:135]
	s_mov_b32 m0, s59
	v_lshl_add_u64 v[232:233], s[30:31], 0, v[132:133]
	global_load_lds_dwordx4 v[230:231], off
	v_lshl_add_u64 v[230:231], s[60:61], 0, v[136:137]
	s_add_i32 m0, s59, 0x2000
	s_nop 0
	global_load_lds_dwordx4 v[230:231], off
	v_lshl_add_u64 v[230:231], s[30:31], 0, v[130:131]
	s_mov_b32 m0, s17
	s_nop 0
	global_load_lds_dwordx4 v[230:231], off
	s_mov_b32 m0, s42
	s_nop 0
	global_load_lds_dwordx4 v[232:233], off
	s_branch .Lal64_1
	s_nop 0
.Lal64_1:
	s_waitcnt vmcnt(8)
	s_waitcnt lgkmcnt(0)
	s_barrier
	s_setprio 1
	v_mfma_f32_16x16x32_bf16 v[62:65], v[160:163], v[196:199], v[62:65]
	v_mfma_f32_16x16x32_bf16 v[58:61], v[168:171], v[196:199], v[58:61]
	v_mfma_f32_16x16x32_bf16 v[54:57], v[160:163], v[204:207], v[54:57]
	v_mfma_f32_16x16x32_bf16 v[50:53], v[168:171], v[204:207], v[50:53]
	v_mfma_f32_16x16x32_bf16 v[38:41], v[160:163], v[212:215], v[38:41]
	v_mfma_f32_16x16x32_bf16 v[34:37], v[168:171], v[212:215], v[34:37]
	v_mfma_f32_16x16x32_bf16 v[22:25], v[160:163], v[220:223], v[22:25]
	v_mfma_f32_16x16x32_bf16 v[18:21], v[168:171], v[220:223], v[18:21]
	v_mfma_f32_16x16x32_bf16 v[62:65], v[164:167], v[200:203], v[62:65]
	v_mfma_f32_16x16x32_bf16 v[58:61], v[172:175], v[200:203], v[58:61]
	v_mfma_f32_16x16x32_bf16 v[54:57], v[164:167], v[208:211], v[54:57]
	v_mfma_f32_16x16x32_bf16 v[50:53], v[172:175], v[208:211], v[50:53]
	v_mfma_f32_16x16x32_bf16 v[38:41], v[164:167], v[216:219], v[38:41]
	v_mfma_f32_16x16x32_bf16 v[34:37], v[172:175], v[216:219], v[34:37]
	v_mfma_f32_16x16x32_bf16 v[22:25], v[164:167], v[224:227], v[22:25]
	v_mfma_f32_16x16x32_bf16 v[18:21], v[172:175], v[224:227], v[18:21]
	v_mfma_f32_16x16x32_bf16 v[46:49], v[176:179], v[196:199], v[46:49]
	v_mfma_f32_16x16x32_bf16 v[42:45], v[184:187], v[196:199], v[42:45]
	v_mfma_f32_16x16x32_bf16 v[30:33], v[176:179], v[204:207], v[30:33]
	v_mfma_f32_16x16x32_bf16 v[26:29], v[184:187], v[204:207], v[26:29]
	v_mfma_f32_16x16x32_bf16 v[14:17], v[176:179], v[212:215], v[14:17]
	v_mfma_f32_16x16x32_bf16 v[10:13], v[184:187], v[212:215], v[10:13]
	v_mfma_f32_16x16x32_bf16 v[6:9], v[176:179], v[220:223], v[6:9]
	v_mfma_f32_16x16x32_bf16 v[2:5], v[184:187], v[220:223], v[2:5]
	v_mfma_f32_16x16x32_bf16 v[46:49], v[180:183], v[200:203], v[46:49]
	v_mfma_f32_16x16x32_bf16 v[42:45], v[188:191], v[200:203], v[42:45]
	v_mfma_f32_16x16x32_bf16 v[30:33], v[180:183], v[208:211], v[30:33]
	v_mfma_f32_16x16x32_bf16 v[26:29], v[188:191], v[208:211], v[26:29]
	v_mfma_f32_16x16x32_bf16 v[14:17], v[180:183], v[216:219], v[14:17]
	v_mfma_f32_16x16x32_bf16 v[10:13], v[188:191], v[216:219], v[10:13]
	v_mfma_f32_16x16x32_bf16 v[6:9], v[180:183], v[224:227], v[6:9]
	v_mfma_f32_16x16x32_bf16 v[2:5], v[188:191], v[224:227], v[2:5]
	s_setprio 0
	s_barrier
	s_add_i32 s59, 0, 0x18000
	v_add_u32_e32 v159, s59, v154
	s_add_i32 s60, 0, 0x1c000
	ds_read_b128 v[160:163], v159
	ds_read_b128 v[164:167], v159 offset:1024
	ds_read_b128 v[168:171], v159 offset:2048
	ds_read_b128 v[172:175], v159 offset:3072
	v_add_u32_e32 v159, s60, v154
	ds_read_b128 v[176:179], v159
	ds_read_b128 v[180:183], v159 offset:1024
	ds_read_b128 v[184:187], v159 offset:2048
	ds_read_b128 v[188:191], v159 offset:3072
	s_add_u32 s30, s30, 0x100000
	s_addc_u32 s31, s31, 0
	s_mov_b32 m0, s43
	v_lshl_add_u64 v[234:235], s[30:31], 0, v[130:131]
	ds_read_b128 v[196:199], v158 offset:32768
	ds_read_b128 v[200:203], v158 offset:33792
	ds_read_b128 v[204:207], v158 offset:34816
	ds_read_b128 v[208:211], v158 offset:35840
	ds_read_b128 v[212:215], v158 offset:36864
	ds_read_b128 v[216:219], v158 offset:37888
	ds_read_b128 v[220:223], v158 offset:38912
	ds_read_b128 v[224:227], v158 offset:39936
	global_load_lds_dwordx4 v[234:235], off
	v_lshl_add_u64 v[234:235], s[30:31], 0, v[132:133]
	s_mov_b32 m0, s45
	s_nop 0
	global_load_lds_dwordx4 v[234:235], off
	s_branch .Lal64_2
	s_nop 0
	s_nop 0
	s_nop 0
	s_nop 0
	s_nop 0
.Lal64_2:
	s_waitcnt vmcnt(8)
	s_waitcnt lgkmcnt(0)
	s_barrier
	s_setprio 1
	v_mfma_f32_16x16x32_bf16 v[126:129], v[160:163], v[196:199], v[126:129]
	v_mfma_f32_16x16x32_bf16 v[122:125], v[168:171], v[196:199], v[122:125]
	v_mfma_f32_16x16x32_bf16 v[118:121], v[160:163], v[204:207], v[118:121]
	v_mfma_f32_16x16x32_bf16 v[114:117], v[168:171], v[204:207], v[114:117]
	v_mfma_f32_16x16x32_bf16 v[102:105], v[160:163], v[212:215], v[102:105]
	v_mfma_f32_16x16x32_bf16 v[98:101], v[168:171], v[212:215], v[98:101]
	v_mfma_f32_16x16x32_bf16 v[86:89], v[160:163], v[220:223], v[86:89]
	v_mfma_f32_16x16x32_bf16 v[82:85], v[168:171], v[220:223], v[82:85]
	v_mfma_f32_16x16x32_bf16 v[126:129], v[164:167], v[200:203], v[126:129]
	v_mfma_f32_16x16x32_bf16 v[122:125], v[172:175], v[200:203], v[122:125]
	v_mfma_f32_16x16x32_bf16 v[118:121], v[164:167], v[208:211], v[118:121]
	v_mfma_f32_16x16x32_bf16 v[114:117], v[172:175], v[208:211], v[114:117]
	v_mfma_f32_16x16x32_bf16 v[102:105], v[164:167], v[216:219], v[102:105]
	v_mfma_f32_16x16x32_bf16 v[98:101], v[172:175], v[216:219], v[98:101]
	v_mfma_f32_16x16x32_bf16 v[86:89], v[164:167], v[224:227], v[86:89]
	v_mfma_f32_16x16x32_bf16 v[82:85], v[172:175], v[224:227], v[82:85]
	v_mfma_f32_16x16x32_bf16 v[110:113], v[176:179], v[196:199], v[110:113]
	v_mfma_f32_16x16x32_bf16 v[106:109], v[184:187], v[196:199], v[106:109]
	v_mfma_f32_16x16x32_bf16 v[94:97], v[176:179], v[204:207], v[94:97]
	v_mfma_f32_16x16x32_bf16 v[90:93], v[184:187], v[204:207], v[90:93]
	v_mfma_f32_16x16x32_bf16 v[78:81], v[176:179], v[212:215], v[78:81]
	v_mfma_f32_16x16x32_bf16 v[74:77], v[184:187], v[212:215], v[74:77]
	v_mfma_f32_16x16x32_bf16 v[70:73], v[176:179], v[220:223], v[70:73]
	v_mfma_f32_16x16x32_bf16 v[66:69], v[184:187], v[220:223], v[66:69]
	v_mfma_f32_16x16x32_bf16 v[110:113], v[180:183], v[200:203], v[110:113]
	v_mfma_f32_16x16x32_bf16 v[106:109], v[188:191], v[200:203], v[106:109]
	v_mfma_f32_16x16x32_bf16 v[94:97], v[180:183], v[208:211], v[94:97]
	v_mfma_f32_16x16x32_bf16 v[90:93], v[188:191], v[208:211], v[90:93]
	v_mfma_f32_16x16x32_bf16 v[78:81], v[180:183], v[216:219], v[78:81]
	v_mfma_f32_16x16x32_bf16 v[74:77], v[188:191], v[216:219], v[74:77]
	v_mfma_f32_16x16x32_bf16 v[70:73], v[180:183], v[224:227], v[70:73]
	v_mfma_f32_16x16x32_bf16 v[66:69], v[188:191], v[224:227], v[66:69]
	s_setprio 0
	s_barrier
	s_add_i32 s30, s59, s41
	v_lshl_add_u64 v[192:193], v[192:193], 0, s[12:13]
	s_mov_b32 m0, s30
	ds_read_b128 v[196:199], v158 offset:49152
	ds_read_b128 v[200:203], v158 offset:50176
	ds_read_b128 v[204:207], v158 offset:51200
	ds_read_b128 v[208:211], v158 offset:52224
	ds_read_b128 v[212:215], v158 offset:53248
	ds_read_b128 v[216:219], v158 offset:54272
	ds_read_b128 v[220:223], v158 offset:55296
	ds_read_b128 v[224:227], v158 offset:56320
	global_load_lds_dwordx4 v[192:193], off
	s_add_i32 m0, s30, 0x2000
	s_add_u32 s28, s28, 0x100080
	v_lshl_add_u64 v[192:193], v[228:229], 0, s[12:13]
	s_addc_u32 s29, s29, 0
	s_add_i32 s30, s60, s41
	global_load_lds_dwordx4 v[192:193], off
	v_lshl_add_u64 v[192:193], s[28:29], 0, v[134:135]
	s_mov_b32 m0, s30
	s_nop 0
	global_load_lds_dwordx4 v[192:193], off
	v_lshl_add_u64 v[192:193], s[28:29], 0, v[136:137]
	s_add_i32 m0, s30, 0x2000
	s_nop 0
	global_load_lds_dwordx4 v[192:193], off
	v_lshl_add_u64 v[192:193], v[230:231], 0, s[12:13]
	s_mov_b32 m0, s47
	s_nop 0
	global_load_lds_dwordx4 v[192:193], off
	v_lshl_add_u64 v[192:193], v[232:233], 0, s[12:13]
	s_mov_b32 m0, s48
	s_nop 0
	global_load_lds_dwordx4 v[192:193], off
	s_branch .Lal64_3
.Lal64_3:
	s_waitcnt vmcnt(8)
	s_waitcnt lgkmcnt(0)
	s_barrier
	s_setprio 1
	v_mfma_f32_16x16x32_bf16 v[62:65], v[160:163], v[196:199], v[62:65]
	v_mfma_f32_16x16x32_bf16 v[58:61], v[168:171], v[196:199], v[58:61]
	v_mfma_f32_16x16x32_bf16 v[54:57], v[160:163], v[204:207], v[54:57]
	v_mfma_f32_16x16x32_bf16 v[50:53], v[168:171], v[204:207], v[50:53]
	v_mfma_f32_16x16x32_bf16 v[38:41], v[160:163], v[212:215], v[38:41]
	v_mfma_f32_16x16x32_bf16 v[34:37], v[168:171], v[212:215], v[34:37]
	v_mfma_f32_16x16x32_bf16 v[22:25], v[160:163], v[220:223], v[22:25]
	v_mfma_f32_16x16x32_bf16 v[18:21], v[168:171], v[220:223], v[18:21]
	v_mfma_f32_16x16x32_bf16 v[62:65], v[164:167], v[200:203], v[62:65]
	v_mfma_f32_16x16x32_bf16 v[58:61], v[172:175], v[200:203], v[58:61]
	v_mfma_f32_16x16x32_bf16 v[54:57], v[164:167], v[208:211], v[54:57]
	v_mfma_f32_16x16x32_bf16 v[50:53], v[172:175], v[208:211], v[50:53]
	v_mfma_f32_16x16x32_bf16 v[38:41], v[164:167], v[216:219], v[38:41]
	v_mfma_f32_16x16x32_bf16 v[34:37], v[172:175], v[216:219], v[34:37]
	v_mfma_f32_16x16x32_bf16 v[22:25], v[164:167], v[224:227], v[22:25]
	v_mfma_f32_16x16x32_bf16 v[18:21], v[172:175], v[224:227], v[18:21]
	v_mfma_f32_16x16x32_bf16 v[46:49], v[176:179], v[196:199], v[46:49]
	v_mfma_f32_16x16x32_bf16 v[42:45], v[184:187], v[196:199], v[42:45]
	v_mfma_f32_16x16x32_bf16 v[30:33], v[176:179], v[204:207], v[30:33]
	v_mfma_f32_16x16x32_bf16 v[26:29], v[184:187], v[204:207], v[26:29]
	v_mfma_f32_16x16x32_bf16 v[14:17], v[176:179], v[212:215], v[14:17]
	v_mfma_f32_16x16x32_bf16 v[10:13], v[184:187], v[212:215], v[10:13]
	v_mfma_f32_16x16x32_bf16 v[6:9], v[176:179], v[220:223], v[6:9]
	v_mfma_f32_16x16x32_bf16 v[2:5], v[184:187], v[220:223], v[2:5]
	v_mfma_f32_16x16x32_bf16 v[46:49], v[180:183], v[200:203], v[46:49]
	v_mfma_f32_16x16x32_bf16 v[42:45], v[188:191], v[200:203], v[42:45]
	v_mfma_f32_16x16x32_bf16 v[30:33], v[180:183], v[208:211], v[30:33]
	v_mfma_f32_16x16x32_bf16 v[26:29], v[188:191], v[208:211], v[26:29]
	v_mfma_f32_16x16x32_bf16 v[14:17], v[180:183], v[216:219], v[14:17]
	v_mfma_f32_16x16x32_bf16 v[10:13], v[188:191], v[216:219], v[10:13]
	v_mfma_f32_16x16x32_bf16 v[6:9], v[180:183], v[224:227], v[6:9]
	v_mfma_f32_16x16x32_bf16 v[2:5], v[188:191], v[224:227], v[2:5]
	s_setprio 0
	s_barrier
	s_add_i32 s58, s58, 2
	s_add_u32 s26, s26, 0x100
	s_addc_u32 s27, s27, 0
	s_add_u32 s56, s56, 0x100
	s_addc_u32 s57, s57, 0
	s_cmp_gt_u32 s58, 61
	s_cbranch_scc0 .LBB0_287
	s_and_b64 vcc, exec, s[14:15]
	s_cbranch_vccz .LBB0_290
	s_barrier

.LBB0_311:
	ds_read_b128 v[152:155], v144
	ds_read_b128 v[156:159], v144 offset:1024
	ds_read_b128 v[160:163], v144 offset:2048
	ds_read_b128 v[164:167], v144 offset:3072
	ds_read_b128 v[168:171], v145
	ds_read_b128 v[172:175], v145 offset:1024
	ds_read_b128 v[176:179], v145 offset:2048
	ds_read_b128 v[180:183], v145 offset:3072
	s_add_u32 s42, s40, 0xfff00080
	s_addc_u32 s43, s41, -1
	s_cmp_eq_u32 s70, 60
	s_cselect_b32 s47, s27, s43
	s_cselect_b32 s46, s66, s42
	s_cselect_b32 s43, s25, s69
	s_cselect_b32 s42, s67, s68
	v_lshl_add_u64 v[192:193], s[40:41], 0, v[134:135]
	s_add_i32 m0, s29, 0xc000
	ds_read_b128 v[184:187], v151
	ds_read_b128 v[188:191], v151 offset:1024
	ds_read_b128 v[196:199], v151 offset:2048
	ds_read_b128 v[200:203], v151 offset:3072
	ds_read_b128 v[204:207], v151 offset:4096
	ds_read_b128 v[208:211], v151 offset:5120
	ds_read_b128 v[212:215], v151 offset:6144
	ds_read_b128 v[216:219], v151 offset:7168
	global_load_lds_dwordx4 v[192:193], off
	v_lshl_add_u64 v[192:193], s[40:41], 0, v[136:137]
	s_add_i32 m0, s29, 0xe000
	s_nop 0
	global_load_lds_dwordx4 v[192:193], off
	s_branch .Lal64_4
	s_nop 0
.Lal64_4:
	s_waitcnt vmcnt(8)
	s_waitcnt lgkmcnt(0)
	s_barrier
	s_setprio 1
	v_mfma_f32_16x16x32_bf16 v[126:129], v[152:155], v[184:187], v[126:129]
	v_mfma_f32_16x16x32_bf16 v[122:125], v[160:163], v[184:187], v[122:125]
	v_mfma_f32_16x16x32_bf16 v[118:121], v[152:155], v[196:199], v[118:121]
	v_mfma_f32_16x16x32_bf16 v[110:113], v[160:163], v[196:199], v[110:113]
	v_mfma_f32_16x16x32_bf16 v[102:105], v[152:155], v[204:207], v[102:105]
	v_mfma_f32_16x16x32_bf16 v[94:97], v[160:163], v[204:207], v[94:97]
	v_mfma_f32_16x16x32_bf16 v[86:89], v[152:155], v[212:215], v[86:89]
	v_mfma_f32_16x16x32_bf16 v[78:81], v[160:163], v[212:215], v[78:81]
	v_mfma_f32_16x16x32_bf16 v[126:129], v[156:159], v[188:191], v[126:129]
	v_mfma_f32_16x16x32_bf16 v[122:125], v[164:167], v[188:191], v[122:125]
	v_mfma_f32_16x16x32_bf16 v[118:121], v[156:159], v[200:203], v[118:121]
	v_mfma_f32_16x16x32_bf16 v[110:113], v[164:167], v[200:203], v[110:113]
	v_mfma_f32_16x16x32_bf16 v[102:105], v[156:159], v[208:211], v[102:105]
	v_mfma_f32_16x16x32_bf16 v[94:97], v[164:167], v[208:211], v[94:97]
	v_mfma_f32_16x16x32_bf16 v[86:89], v[156:159], v[216:219], v[86:89]
	v_mfma_f32_16x16x32_bf16 v[78:81], v[164:167], v[216:219], v[78:81]
	v_mfma_f32_16x16x32_bf16 v[114:117], v[168:171], v[184:187], v[114:117]
	v_mfma_f32_16x16x32_bf16 v[106:109], v[176:179], v[184:187], v[106:109]
	v_mfma_f32_16x16x32_bf16 v[98:101], v[168:171], v[196:199], v[98:101]
	v_mfma_f32_16x16x32_bf16 v[90:93], v[176:179], v[196:199], v[90:93]
	v_mfma_f32_16x16x32_bf16 v[82:85], v[168:171], v[204:207], v[82:85]
	v_mfma_f32_16x16x32_bf16 v[74:77], v[176:179], v[204:207], v[74:77]
	v_mfma_f32_16x16x32_bf16 v[70:73], v[168:171], v[212:215], v[70:73]
	v_mfma_f32_16x16x32_bf16 v[66:69], v[176:179], v[212:215], v[66:69]
	v_mfma_f32_16x16x32_bf16 v[114:117], v[172:175], v[188:191], v[114:117]
	v_mfma_f32_16x16x32_bf16 v[106:109], v[180:183], v[188:191], v[106:109]
	v_mfma_f32_16x16x32_bf16 v[98:101], v[172:175], v[200:203], v[98:101]
	v_mfma_f32_16x16x32_bf16 v[90:93], v[180:183], v[200:203], v[90:93]
	v_mfma_f32_16x16x32_bf16 v[82:85], v[172:175], v[208:211], v[82:85]
	v_mfma_f32_16x16x32_bf16 v[74:77], v[180:183], v[208:211], v[74:77]
	v_mfma_f32_16x16x32_bf16 v[70:73], v[172:175], v[216:219], v[70:73]
	v_mfma_f32_16x16x32_bf16 v[66:69], v[180:183], v[216:219], v[66:69]
	s_setprio 0
	s_barrier
	s_add_i32 s71, s62, s54
	v_lshl_add_u64 v[192:193], s[42:43], 0, v[130:131]
	s_mov_b32 m0, s71
	ds_read_b128 v[184:187], v151 offset:16384
	ds_read_b128 v[188:191], v151 offset:17408
	ds_read_b128 v[196:199], v151 offset:18432
	ds_read_b128 v[200:203], v151 offset:19456
	ds_read_b128 v[204:207], v151 offset:20480
	ds_read_b128 v[208:211], v151 offset:21504
	ds_read_b128 v[212:215], v151 offset:22528
	ds_read_b128 v[216:219], v151 offset:23552
	global_load_lds_dwordx4 v[192:193], off
	s_add_i32 m0, s71, 0x2000
	s_add_u32 s72, s42, 0x100000
	v_lshl_add_u64 v[220:221], s[42:43], 0, v[132:133]
	s_addc_u32 s73, s43, 0
	s_add_i32 s71, s63, s54
	global_load_lds_dwordx4 v[220:221], off
	v_lshl_add_u64 v[222:223], s[72:73], 0, v[130:131]
	s_mov_b32 m0, s71
	v_lshl_add_u64 v[224:225], s[46:47], 0, v[132:133]
	global_load_lds_dwordx4 v[222:223], off
	v_lshl_add_u64 v[222:223], s[72:73], 0, v[132:133]
	s_add_i32 m0, s71, 0x2000
	s_nop 0
	global_load_lds_dwordx4 v[222:223], off
	v_lshl_add_u64 v[222:223], s[46:47], 0, v[130:131]
	s_mov_b32 m0, s29
	s_nop 0
	global_load_lds_dwordx4 v[222:223], off
	s_mov_b32 m0, s55
	s_nop 0
	global_load_lds_dwordx4 v[224:225], off
	s_branch .Lal64_5
	s_nop 0
.Lal64_5:
	s_waitcnt vmcnt(8)
	s_waitcnt lgkmcnt(0)
	s_barrier
	s_setprio 1
	v_mfma_f32_16x16x32_bf16 v[62:65], v[152:155], v[184:187], v[62:65]
	v_mfma_f32_16x16x32_bf16 v[58:61], v[160:163], v[184:187], v[58:61]
	v_mfma_f32_16x16x32_bf16 v[54:57], v[152:155], v[196:199], v[54:57]
	v_mfma_f32_16x16x32_bf16 v[46:49], v[160:163], v[196:199], v[46:49]
	v_mfma_f32_16x16x32_bf16 v[38:41], v[152:155], v[204:207], v[38:41]
	v_mfma_f32_16x16x32_bf16 v[30:33], v[160:163], v[204:207], v[30:33]
	v_mfma_f32_16x16x32_bf16 v[22:25], v[152:155], v[212:215], v[22:25]
	v_mfma_f32_16x16x32_bf16 v[14:17], v[160:163], v[212:215], v[14:17]
	v_mfma_f32_16x16x32_bf16 v[62:65], v[156:159], v[188:191], v[62:65]
	v_mfma_f32_16x16x32_bf16 v[58:61], v[164:167], v[188:191], v[58:61]
	v_mfma_f32_16x16x32_bf16 v[54:57], v[156:159], v[200:203], v[54:57]
	v_mfma_f32_16x16x32_bf16 v[46:49], v[164:167], v[200:203], v[46:49]
	v_mfma_f32_16x16x32_bf16 v[38:41], v[156:159], v[208:211], v[38:41]
	v_mfma_f32_16x16x32_bf16 v[30:33], v[164:167], v[208:211], v[30:33]
	v_mfma_f32_16x16x32_bf16 v[22:25], v[156:159], v[216:219], v[22:25]
	v_mfma_f32_16x16x32_bf16 v[14:17], v[164:167], v[216:219], v[14:17]
	v_mfma_f32_16x16x32_bf16 v[50:53], v[168:171], v[184:187], v[50:53]
	v_mfma_f32_16x16x32_bf16 v[42:45], v[176:179], v[184:187], v[42:45]
	v_mfma_f32_16x16x32_bf16 v[34:37], v[168:171], v[196:199], v[34:37]
	v_mfma_f32_16x16x32_bf16 v[26:29], v[176:179], v[196:199], v[26:29]
	v_mfma_f32_16x16x32_bf16 v[18:21], v[168:171], v[204:207], v[18:21]
	v_mfma_f32_16x16x32_bf16 v[10:13], v[176:179], v[204:207], v[10:13]
	v_mfma_f32_16x16x32_bf16 v[6:9], v[168:171], v[212:215], v[6:9]
	v_mfma_f32_16x16x32_bf16 v[2:5], v[176:179], v[212:215], v[2:5]
	v_mfma_f32_16x16x32_bf16 v[50:53], v[172:175], v[188:191], v[50:53]
	v_mfma_f32_16x16x32_bf16 v[42:45], v[180:183], v[188:191], v[42:45]
	v_mfma_f32_16x16x32_bf16 v[34:37], v[172:175], v[200:203], v[34:37]
	v_mfma_f32_16x16x32_bf16 v[26:29], v[180:183], v[200:203], v[26:29]
	v_mfma_f32_16x16x32_bf16 v[18:21], v[172:175], v[208:211], v[18:21]
	v_mfma_f32_16x16x32_bf16 v[10:13], v[180:183], v[208:211], v[10:13]
	v_mfma_f32_16x16x32_bf16 v[6:9], v[172:175], v[216:219], v[6:9]
	v_mfma_f32_16x16x32_bf16 v[2:5], v[180:183], v[216:219], v[2:5]
	s_setprio 0
	s_barrier
	s_add_i32 s71, 0, 0x18000
	s_add_i32 s72, 0, 0x1c000
	v_add_u32_e32 v164, s71, v142
	v_add_u32_e32 v180, s72, v142
	ds_read_b128 v[152:155], v164
	ds_read_b128 v[156:159], v164 offset:1024
	ds_read_b128 v[160:163], v164 offset:2048
	ds_read_b128 v[164:167], v164 offset:3072
	ds_read_b128 v[168:171], v180
	ds_read_b128 v[172:175], v180 offset:1024
	ds_read_b128 v[176:179], v180 offset:2048
	ds_read_b128 v[180:183], v180 offset:3072
	s_add_u32 s46, s46, 0x100000
	s_addc_u32 s47, s47, 0
	s_mov_b32 m0, s56
	v_lshl_add_u64 v[226:227], s[46:47], 0, v[130:131]
	ds_read_b128 v[184:187], v151 offset:32768
	ds_read_b128 v[188:191], v151 offset:33792
	ds_read_b128 v[196:199], v151 offset:34816
	ds_read_b128 v[200:203], v151 offset:35840
	ds_read_b128 v[204:207], v151 offset:36864
	ds_read_b128 v[208:211], v151 offset:37888
	ds_read_b128 v[212:215], v151 offset:38912
	ds_read_b128 v[216:219], v151 offset:39936
	global_load_lds_dwordx4 v[226:227], off
	v_lshl_add_u64 v[226:227], s[46:47], 0, v[132:133]
	s_mov_b32 m0, s57
	s_nop 0
	global_load_lds_dwordx4 v[226:227], off
	s_branch .Lal64_6
	s_nop 0
	s_nop 0
	s_nop 0
	s_nop 0
	s_nop 0
.Lal64_6:
	s_waitcnt vmcnt(8)
	s_waitcnt lgkmcnt(0)
	s_barrier
	s_setprio 1
	v_mfma_f32_16x16x32_bf16 v[126:129], v[152:155], v[184:187], v[126:129]
	v_mfma_f32_16x16x32_bf16 v[122:125], v[160:163], v[184:187], v[122:125]
	v_mfma_f32_16x16x32_bf16 v[118:121], v[152:155], v[196:199], v[118:121]
	v_mfma_f32_16x16x32_bf16 v[110:113], v[160:163], v[196:199], v[110:113]
	v_mfma_f32_16x16x32_bf16 v[102:105], v[152:155], v[204:207], v[102:105]
	v_mfma_f32_16x16x32_bf16 v[94:97], v[160:163], v[204:207], v[94:97]
	v_mfma_f32_16x16x32_bf16 v[86:89], v[152:155], v[212:215], v[86:89]
	v_mfma_f32_16x16x32_bf16 v[78:81], v[160:163], v[212:215], v[78:81]
	v_mfma_f32_16x16x32_bf16 v[126:129], v[156:159], v[188:191], v[126:129]
	v_mfma_f32_16x16x32_bf16 v[122:125], v[164:167], v[188:191], v[122:125]
	v_mfma_f32_16x16x32_bf16 v[118:121], v[156:159], v[200:203], v[118:121]
	v_mfma_f32_16x16x32_bf16 v[110:113], v[164:167], v[200:203], v[110:113]
	v_mfma_f32_16x16x32_bf16 v[102:105], v[156:159], v[208:211], v[102:105]
	v_mfma_f32_16x16x32_bf16 v[94:97], v[164:167], v[208:211], v[94:97]
	v_mfma_f32_16x16x32_bf16 v[86:89], v[156:159], v[216:219], v[86:89]
	v_mfma_f32_16x16x32_bf16 v[78:81], v[164:167], v[216:219], v[78:81]
	v_mfma_f32_16x16x32_bf16 v[114:117], v[168:171], v[184:187], v[114:117]
	v_mfma_f32_16x16x32_bf16 v[106:109], v[176:179], v[184:187], v[106:109]
	v_mfma_f32_16x16x32_bf16 v[98:101], v[168:171], v[196:199], v[98:101]
	v_mfma_f32_16x16x32_bf16 v[90:93], v[176:179], v[196:199], v[90:93]
	v_mfma_f32_16x16x32_bf16 v[82:85], v[168:171], v[204:207], v[82:85]
	v_mfma_f32_16x16x32_bf16 v[74:77], v[176:179], v[204:207], v[74:77]
	v_mfma_f32_16x16x32_bf16 v[70:73], v[168:171], v[212:215], v[70:73]
	v_mfma_f32_16x16x32_bf16 v[66:69], v[176:179], v[212:215], v[66:69]
	v_mfma_f32_16x16x32_bf16 v[114:117], v[172:175], v[188:191], v[114:117]
	v_mfma_f32_16x16x32_bf16 v[106:109], v[180:183], v[188:191], v[106:109]
	v_mfma_f32_16x16x32_bf16 v[98:101], v[172:175], v[200:203], v[98:101]
	v_mfma_f32_16x16x32_bf16 v[90:93], v[180:183], v[200:203], v[90:93]
	v_mfma_f32_16x16x32_bf16 v[82:85], v[172:175], v[208:211], v[82:85]
	v_mfma_f32_16x16x32_bf16 v[74:77], v[180:183], v[208:211], v[74:77]
	v_mfma_f32_16x16x32_bf16 v[70:73], v[172:175], v[216:219], v[70:73]
	v_mfma_f32_16x16x32_bf16 v[66:69], v[180:183], v[216:219], v[66:69]
	s_setprio 0
	s_barrier
	s_add_i32 s46, s71, s54
	v_lshl_add_u64 v[192:193], v[192:193], 0, s[10:11]
	s_mov_b32 m0, s46
	ds_read_b128 v[184:187], v151 offset:49152
	ds_read_b128 v[188:191], v151 offset:50176
	ds_read_b128 v[196:199], v151 offset:51200
	ds_read_b128 v[200:203], v151 offset:52224
	ds_read_b128 v[204:207], v151 offset:53248
	ds_read_b128 v[208:211], v151 offset:54272
	ds_read_b128 v[212:215], v151 offset:55296
	ds_read_b128 v[216:219], v151 offset:56320
	global_load_lds_dwordx4 v[192:193], off
	s_add_i32 m0, s46, 0x2000
	s_add_u32 s42, s42, 0x100080
	v_lshl_add_u64 v[192:193], v[220:221], 0, s[10:11]
	s_addc_u32 s43, s43, 0
	s_add_i32 s46, s72, s54
	global_load_lds_dwordx4 v[192:193], off
	v_lshl_add_u64 v[192:193], s[42:43], 0, v[130:131]
	s_mov_b32 m0, s46
	s_nop 0
	global_load_lds_dwordx4 v[192:193], off
	v_lshl_add_u64 v[192:193], s[42:43], 0, v[132:133]
	s_add_i32 m0, s46, 0x2000
	s_nop 0
	global_load_lds_dwordx4 v[192:193], off
	v_lshl_add_u64 v[192:193], v[222:223], 0, s[10:11]
	s_mov_b32 m0, s59
	s_nop 0
	global_load_lds_dwordx4 v[192:193], off
	v_lshl_add_u64 v[192:193], v[224:225], 0, s[10:11]
	s_mov_b32 m0, s60
	s_nop 0
	global_load_lds_dwordx4 v[192:193], off
	s_branch .Lal64_7
.Lal64_7:
	s_waitcnt vmcnt(8)
	s_waitcnt lgkmcnt(0)
	s_barrier
	s_setprio 1
	v_mfma_f32_16x16x32_bf16 v[62:65], v[152:155], v[184:187], v[62:65]
	v_mfma_f32_16x16x32_bf16 v[58:61], v[160:163], v[184:187], v[58:61]
	v_mfma_f32_16x16x32_bf16 v[54:57], v[152:155], v[196:199], v[54:57]
	v_mfma_f32_16x16x32_bf16 v[46:49], v[160:163], v[196:199], v[46:49]
	v_mfma_f32_16x16x32_bf16 v[38:41], v[152:155], v[204:207], v[38:41]
	v_mfma_f32_16x16x32_bf16 v[30:33], v[160:163], v[204:207], v[30:33]
	v_mfma_f32_16x16x32_bf16 v[22:25], v[152:155], v[212:215], v[22:25]
	v_mfma_f32_16x16x32_bf16 v[14:17], v[160:163], v[212:215], v[14:17]
	v_mfma_f32_16x16x32_bf16 v[62:65], v[156:159], v[188:191], v[62:65]
	v_mfma_f32_16x16x32_bf16 v[58:61], v[164:167], v[188:191], v[58:61]
	v_mfma_f32_16x16x32_bf16 v[54:57], v[156:159], v[200:203], v[54:57]
	v_mfma_f32_16x16x32_bf16 v[46:49], v[164:167], v[200:203], v[46:49]
	v_mfma_f32_16x16x32_bf16 v[38:41], v[156:159], v[208:211], v[38:41]
	v_mfma_f32_16x16x32_bf16 v[30:33], v[164:167], v[208:211], v[30:33]
	v_mfma_f32_16x16x32_bf16 v[22:25], v[156:159], v[216:219], v[22:25]
	v_mfma_f32_16x16x32_bf16 v[14:17], v[164:167], v[216:219], v[14:17]
	v_mfma_f32_16x16x32_bf16 v[50:53], v[168:171], v[184:187], v[50:53]
	v_mfma_f32_16x16x32_bf16 v[42:45], v[176:179], v[184:187], v[42:45]
	v_mfma_f32_16x16x32_bf16 v[34:37], v[168:171], v[196:199], v[34:37]
	v_mfma_f32_16x16x32_bf16 v[26:29], v[176:179], v[196:199], v[26:29]
	v_mfma_f32_16x16x32_bf16 v[18:21], v[168:171], v[204:207], v[18:21]
	v_mfma_f32_16x16x32_bf16 v[10:13], v[176:179], v[204:207], v[10:13]
	v_mfma_f32_16x16x32_bf16 v[6:9], v[168:171], v[212:215], v[6:9]
	v_mfma_f32_16x16x32_bf16 v[2:5], v[176:179], v[212:215], v[2:5]
	v_mfma_f32_16x16x32_bf16 v[50:53], v[172:175], v[188:191], v[50:53]
	v_mfma_f32_16x16x32_bf16 v[42:45], v[180:183], v[188:191], v[42:45]
	v_mfma_f32_16x16x32_bf16 v[34:37], v[172:175], v[200:203], v[34:37]
	v_mfma_f32_16x16x32_bf16 v[26:29], v[180:183], v[200:203], v[26:29]
	v_mfma_f32_16x16x32_bf16 v[18:21], v[172:175], v[208:211], v[18:21]
	v_mfma_f32_16x16x32_bf16 v[10:13], v[180:183], v[208:211], v[10:13]
	v_mfma_f32_16x16x32_bf16 v[6:9], v[172:175], v[216:219], v[6:9]
	v_mfma_f32_16x16x32_bf16 v[2:5], v[180:183], v[216:219], v[2:5]
	s_setprio 0
	s_barrier
	s_add_i32 s70, s70, 2
	s_add_u32 s40, s40, 0x100
	s_addc_u32 s41, s41, 0
	s_add_u32 s68, s68, 0x100
	s_addc_u32 s69, s69, 0
	s_cmp_gt_u32 s70, 61
	s_cbranch_scc0 .LBB0_311
	s_and_b64 vcc, exec, s[12:13]
	s_cbranch_vccz .LBB0_314
	s_barrier

.LBB0_335:
	ds_read_b128 v[144:147], v140
	ds_read_b128 v[148:151], v140 offset:1024
	ds_read_b128 v[152:155], v140 offset:2048
	ds_read_b128 v[156:159], v140 offset:3072
	ds_read_b128 v[160:163], v142
	ds_read_b128 v[164:167], v142 offset:1024
	ds_read_b128 v[168:171], v142 offset:2048
	ds_read_b128 v[172:175], v142 offset:3072
	s_add_u32 s42, s40, 0xfff00080
	s_addc_u32 s43, s41, -1
	s_cmp_eq_u32 s67, 60
	s_cselect_b32 s47, s27, s43
	s_cselect_b32 s46, s63, s42
	s_cselect_b32 s43, s25, s66
	s_cselect_b32 s42, s64, s65
	v_lshl_add_u64 v[192:193], s[40:41], 0, v[134:135]
	s_add_i32 m0, s29, 0xc000
	ds_read_b128 v[176:179], v143
	ds_read_b128 v[180:183], v143 offset:1024
	ds_read_b128 v[184:187], v143 offset:2048
	ds_read_b128 v[188:191], v143 offset:3072
	ds_read_b128 v[196:199], v143 offset:4096
	ds_read_b128 v[200:203], v143 offset:5120
	ds_read_b128 v[204:207], v143 offset:6144
	ds_read_b128 v[208:211], v143 offset:7168
	global_load_lds_dwordx4 v[192:193], off
	v_lshl_add_u64 v[192:193], s[40:41], 0, v[136:137]
	s_add_i32 m0, s29, 0xe000
	s_nop 0
	global_load_lds_dwordx4 v[192:193], off
	s_branch .Lal64_8
	s_nop 0
	s_nop 0
	s_nop 0
	s_nop 0
	s_nop 0
	s_nop 0
	s_nop 0
	s_nop 0
	s_nop 0
	s_nop 0
	s_nop 0
	s_nop 0
	s_nop 0
.Lal64_8:
	s_waitcnt vmcnt(8)
	s_waitcnt lgkmcnt(0)
	s_barrier
	s_setprio 1
	v_mfma_f32_16x16x32_bf16 v[126:129], v[144:147], v[176:179], v[126:129]
	v_mfma_f32_16x16x32_bf16 v[122:125], v[152:155], v[176:179], v[122:125]
	v_mfma_f32_16x16x32_bf16 v[118:121], v[144:147], v[184:187], v[118:121]
	v_mfma_f32_16x16x32_bf16 v[110:113], v[152:155], v[184:187], v[110:113]
	v_mfma_f32_16x16x32_bf16 v[102:105], v[144:147], v[196:199], v[102:105]
	v_mfma_f32_16x16x32_bf16 v[94:97], v[152:155], v[196:199], v[94:97]
	v_mfma_f32_16x16x32_bf16 v[86:89], v[144:147], v[204:207], v[86:89]
	v_mfma_f32_16x16x32_bf16 v[78:81], v[152:155], v[204:207], v[78:81]
	v_mfma_f32_16x16x32_bf16 v[126:129], v[148:151], v[180:183], v[126:129]
	v_mfma_f32_16x16x32_bf16 v[122:125], v[156:159], v[180:183], v[122:125]
	v_mfma_f32_16x16x32_bf16 v[118:121], v[148:151], v[188:191], v[118:121]
	v_mfma_f32_16x16x32_bf16 v[110:113], v[156:159], v[188:191], v[110:113]
	v_mfma_f32_16x16x32_bf16 v[102:105], v[148:151], v[200:203], v[102:105]
	v_mfma_f32_16x16x32_bf16 v[94:97], v[156:159], v[200:203], v[94:97]
	v_mfma_f32_16x16x32_bf16 v[86:89], v[148:151], v[208:211], v[86:89]
	v_mfma_f32_16x16x32_bf16 v[78:81], v[156:159], v[208:211], v[78:81]
	v_mfma_f32_16x16x32_bf16 v[114:117], v[160:163], v[176:179], v[114:117]
	v_mfma_f32_16x16x32_bf16 v[106:109], v[168:171], v[176:179], v[106:109]
	v_mfma_f32_16x16x32_bf16 v[98:101], v[160:163], v[184:187], v[98:101]
	v_mfma_f32_16x16x32_bf16 v[90:93], v[168:171], v[184:187], v[90:93]
	v_mfma_f32_16x16x32_bf16 v[82:85], v[160:163], v[196:199], v[82:85]
	v_mfma_f32_16x16x32_bf16 v[74:77], v[168:171], v[196:199], v[74:77]
	v_mfma_f32_16x16x32_bf16 v[70:73], v[160:163], v[204:207], v[70:73]
	v_mfma_f32_16x16x32_bf16 v[66:69], v[168:171], v[204:207], v[66:69]
	v_mfma_f32_16x16x32_bf16 v[114:117], v[164:167], v[180:183], v[114:117]
	v_mfma_f32_16x16x32_bf16 v[106:109], v[172:175], v[180:183], v[106:109]
	v_mfma_f32_16x16x32_bf16 v[98:101], v[164:167], v[188:191], v[98:101]
	v_mfma_f32_16x16x32_bf16 v[90:93], v[172:175], v[188:191], v[90:93]
	v_mfma_f32_16x16x32_bf16 v[82:85], v[164:167], v[200:203], v[82:85]
	v_mfma_f32_16x16x32_bf16 v[74:77], v[172:175], v[200:203], v[74:77]
	v_mfma_f32_16x16x32_bf16 v[70:73], v[164:167], v[208:211], v[70:73]
	v_mfma_f32_16x16x32_bf16 v[66:69], v[172:175], v[208:211], v[66:69]
	s_setprio 0
	s_barrier
	s_add_i32 s68, s59, s51
	v_lshl_add_u64 v[192:193], s[42:43], 0, v[130:131]
	s_mov_b32 m0, s68
	ds_read_b128 v[176:179], v143 offset:16384
	ds_read_b128 v[180:183], v143 offset:17408
	ds_read_b128 v[184:187], v143 offset:18432
	ds_read_b128 v[188:191], v143 offset:19456
	ds_read_b128 v[196:199], v143 offset:20480
	ds_read_b128 v[200:203], v143 offset:21504
	ds_read_b128 v[204:207], v143 offset:22528
	ds_read_b128 v[208:211], v143 offset:23552
	global_load_lds_dwordx4 v[192:193], off
	s_add_i32 m0, s68, 0x2000
	s_add_u32 s68, s42, 0x100000
	v_lshl_add_u64 v[212:213], s[42:43], 0, v[132:133]
	s_addc_u32 s69, s43, 0
	s_add_i32 s70, s60, s51
	global_load_lds_dwordx4 v[212:213], off
	v_lshl_add_u64 v[214:215], s[68:69], 0, v[130:131]
	s_mov_b32 m0, s70
	v_lshl_add_u64 v[216:217], s[46:47], 0, v[132:133]
	global_load_lds_dwordx4 v[214:215], off
	v_lshl_add_u64 v[214:215], s[68:69], 0, v[132:133]
	s_add_i32 m0, s70, 0x2000
	s_nop 0
	global_load_lds_dwordx4 v[214:215], off
	v_lshl_add_u64 v[214:215], s[46:47], 0, v[130:131]
	s_mov_b32 m0, s29
	s_nop 0
	global_load_lds_dwordx4 v[214:215], off
	s_mov_b32 m0, s52
	s_nop 0
	global_load_lds_dwordx4 v[216:217], off
	s_branch .Lal64_9
	s_nop 0
.Lal64_9:
	s_waitcnt vmcnt(8)
	s_waitcnt lgkmcnt(0)
	s_barrier
	s_setprio 1
	v_mfma_f32_16x16x32_bf16 v[62:65], v[144:147], v[176:179], v[62:65]
	v_mfma_f32_16x16x32_bf16 v[58:61], v[152:155], v[176:179], v[58:61]
	v_mfma_f32_16x16x32_bf16 v[54:57], v[144:147], v[184:187], v[54:57]
	v_mfma_f32_16x16x32_bf16 v[46:49], v[152:155], v[184:187], v[46:49]
	v_mfma_f32_16x16x32_bf16 v[38:41], v[144:147], v[196:199], v[38:41]
	v_mfma_f32_16x16x32_bf16 v[30:33], v[152:155], v[196:199], v[30:33]
	v_mfma_f32_16x16x32_bf16 v[22:25], v[144:147], v[204:207], v[22:25]
	v_mfma_f32_16x16x32_bf16 v[14:17], v[152:155], v[204:207], v[14:17]
	v_mfma_f32_16x16x32_bf16 v[62:65], v[148:151], v[180:183], v[62:65]
	v_mfma_f32_16x16x32_bf16 v[58:61], v[156:159], v[180:183], v[58:61]
	v_mfma_f32_16x16x32_bf16 v[54:57], v[148:151], v[188:191], v[54:57]
	v_mfma_f32_16x16x32_bf16 v[46:49], v[156:159], v[188:191], v[46:49]
	v_mfma_f32_16x16x32_bf16 v[38:41], v[148:151], v[200:203], v[38:41]
	v_mfma_f32_16x16x32_bf16 v[30:33], v[156:159], v[200:203], v[30:33]
	v_mfma_f32_16x16x32_bf16 v[22:25], v[148:151], v[208:211], v[22:25]
	v_mfma_f32_16x16x32_bf16 v[14:17], v[156:159], v[208:211], v[14:17]
	v_mfma_f32_16x16x32_bf16 v[50:53], v[160:163], v[176:179], v[50:53]
	v_mfma_f32_16x16x32_bf16 v[42:45], v[168:171], v[176:179], v[42:45]
	v_mfma_f32_16x16x32_bf16 v[34:37], v[160:163], v[184:187], v[34:37]
	v_mfma_f32_16x16x32_bf16 v[26:29], v[168:171], v[184:187], v[26:29]
	v_mfma_f32_16x16x32_bf16 v[18:21], v[160:163], v[196:199], v[18:21]
	v_mfma_f32_16x16x32_bf16 v[10:13], v[168:171], v[196:199], v[10:13]
	v_mfma_f32_16x16x32_bf16 v[6:9], v[160:163], v[204:207], v[6:9]
	v_mfma_f32_16x16x32_bf16 v[2:5], v[168:171], v[204:207], v[2:5]
	v_mfma_f32_16x16x32_bf16 v[50:53], v[164:167], v[180:183], v[50:53]
	v_mfma_f32_16x16x32_bf16 v[42:45], v[172:175], v[180:183], v[42:45]
	v_mfma_f32_16x16x32_bf16 v[34:37], v[164:167], v[188:191], v[34:37]
	v_mfma_f32_16x16x32_bf16 v[26:29], v[172:175], v[188:191], v[26:29]
	v_mfma_f32_16x16x32_bf16 v[18:21], v[164:167], v[200:203], v[18:21]
	v_mfma_f32_16x16x32_bf16 v[10:13], v[172:175], v[200:203], v[10:13]
	v_mfma_f32_16x16x32_bf16 v[6:9], v[164:167], v[208:211], v[6:9]
	v_mfma_f32_16x16x32_bf16 v[2:5], v[172:175], v[208:211], v[2:5]
	s_setprio 0
	s_barrier
	s_add_i32 s68, 0, 0x18000
	s_add_i32 s69, 0, 0x1c000
	v_add_u32_e32 v156, s68, v139
	v_add_u32_e32 v172, s69, v139
	ds_read_b128 v[144:147], v156
	ds_read_b128 v[148:151], v156 offset:1024
	ds_read_b128 v[152:155], v156 offset:2048
	ds_read_b128 v[156:159], v156 offset:3072
	ds_read_b128 v[160:163], v172
	ds_read_b128 v[164:167], v172 offset:1024
	ds_read_b128 v[168:171], v172 offset:2048
	ds_read_b128 v[172:175], v172 offset:3072
	s_add_u32 s46, s46, 0x100000
	s_addc_u32 s47, s47, 0
	s_mov_b32 m0, s53
	v_lshl_add_u64 v[218:219], s[46:47], 0, v[130:131]
	ds_read_b128 v[176:179], v143 offset:32768
	ds_read_b128 v[180:183], v143 offset:33792
	ds_read_b128 v[184:187], v143 offset:34816
	ds_read_b128 v[188:191], v143 offset:35840
	ds_read_b128 v[196:199], v143 offset:36864
	ds_read_b128 v[200:203], v143 offset:37888
	ds_read_b128 v[204:207], v143 offset:38912
	ds_read_b128 v[208:211], v143 offset:39936
	global_load_lds_dwordx4 v[218:219], off
	v_lshl_add_u64 v[218:219], s[46:47], 0, v[132:133]
	s_mov_b32 m0, s54
	s_nop 0
	global_load_lds_dwordx4 v[218:219], off
	s_branch .Lal64_10
	s_nop 0
	s_nop 0
	s_nop 0
	s_nop 0
	s_nop 0
.Lal64_10:
	s_waitcnt vmcnt(8)
	s_waitcnt lgkmcnt(0)
	s_barrier
	s_setprio 1
	v_mfma_f32_16x16x32_bf16 v[126:129], v[144:147], v[176:179], v[126:129]
	v_mfma_f32_16x16x32_bf16 v[122:125], v[152:155], v[176:179], v[122:125]
	v_mfma_f32_16x16x32_bf16 v[118:121], v[144:147], v[184:187], v[118:121]
	v_mfma_f32_16x16x32_bf16 v[110:113], v[152:155], v[184:187], v[110:113]
	v_mfma_f32_16x16x32_bf16 v[102:105], v[144:147], v[196:199], v[102:105]
	v_mfma_f32_16x16x32_bf16 v[94:97], v[152:155], v[196:199], v[94:97]
	v_mfma_f32_16x16x32_bf16 v[86:89], v[144:147], v[204:207], v[86:89]
	v_mfma_f32_16x16x32_bf16 v[78:81], v[152:155], v[204:207], v[78:81]
	v_mfma_f32_16x16x32_bf16 v[126:129], v[148:151], v[180:183], v[126:129]
	v_mfma_f32_16x16x32_bf16 v[122:125], v[156:159], v[180:183], v[122:125]
	v_mfma_f32_16x16x32_bf16 v[118:121], v[148:151], v[188:191], v[118:121]
	v_mfma_f32_16x16x32_bf16 v[110:113], v[156:159], v[188:191], v[110:113]
	v_mfma_f32_16x16x32_bf16 v[102:105], v[148:151], v[200:203], v[102:105]
	v_mfma_f32_16x16x32_bf16 v[94:97], v[156:159], v[200:203], v[94:97]
	v_mfma_f32_16x16x32_bf16 v[86:89], v[148:151], v[208:211], v[86:89]
	v_mfma_f32_16x16x32_bf16 v[78:81], v[156:159], v[208:211], v[78:81]
	v_mfma_f32_16x16x32_bf16 v[114:117], v[160:163], v[176:179], v[114:117]
	v_mfma_f32_16x16x32_bf16 v[106:109], v[168:171], v[176:179], v[106:109]
	v_mfma_f32_16x16x32_bf16 v[98:101], v[160:163], v[184:187], v[98:101]
	v_mfma_f32_16x16x32_bf16 v[90:93], v[168:171], v[184:187], v[90:93]
	v_mfma_f32_16x16x32_bf16 v[82:85], v[160:163], v[196:199], v[82:85]
	v_mfma_f32_16x16x32_bf16 v[74:77], v[168:171], v[196:199], v[74:77]
	v_mfma_f32_16x16x32_bf16 v[70:73], v[160:163], v[204:207], v[70:73]
	v_mfma_f32_16x16x32_bf16 v[66:69], v[168:171], v[204:207], v[66:69]
	v_mfma_f32_16x16x32_bf16 v[114:117], v[164:167], v[180:183], v[114:117]
	v_mfma_f32_16x16x32_bf16 v[106:109], v[172:175], v[180:183], v[106:109]
	v_mfma_f32_16x16x32_bf16 v[98:101], v[164:167], v[188:191], v[98:101]
	v_mfma_f32_16x16x32_bf16 v[90:93], v[172:175], v[188:191], v[90:93]
	v_mfma_f32_16x16x32_bf16 v[82:85], v[164:167], v[200:203], v[82:85]
	v_mfma_f32_16x16x32_bf16 v[74:77], v[172:175], v[200:203], v[74:77]
	v_mfma_f32_16x16x32_bf16 v[70:73], v[164:167], v[208:211], v[70:73]
	v_mfma_f32_16x16x32_bf16 v[66:69], v[172:175], v[208:211], v[66:69]
	s_setprio 0
	s_barrier
	s_add_i32 s46, s68, s51
	v_lshl_add_u64 v[192:193], v[192:193], 0, s[10:11]
	s_mov_b32 m0, s46
	ds_read_b128 v[176:179], v143 offset:49152
	ds_read_b128 v[180:183], v143 offset:50176
	ds_read_b128 v[184:187], v143 offset:51200
	ds_read_b128 v[188:191], v143 offset:52224
	ds_read_b128 v[196:199], v143 offset:53248
	ds_read_b128 v[200:203], v143 offset:54272
	ds_read_b128 v[204:207], v143 offset:55296
	ds_read_b128 v[208:211], v143 offset:56320
	global_load_lds_dwordx4 v[192:193], off
	s_add_i32 m0, s46, 0x2000
	s_add_u32 s42, s42, 0x100080
	v_lshl_add_u64 v[192:193], v[212:213], 0, s[10:11]
	s_addc_u32 s43, s43, 0
	s_add_i32 s46, s69, s51
	global_load_lds_dwordx4 v[192:193], off
	v_lshl_add_u64 v[192:193], s[42:43], 0, v[130:131]
	s_mov_b32 m0, s46
	s_nop 0
	global_load_lds_dwordx4 v[192:193], off
	v_lshl_add_u64 v[192:193], s[42:43], 0, v[132:133]
	s_add_i32 m0, s46, 0x2000
	s_nop 0
	global_load_lds_dwordx4 v[192:193], off
	v_lshl_add_u64 v[192:193], v[214:215], 0, s[10:11]
	s_mov_b32 m0, s56
	s_nop 0
	global_load_lds_dwordx4 v[192:193], off
	v_lshl_add_u64 v[192:193], v[216:217], 0, s[10:11]
	s_mov_b32 m0, s57
	s_nop 0
	global_load_lds_dwordx4 v[192:193], off
	s_branch .Lal64_11
.Lal64_11:
	s_waitcnt vmcnt(8)
	s_waitcnt lgkmcnt(0)
	s_barrier
	s_setprio 1
	v_mfma_f32_16x16x32_bf16 v[62:65], v[144:147], v[176:179], v[62:65]
	v_mfma_f32_16x16x32_bf16 v[58:61], v[152:155], v[176:179], v[58:61]
	v_mfma_f32_16x16x32_bf16 v[54:57], v[144:147], v[184:187], v[54:57]
	v_mfma_f32_16x16x32_bf16 v[46:49], v[152:155], v[184:187], v[46:49]
	v_mfma_f32_16x16x32_bf16 v[38:41], v[144:147], v[196:199], v[38:41]
	v_mfma_f32_16x16x32_bf16 v[30:33], v[152:155], v[196:199], v[30:33]
	v_mfma_f32_16x16x32_bf16 v[22:25], v[144:147], v[204:207], v[22:25]
	v_mfma_f32_16x16x32_bf16 v[14:17], v[152:155], v[204:207], v[14:17]
	v_mfma_f32_16x16x32_bf16 v[62:65], v[148:151], v[180:183], v[62:65]
	v_mfma_f32_16x16x32_bf16 v[58:61], v[156:159], v[180:183], v[58:61]
	v_mfma_f32_16x16x32_bf16 v[54:57], v[148:151], v[188:191], v[54:57]
	v_mfma_f32_16x16x32_bf16 v[46:49], v[156:159], v[188:191], v[46:49]
	v_mfma_f32_16x16x32_bf16 v[38:41], v[148:151], v[200:203], v[38:41]
	v_mfma_f32_16x16x32_bf16 v[30:33], v[156:159], v[200:203], v[30:33]
	v_mfma_f32_16x16x32_bf16 v[22:25], v[148:151], v[208:211], v[22:25]
	v_mfma_f32_16x16x32_bf16 v[14:17], v[156:159], v[208:211], v[14:17]
	v_mfma_f32_16x16x32_bf16 v[50:53], v[160:163], v[176:179], v[50:53]
	v_mfma_f32_16x16x32_bf16 v[42:45], v[168:171], v[176:179], v[42:45]
	v_mfma_f32_16x16x32_bf16 v[34:37], v[160:163], v[184:187], v[34:37]
	v_mfma_f32_16x16x32_bf16 v[26:29], v[168:171], v[184:187], v[26:29]
	v_mfma_f32_16x16x32_bf16 v[18:21], v[160:163], v[196:199], v[18:21]
	v_mfma_f32_16x16x32_bf16 v[10:13], v[168:171], v[196:199], v[10:13]
	v_mfma_f32_16x16x32_bf16 v[6:9], v[160:163], v[204:207], v[6:9]
	v_mfma_f32_16x16x32_bf16 v[2:5], v[168:171], v[204:207], v[2:5]
	v_mfma_f32_16x16x32_bf16 v[50:53], v[164:167], v[180:183], v[50:53]
	v_mfma_f32_16x16x32_bf16 v[42:45], v[172:175], v[180:183], v[42:45]
	v_mfma_f32_16x16x32_bf16 v[34:37], v[164:167], v[188:191], v[34:37]
	v_mfma_f32_16x16x32_bf16 v[26:29], v[172:175], v[188:191], v[26:29]
	v_mfma_f32_16x16x32_bf16 v[18:21], v[164:167], v[200:203], v[18:21]
	v_mfma_f32_16x16x32_bf16 v[10:13], v[172:175], v[200:203], v[10:13]
	v_mfma_f32_16x16x32_bf16 v[6:9], v[164:167], v[208:211], v[6:9]
	v_mfma_f32_16x16x32_bf16 v[2:5], v[172:175], v[208:211], v[2:5]
	s_setprio 0
	s_barrier
	s_add_i32 s67, s67, 2
	s_add_u32 s40, s40, 0x100
	s_addc_u32 s41, s41, 0
	s_add_u32 s65, s65, 0x100
	s_addc_u32 s66, s66, 0
	s_cmp_gt_u32 s67, 61
	s_cbranch_scc0 .LBB0_335
	s_and_b64 vcc, exec, s[12:13]
	s_cbranch_vccz .LBB0_338
	s_barrier

.LBB0_657:
	ds_read_b128 v[158:161], v155
	ds_read_b128 v[162:165], v155 offset:1024
	ds_read_b128 v[166:169], v155 offset:2048
	ds_read_b128 v[170:173], v155 offset:3072
	ds_read_b128 v[174:177], v156
	ds_read_b128 v[178:181], v156 offset:1024
	ds_read_b128 v[182:185], v156 offset:2048
	ds_read_b128 v[186:189], v156 offset:3072
	s_add_u32 s28, s26, 0xfff00080
	s_addc_u32 s29, s27, -1
	s_cmp_eq_u32 s58, 60
	s_cselect_b32 s31, s21, s29
	s_cselect_b32 s30, s54, s28
	s_cselect_b32 s29, s19, s57
	s_cselect_b32 s28, s55, s56
	v_lshl_add_u64 v[224:225], s[26:27], 0, v[138:139]
	s_add_i32 m0, s17, 0xc000
	ds_read_b128 v[190:193], v157
	ds_read_b128 v[196:199], v157 offset:1024
	ds_read_b128 v[200:203], v157 offset:2048
	ds_read_b128 v[204:207], v157 offset:3072
	ds_read_b128 v[208:211], v157 offset:4096
	ds_read_b128 v[212:215], v157 offset:5120
	ds_read_b128 v[216:219], v157 offset:6144
	ds_read_b128 v[220:223], v157 offset:7168
	global_load_lds_dwordx4 v[224:225], off
	v_lshl_add_u64 v[224:225], s[26:27], 0, v[140:141]
	s_add_i32 m0, s17, 0xe000
	s_nop 0
	global_load_lds_dwordx4 v[224:225], off
	s_branch .Lal64_12
	s_nop 0
	s_nop 0
.Lal64_12:
	s_waitcnt vmcnt(8)
	s_waitcnt lgkmcnt(0)
	s_barrier
	s_setprio 1
	v_mfma_f32_16x16x32_bf16 v[126:129], v[158:161], v[190:193], v[126:129]
	v_mfma_f32_16x16x32_bf16 v[122:125], v[166:169], v[190:193], v[122:125]
	v_mfma_f32_16x16x32_bf16 v[118:121], v[158:161], v[200:203], v[118:121]
	v_mfma_f32_16x16x32_bf16 v[114:117], v[166:169], v[200:203], v[114:117]
	v_mfma_f32_16x16x32_bf16 v[102:105], v[158:161], v[208:211], v[102:105]
	v_mfma_f32_16x16x32_bf16 v[98:101], v[166:169], v[208:211], v[98:101]
	v_mfma_f32_16x16x32_bf16 v[86:89], v[158:161], v[216:219], v[86:89]
	v_mfma_f32_16x16x32_bf16 v[82:85], v[166:169], v[216:219], v[82:85]
	v_mfma_f32_16x16x32_bf16 v[126:129], v[162:165], v[196:199], v[126:129]
	v_mfma_f32_16x16x32_bf16 v[122:125], v[170:173], v[196:199], v[122:125]
	v_mfma_f32_16x16x32_bf16 v[118:121], v[162:165], v[204:207], v[118:121]
	v_mfma_f32_16x16x32_bf16 v[114:117], v[170:173], v[204:207], v[114:117]
	v_mfma_f32_16x16x32_bf16 v[102:105], v[162:165], v[212:215], v[102:105]
	v_mfma_f32_16x16x32_bf16 v[98:101], v[170:173], v[212:215], v[98:101]
	v_mfma_f32_16x16x32_bf16 v[86:89], v[162:165], v[220:223], v[86:89]
	v_mfma_f32_16x16x32_bf16 v[82:85], v[170:173], v[220:223], v[82:85]
	v_mfma_f32_16x16x32_bf16 v[110:113], v[174:177], v[190:193], v[110:113]
	v_mfma_f32_16x16x32_bf16 v[106:109], v[182:185], v[190:193], v[106:109]
	v_mfma_f32_16x16x32_bf16 v[94:97], v[174:177], v[200:203], v[94:97]
	v_mfma_f32_16x16x32_bf16 v[90:93], v[182:185], v[200:203], v[90:93]
	v_mfma_f32_16x16x32_bf16 v[78:81], v[174:177], v[208:211], v[78:81]
	v_mfma_f32_16x16x32_bf16 v[74:77], v[182:185], v[208:211], v[74:77]
	v_mfma_f32_16x16x32_bf16 v[70:73], v[174:177], v[216:219], v[70:73]
	v_mfma_f32_16x16x32_bf16 v[66:69], v[182:185], v[216:219], v[66:69]
	v_mfma_f32_16x16x32_bf16 v[110:113], v[178:181], v[196:199], v[110:113]
	v_mfma_f32_16x16x32_bf16 v[106:109], v[186:189], v[196:199], v[106:109]
	v_mfma_f32_16x16x32_bf16 v[94:97], v[178:181], v[204:207], v[94:97]
	v_mfma_f32_16x16x32_bf16 v[90:93], v[186:189], v[204:207], v[90:93]
	v_mfma_f32_16x16x32_bf16 v[78:81], v[178:181], v[212:215], v[78:81]
	v_mfma_f32_16x16x32_bf16 v[74:77], v[186:189], v[212:215], v[74:77]
	v_mfma_f32_16x16x32_bf16 v[70:73], v[178:181], v[220:223], v[70:73]
	v_mfma_f32_16x16x32_bf16 v[66:69], v[186:189], v[220:223], v[66:69]
	s_setprio 0
	s_barrier
	s_add_i32 s59, s50, s41
	v_lshl_add_u64 v[224:225], s[28:29], 0, v[134:135]
	s_mov_b32 m0, s59
	ds_read_b128 v[190:193], v157 offset:16384
	ds_read_b128 v[196:199], v157 offset:17408
	ds_read_b128 v[200:203], v157 offset:18432
	ds_read_b128 v[204:207], v157 offset:19456
	ds_read_b128 v[208:211], v157 offset:20480
	ds_read_b128 v[212:215], v157 offset:21504
	ds_read_b128 v[216:219], v157 offset:22528
	ds_read_b128 v[220:223], v157 offset:23552
	global_load_lds_dwordx4 v[224:225], off
	s_add_i32 m0, s59, 0x2000
	s_add_u32 s60, s28, 0x100000
	v_lshl_add_u64 v[226:227], s[28:29], 0, v[136:137]
	s_addc_u32 s61, s29, 0
	s_add_i32 s59, s51, s41
	global_load_lds_dwordx4 v[226:227], off
	v_lshl_add_u64 v[228:229], s[60:61], 0, v[134:135]
	s_mov_b32 m0, s59
	v_lshl_add_u64 v[230:231], s[30:31], 0, v[132:133]
	global_load_lds_dwordx4 v[228:229], off
	v_lshl_add_u64 v[228:229], s[60:61], 0, v[136:137]
	s_add_i32 m0, s59, 0x2000
	s_nop 0
	global_load_lds_dwordx4 v[228:229], off
	v_lshl_add_u64 v[228:229], s[30:31], 0, v[130:131]
	s_mov_b32 m0, s17
	s_nop 0
	global_load_lds_dwordx4 v[228:229], off
	s_mov_b32 m0, s42
	s_nop 0
	global_load_lds_dwordx4 v[230:231], off
	s_branch .Lal64_13
	s_nop 0
.Lal64_13:
	s_waitcnt vmcnt(8)
	s_waitcnt lgkmcnt(0)
	s_barrier
	s_setprio 1
	v_mfma_f32_16x16x32_bf16 v[62:65], v[158:161], v[190:193], v[62:65]
	v_mfma_f32_16x16x32_bf16 v[58:61], v[166:169], v[190:193], v[58:61]
	v_mfma_f32_16x16x32_bf16 v[54:57], v[158:161], v[200:203], v[54:57]
	v_mfma_f32_16x16x32_bf16 v[50:53], v[166:169], v[200:203], v[50:53]
	v_mfma_f32_16x16x32_bf16 v[38:41], v[158:161], v[208:211], v[38:41]
	v_mfma_f32_16x16x32_bf16 v[34:37], v[166:169], v[208:211], v[34:37]
	v_mfma_f32_16x16x32_bf16 v[22:25], v[158:161], v[216:219], v[22:25]
	v_mfma_f32_16x16x32_bf16 v[18:21], v[166:169], v[216:219], v[18:21]
	v_mfma_f32_16x16x32_bf16 v[62:65], v[162:165], v[196:199], v[62:65]
	v_mfma_f32_16x16x32_bf16 v[58:61], v[170:173], v[196:199], v[58:61]
	v_mfma_f32_16x16x32_bf16 v[54:57], v[162:165], v[204:207], v[54:57]
	v_mfma_f32_16x16x32_bf16 v[50:53], v[170:173], v[204:207], v[50:53]
	v_mfma_f32_16x16x32_bf16 v[38:41], v[162:165], v[212:215], v[38:41]
	v_mfma_f32_16x16x32_bf16 v[34:37], v[170:173], v[212:215], v[34:37]
	v_mfma_f32_16x16x32_bf16 v[22:25], v[162:165], v[220:223], v[22:25]
	v_mfma_f32_16x16x32_bf16 v[18:21], v[170:173], v[220:223], v[18:21]
	v_mfma_f32_16x16x32_bf16 v[46:49], v[174:177], v[190:193], v[46:49]
	v_mfma_f32_16x16x32_bf16 v[42:45], v[182:185], v[190:193], v[42:45]
	v_mfma_f32_16x16x32_bf16 v[30:33], v[174:177], v[200:203], v[30:33]
	v_mfma_f32_16x16x32_bf16 v[26:29], v[182:185], v[200:203], v[26:29]
	v_mfma_f32_16x16x32_bf16 v[14:17], v[174:177], v[208:211], v[14:17]
	v_mfma_f32_16x16x32_bf16 v[10:13], v[182:185], v[208:211], v[10:13]
	v_mfma_f32_16x16x32_bf16 v[6:9], v[174:177], v[216:219], v[6:9]
	v_mfma_f32_16x16x32_bf16 v[2:5], v[182:185], v[216:219], v[2:5]
	v_mfma_f32_16x16x32_bf16 v[46:49], v[178:181], v[196:199], v[46:49]
	v_mfma_f32_16x16x32_bf16 v[42:45], v[186:189], v[196:199], v[42:45]
	v_mfma_f32_16x16x32_bf16 v[30:33], v[178:181], v[204:207], v[30:33]
	v_mfma_f32_16x16x32_bf16 v[26:29], v[186:189], v[204:207], v[26:29]
	v_mfma_f32_16x16x32_bf16 v[14:17], v[178:181], v[212:215], v[14:17]
	v_mfma_f32_16x16x32_bf16 v[10:13], v[186:189], v[212:215], v[10:13]
	v_mfma_f32_16x16x32_bf16 v[6:9], v[178:181], v[220:223], v[6:9]
	v_mfma_f32_16x16x32_bf16 v[2:5], v[186:189], v[220:223], v[2:5]
	s_setprio 0
	s_barrier
	s_add_i32 s59, 0, 0x18000
	s_add_i32 s60, 0, 0x1c000
	v_add_u32_e32 v170, s59, v153
	v_add_u32_e32 v186, s60, v153
	ds_read_b128 v[158:161], v170
	ds_read_b128 v[162:165], v170 offset:1024
	ds_read_b128 v[166:169], v170 offset:2048
	ds_read_b128 v[170:173], v170 offset:3072
	ds_read_b128 v[174:177], v186
	ds_read_b128 v[178:181], v186 offset:1024
	ds_read_b128 v[182:185], v186 offset:2048
	ds_read_b128 v[186:189], v186 offset:3072
	s_add_u32 s30, s30, 0x100000
	s_addc_u32 s31, s31, 0
	s_mov_b32 m0, s43
	v_lshl_add_u64 v[232:233], s[30:31], 0, v[130:131]
	ds_read_b128 v[190:193], v157 offset:32768
	ds_read_b128 v[196:199], v157 offset:33792
	ds_read_b128 v[200:203], v157 offset:34816
	ds_read_b128 v[204:207], v157 offset:35840
	ds_read_b128 v[208:211], v157 offset:36864
	ds_read_b128 v[212:215], v157 offset:37888
	ds_read_b128 v[216:219], v157 offset:38912
	ds_read_b128 v[220:223], v157 offset:39936
	global_load_lds_dwordx4 v[232:233], off
	v_lshl_add_u64 v[232:233], s[30:31], 0, v[132:133]
	s_mov_b32 m0, s45
	s_nop 0
	global_load_lds_dwordx4 v[232:233], off
	s_branch .Lal64_14
	s_nop 0
	s_nop 0
	s_nop 0
	s_nop 0
	s_nop 0
.Lal64_14:
	s_waitcnt vmcnt(8)
	s_waitcnt lgkmcnt(0)
	s_barrier
	s_setprio 1
	v_mfma_f32_16x16x32_bf16 v[126:129], v[158:161], v[190:193], v[126:129]
	v_mfma_f32_16x16x32_bf16 v[122:125], v[166:169], v[190:193], v[122:125]
	v_mfma_f32_16x16x32_bf16 v[118:121], v[158:161], v[200:203], v[118:121]
	v_mfma_f32_16x16x32_bf16 v[114:117], v[166:169], v[200:203], v[114:117]
	v_mfma_f32_16x16x32_bf16 v[102:105], v[158:161], v[208:211], v[102:105]
	v_mfma_f32_16x16x32_bf16 v[98:101], v[166:169], v[208:211], v[98:101]
	v_mfma_f32_16x16x32_bf16 v[86:89], v[158:161], v[216:219], v[86:89]
	v_mfma_f32_16x16x32_bf16 v[82:85], v[166:169], v[216:219], v[82:85]
	v_mfma_f32_16x16x32_bf16 v[126:129], v[162:165], v[196:199], v[126:129]
	v_mfma_f32_16x16x32_bf16 v[122:125], v[170:173], v[196:199], v[122:125]
	v_mfma_f32_16x16x32_bf16 v[118:121], v[162:165], v[204:207], v[118:121]
	v_mfma_f32_16x16x32_bf16 v[114:117], v[170:173], v[204:207], v[114:117]
	v_mfma_f32_16x16x32_bf16 v[102:105], v[162:165], v[212:215], v[102:105]
	v_mfma_f32_16x16x32_bf16 v[98:101], v[170:173], v[212:215], v[98:101]
	v_mfma_f32_16x16x32_bf16 v[86:89], v[162:165], v[220:223], v[86:89]
	v_mfma_f32_16x16x32_bf16 v[82:85], v[170:173], v[220:223], v[82:85]
	v_mfma_f32_16x16x32_bf16 v[110:113], v[174:177], v[190:193], v[110:113]
	v_mfma_f32_16x16x32_bf16 v[106:109], v[182:185], v[190:193], v[106:109]
	v_mfma_f32_16x16x32_bf16 v[94:97], v[174:177], v[200:203], v[94:97]
	v_mfma_f32_16x16x32_bf16 v[90:93], v[182:185], v[200:203], v[90:93]
	v_mfma_f32_16x16x32_bf16 v[78:81], v[174:177], v[208:211], v[78:81]
	v_mfma_f32_16x16x32_bf16 v[74:77], v[182:185], v[208:211], v[74:77]
	v_mfma_f32_16x16x32_bf16 v[70:73], v[174:177], v[216:219], v[70:73]
	v_mfma_f32_16x16x32_bf16 v[66:69], v[182:185], v[216:219], v[66:69]
	v_mfma_f32_16x16x32_bf16 v[110:113], v[178:181], v[196:199], v[110:113]
	v_mfma_f32_16x16x32_bf16 v[106:109], v[186:189], v[196:199], v[106:109]
	v_mfma_f32_16x16x32_bf16 v[94:97], v[178:181], v[204:207], v[94:97]
	v_mfma_f32_16x16x32_bf16 v[90:93], v[186:189], v[204:207], v[90:93]
	v_mfma_f32_16x16x32_bf16 v[78:81], v[178:181], v[212:215], v[78:81]
	v_mfma_f32_16x16x32_bf16 v[74:77], v[186:189], v[212:215], v[74:77]
	v_mfma_f32_16x16x32_bf16 v[70:73], v[178:181], v[220:223], v[70:73]
	v_mfma_f32_16x16x32_bf16 v[66:69], v[186:189], v[220:223], v[66:69]
	s_setprio 0
	s_barrier
	s_add_i32 s30, s59, s41
	v_lshl_add_u64 v[224:225], v[224:225], 0, s[12:13]
	s_mov_b32 m0, s30
	ds_read_b128 v[190:193], v157 offset:49152
	ds_read_b128 v[196:199], v157 offset:50176
	ds_read_b128 v[200:203], v157 offset:51200
	ds_read_b128 v[204:207], v157 offset:52224
	ds_read_b128 v[208:211], v157 offset:53248
	ds_read_b128 v[212:215], v157 offset:54272
	ds_read_b128 v[216:219], v157 offset:55296
	ds_read_b128 v[220:223], v157 offset:56320
	global_load_lds_dwordx4 v[224:225], off
	s_add_i32 m0, s30, 0x2000
	s_add_u32 s28, s28, 0x100080
	v_lshl_add_u64 v[224:225], v[226:227], 0, s[12:13]
	s_addc_u32 s29, s29, 0
	s_add_i32 s30, s60, s41
	global_load_lds_dwordx4 v[224:225], off
	v_lshl_add_u64 v[224:225], s[28:29], 0, v[134:135]
	s_mov_b32 m0, s30
	s_nop 0
	global_load_lds_dwordx4 v[224:225], off
	v_lshl_add_u64 v[224:225], s[28:29], 0, v[136:137]
	s_add_i32 m0, s30, 0x2000
	s_nop 0
	global_load_lds_dwordx4 v[224:225], off
	v_lshl_add_u64 v[224:225], v[228:229], 0, s[12:13]
	s_mov_b32 m0, s47
	s_nop 0
	global_load_lds_dwordx4 v[224:225], off
	v_lshl_add_u64 v[224:225], v[230:231], 0, s[12:13]
	s_mov_b32 m0, s48
	s_nop 0
	global_load_lds_dwordx4 v[224:225], off
	s_branch .Lal64_15
.Lal64_15:
	s_waitcnt vmcnt(8)
	s_waitcnt lgkmcnt(0)
	s_barrier
	s_setprio 1
	v_mfma_f32_16x16x32_bf16 v[62:65], v[158:161], v[190:193], v[62:65]
	v_mfma_f32_16x16x32_bf16 v[58:61], v[166:169], v[190:193], v[58:61]
	v_mfma_f32_16x16x32_bf16 v[54:57], v[158:161], v[200:203], v[54:57]
	v_mfma_f32_16x16x32_bf16 v[50:53], v[166:169], v[200:203], v[50:53]
	v_mfma_f32_16x16x32_bf16 v[38:41], v[158:161], v[208:211], v[38:41]
	v_mfma_f32_16x16x32_bf16 v[34:37], v[166:169], v[208:211], v[34:37]
	v_mfma_f32_16x16x32_bf16 v[22:25], v[158:161], v[216:219], v[22:25]
	v_mfma_f32_16x16x32_bf16 v[18:21], v[166:169], v[216:219], v[18:21]
	v_mfma_f32_16x16x32_bf16 v[62:65], v[162:165], v[196:199], v[62:65]
	v_mfma_f32_16x16x32_bf16 v[58:61], v[170:173], v[196:199], v[58:61]
	v_mfma_f32_16x16x32_bf16 v[54:57], v[162:165], v[204:207], v[54:57]
	v_mfma_f32_16x16x32_bf16 v[50:53], v[170:173], v[204:207], v[50:53]
	v_mfma_f32_16x16x32_bf16 v[38:41], v[162:165], v[212:215], v[38:41]
	v_mfma_f32_16x16x32_bf16 v[34:37], v[170:173], v[212:215], v[34:37]
	v_mfma_f32_16x16x32_bf16 v[22:25], v[162:165], v[220:223], v[22:25]
	v_mfma_f32_16x16x32_bf16 v[18:21], v[170:173], v[220:223], v[18:21]
	v_mfma_f32_16x16x32_bf16 v[46:49], v[174:177], v[190:193], v[46:49]
	v_mfma_f32_16x16x32_bf16 v[42:45], v[182:185], v[190:193], v[42:45]
	v_mfma_f32_16x16x32_bf16 v[30:33], v[174:177], v[200:203], v[30:33]
	v_mfma_f32_16x16x32_bf16 v[26:29], v[182:185], v[200:203], v[26:29]
	v_mfma_f32_16x16x32_bf16 v[14:17], v[174:177], v[208:211], v[14:17]
	v_mfma_f32_16x16x32_bf16 v[10:13], v[182:185], v[208:211], v[10:13]
	v_mfma_f32_16x16x32_bf16 v[6:9], v[174:177], v[216:219], v[6:9]
	v_mfma_f32_16x16x32_bf16 v[2:5], v[182:185], v[216:219], v[2:5]
	v_mfma_f32_16x16x32_bf16 v[46:49], v[178:181], v[196:199], v[46:49]
	v_mfma_f32_16x16x32_bf16 v[42:45], v[186:189], v[196:199], v[42:45]
	v_mfma_f32_16x16x32_bf16 v[30:33], v[178:181], v[204:207], v[30:33]
	v_mfma_f32_16x16x32_bf16 v[26:29], v[186:189], v[204:207], v[26:29]
	v_mfma_f32_16x16x32_bf16 v[14:17], v[178:181], v[212:215], v[14:17]
	v_mfma_f32_16x16x32_bf16 v[10:13], v[186:189], v[212:215], v[10:13]
	v_mfma_f32_16x16x32_bf16 v[6:9], v[178:181], v[220:223], v[6:9]
	v_mfma_f32_16x16x32_bf16 v[2:5], v[186:189], v[220:223], v[2:5]
	s_setprio 0
	s_barrier
	s_add_i32 s58, s58, 2
	s_add_u32 s26, s26, 0x100
	s_addc_u32 s27, s27, 0
	s_add_u32 s56, s56, 0x100
	s_addc_u32 s57, s57, 0
	s_cmp_gt_u32 s58, 61
	s_cbranch_scc0 .LBB0_657
	s_and_b64 vcc, exec, s[14:15]
	s_cbranch_vccz .LBB0_660
	s_barrier

.LBB0_681:
	ds_read_b128 v[152:155], v144
	ds_read_b128 v[156:159], v144 offset:1024
	ds_read_b128 v[160:163], v144 offset:2048
	ds_read_b128 v[164:167], v144 offset:3072
	ds_read_b128 v[168:171], v145
	ds_read_b128 v[172:175], v145 offset:1024
	ds_read_b128 v[176:179], v145 offset:2048
	ds_read_b128 v[180:183], v145 offset:3072
	s_add_u32 s42, s40, 0xfff00080
	s_addc_u32 s43, s41, -1
	s_cmp_eq_u32 s70, 60
	s_cselect_b32 s47, s27, s43
	s_cselect_b32 s46, s66, s42
	s_cselect_b32 s43, s25, s69
	s_cselect_b32 s42, s67, s68
	v_lshl_add_u64 v[192:193], s[40:41], 0, v[134:135]
	s_add_i32 m0, s29, 0xc000
	ds_read_b128 v[184:187], v150
	ds_read_b128 v[188:191], v150 offset:1024
	ds_read_b128 v[196:199], v150 offset:2048
	ds_read_b128 v[200:203], v150 offset:3072
	ds_read_b128 v[204:207], v150 offset:4096
	ds_read_b128 v[208:211], v150 offset:5120
	ds_read_b128 v[212:215], v150 offset:6144
	ds_read_b128 v[216:219], v150 offset:7168
	global_load_lds_dwordx4 v[192:193], off
	v_lshl_add_u64 v[192:193], s[40:41], 0, v[136:137]
	s_add_i32 m0, s29, 0xe000
	s_nop 0
	global_load_lds_dwordx4 v[192:193], off
	s_branch .Lal64_16
.Lal64_16:
	s_waitcnt vmcnt(8)
	s_waitcnt lgkmcnt(0)
	s_barrier
	s_setprio 1
	v_mfma_f32_16x16x32_bf16 v[126:129], v[152:155], v[184:187], v[126:129]
	v_mfma_f32_16x16x32_bf16 v[122:125], v[160:163], v[184:187], v[122:125]
	v_mfma_f32_16x16x32_bf16 v[118:121], v[152:155], v[196:199], v[118:121]
	v_mfma_f32_16x16x32_bf16 v[110:113], v[160:163], v[196:199], v[110:113]
	v_mfma_f32_16x16x32_bf16 v[102:105], v[152:155], v[204:207], v[102:105]
	v_mfma_f32_16x16x32_bf16 v[94:97], v[160:163], v[204:207], v[94:97]
	v_mfma_f32_16x16x32_bf16 v[86:89], v[152:155], v[212:215], v[86:89]
	v_mfma_f32_16x16x32_bf16 v[78:81], v[160:163], v[212:215], v[78:81]
	v_mfma_f32_16x16x32_bf16 v[126:129], v[156:159], v[188:191], v[126:129]
	v_mfma_f32_16x16x32_bf16 v[122:125], v[164:167], v[188:191], v[122:125]
	v_mfma_f32_16x16x32_bf16 v[118:121], v[156:159], v[200:203], v[118:121]
	v_mfma_f32_16x16x32_bf16 v[110:113], v[164:167], v[200:203], v[110:113]
	v_mfma_f32_16x16x32_bf16 v[102:105], v[156:159], v[208:211], v[102:105]
	v_mfma_f32_16x16x32_bf16 v[94:97], v[164:167], v[208:211], v[94:97]
	v_mfma_f32_16x16x32_bf16 v[86:89], v[156:159], v[216:219], v[86:89]
	v_mfma_f32_16x16x32_bf16 v[78:81], v[164:167], v[216:219], v[78:81]
	v_mfma_f32_16x16x32_bf16 v[114:117], v[168:171], v[184:187], v[114:117]
	v_mfma_f32_16x16x32_bf16 v[106:109], v[176:179], v[184:187], v[106:109]
	v_mfma_f32_16x16x32_bf16 v[98:101], v[168:171], v[196:199], v[98:101]
	v_mfma_f32_16x16x32_bf16 v[90:93], v[176:179], v[196:199], v[90:93]
	v_mfma_f32_16x16x32_bf16 v[82:85], v[168:171], v[204:207], v[82:85]
	v_mfma_f32_16x16x32_bf16 v[74:77], v[176:179], v[204:207], v[74:77]
	v_mfma_f32_16x16x32_bf16 v[70:73], v[168:171], v[212:215], v[70:73]
	v_mfma_f32_16x16x32_bf16 v[66:69], v[176:179], v[212:215], v[66:69]
	v_mfma_f32_16x16x32_bf16 v[114:117], v[172:175], v[188:191], v[114:117]
	v_mfma_f32_16x16x32_bf16 v[106:109], v[180:183], v[188:191], v[106:109]
	v_mfma_f32_16x16x32_bf16 v[98:101], v[172:175], v[200:203], v[98:101]
	v_mfma_f32_16x16x32_bf16 v[90:93], v[180:183], v[200:203], v[90:93]
	v_mfma_f32_16x16x32_bf16 v[82:85], v[172:175], v[208:211], v[82:85]
	v_mfma_f32_16x16x32_bf16 v[74:77], v[180:183], v[208:211], v[74:77]
	v_mfma_f32_16x16x32_bf16 v[70:73], v[172:175], v[216:219], v[70:73]
	v_mfma_f32_16x16x32_bf16 v[66:69], v[180:183], v[216:219], v[66:69]
	s_setprio 0
	s_barrier
	s_add_i32 s71, s62, s54
	v_lshl_add_u64 v[192:193], s[42:43], 0, v[130:131]
	s_mov_b32 m0, s71
	ds_read_b128 v[184:187], v150 offset:16384
	ds_read_b128 v[188:191], v150 offset:17408
	ds_read_b128 v[196:199], v150 offset:18432
	ds_read_b128 v[200:203], v150 offset:19456
	ds_read_b128 v[204:207], v150 offset:20480
	ds_read_b128 v[208:211], v150 offset:21504
	ds_read_b128 v[212:215], v150 offset:22528
	ds_read_b128 v[216:219], v150 offset:23552
	global_load_lds_dwordx4 v[192:193], off
	s_add_i32 m0, s71, 0x2000
	s_add_u32 s72, s42, 0x100000
	v_lshl_add_u64 v[220:221], s[42:43], 0, v[132:133]
	s_addc_u32 s73, s43, 0
	s_add_i32 s71, s63, s54
	global_load_lds_dwordx4 v[220:221], off
	v_lshl_add_u64 v[222:223], s[72:73], 0, v[130:131]
	s_mov_b32 m0, s71
	v_lshl_add_u64 v[224:225], s[46:47], 0, v[132:133]
	global_load_lds_dwordx4 v[222:223], off
	v_lshl_add_u64 v[222:223], s[72:73], 0, v[132:133]
	s_add_i32 m0, s71, 0x2000
	s_nop 0
	global_load_lds_dwordx4 v[222:223], off
	v_lshl_add_u64 v[222:223], s[46:47], 0, v[130:131]
	s_mov_b32 m0, s29
	s_nop 0
	global_load_lds_dwordx4 v[222:223], off
	s_mov_b32 m0, s55
	s_nop 0
	global_load_lds_dwordx4 v[224:225], off
	s_branch .Lal64_17
	s_nop 0
.Lal64_17:
	s_waitcnt vmcnt(8)
	s_waitcnt lgkmcnt(0)
	s_barrier
	s_setprio 1
	v_mfma_f32_16x16x32_bf16 v[62:65], v[152:155], v[184:187], v[62:65]
	v_mfma_f32_16x16x32_bf16 v[58:61], v[160:163], v[184:187], v[58:61]
	v_mfma_f32_16x16x32_bf16 v[54:57], v[152:155], v[196:199], v[54:57]
	v_mfma_f32_16x16x32_bf16 v[46:49], v[160:163], v[196:199], v[46:49]
	v_mfma_f32_16x16x32_bf16 v[38:41], v[152:155], v[204:207], v[38:41]
	v_mfma_f32_16x16x32_bf16 v[30:33], v[160:163], v[204:207], v[30:33]
	v_mfma_f32_16x16x32_bf16 v[22:25], v[152:155], v[212:215], v[22:25]
	v_mfma_f32_16x16x32_bf16 v[14:17], v[160:163], v[212:215], v[14:17]
	v_mfma_f32_16x16x32_bf16 v[62:65], v[156:159], v[188:191], v[62:65]
	v_mfma_f32_16x16x32_bf16 v[58:61], v[164:167], v[188:191], v[58:61]
	v_mfma_f32_16x16x32_bf16 v[54:57], v[156:159], v[200:203], v[54:57]
	v_mfma_f32_16x16x32_bf16 v[46:49], v[164:167], v[200:203], v[46:49]
	v_mfma_f32_16x16x32_bf16 v[38:41], v[156:159], v[208:211], v[38:41]
	v_mfma_f32_16x16x32_bf16 v[30:33], v[164:167], v[208:211], v[30:33]
	v_mfma_f32_16x16x32_bf16 v[22:25], v[156:159], v[216:219], v[22:25]
	v_mfma_f32_16x16x32_bf16 v[14:17], v[164:167], v[216:219], v[14:17]
	v_mfma_f32_16x16x32_bf16 v[50:53], v[168:171], v[184:187], v[50:53]
	v_mfma_f32_16x16x32_bf16 v[42:45], v[176:179], v[184:187], v[42:45]
	v_mfma_f32_16x16x32_bf16 v[34:37], v[168:171], v[196:199], v[34:37]
	v_mfma_f32_16x16x32_bf16 v[26:29], v[176:179], v[196:199], v[26:29]
	v_mfma_f32_16x16x32_bf16 v[18:21], v[168:171], v[204:207], v[18:21]
	v_mfma_f32_16x16x32_bf16 v[10:13], v[176:179], v[204:207], v[10:13]
	v_mfma_f32_16x16x32_bf16 v[6:9], v[168:171], v[212:215], v[6:9]
	v_mfma_f32_16x16x32_bf16 v[2:5], v[176:179], v[212:215], v[2:5]
	v_mfma_f32_16x16x32_bf16 v[50:53], v[172:175], v[188:191], v[50:53]
	v_mfma_f32_16x16x32_bf16 v[42:45], v[180:183], v[188:191], v[42:45]
	v_mfma_f32_16x16x32_bf16 v[34:37], v[172:175], v[200:203], v[34:37]
	v_mfma_f32_16x16x32_bf16 v[26:29], v[180:183], v[200:203], v[26:29]
	v_mfma_f32_16x16x32_bf16 v[18:21], v[172:175], v[208:211], v[18:21]
	v_mfma_f32_16x16x32_bf16 v[10:13], v[180:183], v[208:211], v[10:13]
	v_mfma_f32_16x16x32_bf16 v[6:9], v[172:175], v[216:219], v[6:9]
	v_mfma_f32_16x16x32_bf16 v[2:5], v[180:183], v[216:219], v[2:5]
	s_setprio 0
	s_barrier
	s_add_i32 s71, 0, 0x18000
	v_add_u32_e32 v151, s71, v142
	s_add_i32 s72, 0, 0x1c000
	ds_read_b128 v[152:155], v151
	ds_read_b128 v[156:159], v151 offset:1024
	ds_read_b128 v[160:163], v151 offset:2048
	ds_read_b128 v[164:167], v151 offset:3072
	v_add_u32_e32 v151, s72, v142
	ds_read_b128 v[168:171], v151
	ds_read_b128 v[172:175], v151 offset:1024
	ds_read_b128 v[176:179], v151 offset:2048
	ds_read_b128 v[180:183], v151 offset:3072
	s_add_u32 s46, s46, 0x100000
	s_addc_u32 s47, s47, 0
	s_mov_b32 m0, s56
	v_lshl_add_u64 v[226:227], s[46:47], 0, v[130:131]
	ds_read_b128 v[184:187], v150 offset:32768
	ds_read_b128 v[188:191], v150 offset:33792
	ds_read_b128 v[196:199], v150 offset:34816
	ds_read_b128 v[200:203], v150 offset:35840
	ds_read_b128 v[204:207], v150 offset:36864
	ds_read_b128 v[208:211], v150 offset:37888
	ds_read_b128 v[212:215], v150 offset:38912
	ds_read_b128 v[216:219], v150 offset:39936
	global_load_lds_dwordx4 v[226:227], off
	v_lshl_add_u64 v[226:227], s[46:47], 0, v[132:133]
	s_mov_b32 m0, s57
	s_nop 0
	global_load_lds_dwordx4 v[226:227], off
	s_branch .Lal64_18
	s_nop 0
	s_nop 0
	s_nop 0
	s_nop 0
	s_nop 0
.Lal64_18:
	s_waitcnt vmcnt(8)
	s_waitcnt lgkmcnt(0)
	s_barrier
	s_setprio 1
	v_mfma_f32_16x16x32_bf16 v[126:129], v[152:155], v[184:187], v[126:129]
	v_mfma_f32_16x16x32_bf16 v[122:125], v[160:163], v[184:187], v[122:125]
	v_mfma_f32_16x16x32_bf16 v[118:121], v[152:155], v[196:199], v[118:121]
	v_mfma_f32_16x16x32_bf16 v[110:113], v[160:163], v[196:199], v[110:113]
	v_mfma_f32_16x16x32_bf16 v[102:105], v[152:155], v[204:207], v[102:105]
	v_mfma_f32_16x16x32_bf16 v[94:97], v[160:163], v[204:207], v[94:97]
	v_mfma_f32_16x16x32_bf16 v[86:89], v[152:155], v[212:215], v[86:89]
	v_mfma_f32_16x16x32_bf16 v[78:81], v[160:163], v[212:215], v[78:81]
	v_mfma_f32_16x16x32_bf16 v[126:129], v[156:159], v[188:191], v[126:129]
	v_mfma_f32_16x16x32_bf16 v[122:125], v[164:167], v[188:191], v[122:125]
	v_mfma_f32_16x16x32_bf16 v[118:121], v[156:159], v[200:203], v[118:121]
	v_mfma_f32_16x16x32_bf16 v[110:113], v[164:167], v[200:203], v[110:113]
	v_mfma_f32_16x16x32_bf16 v[102:105], v[156:159], v[208:211], v[102:105]
	v_mfma_f32_16x16x32_bf16 v[94:97], v[164:167], v[208:211], v[94:97]
	v_mfma_f32_16x16x32_bf16 v[86:89], v[156:159], v[216:219], v[86:89]
	v_mfma_f32_16x16x32_bf16 v[78:81], v[164:167], v[216:219], v[78:81]
	v_mfma_f32_16x16x32_bf16 v[114:117], v[168:171], v[184:187], v[114:117]
	v_mfma_f32_16x16x32_bf16 v[106:109], v[176:179], v[184:187], v[106:109]
	v_mfma_f32_16x16x32_bf16 v[98:101], v[168:171], v[196:199], v[98:101]
	v_mfma_f32_16x16x32_bf16 v[90:93], v[176:179], v[196:199], v[90:93]
	v_mfma_f32_16x16x32_bf16 v[82:85], v[168:171], v[204:207], v[82:85]
	v_mfma_f32_16x16x32_bf16 v[74:77], v[176:179], v[204:207], v[74:77]
	v_mfma_f32_16x16x32_bf16 v[70:73], v[168:171], v[212:215], v[70:73]
	v_mfma_f32_16x16x32_bf16 v[66:69], v[176:179], v[212:215], v[66:69]
	v_mfma_f32_16x16x32_bf16 v[114:117], v[172:175], v[188:191], v[114:117]
	v_mfma_f32_16x16x32_bf16 v[106:109], v[180:183], v[188:191], v[106:109]
	v_mfma_f32_16x16x32_bf16 v[98:101], v[172:175], v[200:203], v[98:101]
	v_mfma_f32_16x16x32_bf16 v[90:93], v[180:183], v[200:203], v[90:93]
	v_mfma_f32_16x16x32_bf16 v[82:85], v[172:175], v[208:211], v[82:85]
	v_mfma_f32_16x16x32_bf16 v[74:77], v[180:183], v[208:211], v[74:77]
	v_mfma_f32_16x16x32_bf16 v[70:73], v[172:175], v[216:219], v[70:73]
	v_mfma_f32_16x16x32_bf16 v[66:69], v[180:183], v[216:219], v[66:69]
	s_setprio 0
	s_barrier
	s_add_i32 s46, s71, s54
	v_lshl_add_u64 v[192:193], v[192:193], 0, s[10:11]
	s_mov_b32 m0, s46
	ds_read_b128 v[184:187], v150 offset:49152
	ds_read_b128 v[188:191], v150 offset:50176
	ds_read_b128 v[196:199], v150 offset:51200
	ds_read_b128 v[200:203], v150 offset:52224
	ds_read_b128 v[204:207], v150 offset:53248
	ds_read_b128 v[208:211], v150 offset:54272
	ds_read_b128 v[212:215], v150 offset:55296
	ds_read_b128 v[216:219], v150 offset:56320
	global_load_lds_dwordx4 v[192:193], off
	s_add_i32 m0, s46, 0x2000
	s_add_u32 s42, s42, 0x100080
	v_lshl_add_u64 v[192:193], v[220:221], 0, s[10:11]
	s_addc_u32 s43, s43, 0
	s_add_i32 s46, s72, s54
	global_load_lds_dwordx4 v[192:193], off
	v_lshl_add_u64 v[192:193], s[42:43], 0, v[130:131]
	s_mov_b32 m0, s46
	s_nop 0
	global_load_lds_dwordx4 v[192:193], off
	v_lshl_add_u64 v[192:193], s[42:43], 0, v[132:133]
	s_add_i32 m0, s46, 0x2000
	s_nop 0
	global_load_lds_dwordx4 v[192:193], off
	v_lshl_add_u64 v[192:193], v[222:223], 0, s[10:11]
	s_mov_b32 m0, s59
	s_nop 0
	global_load_lds_dwordx4 v[192:193], off
	v_lshl_add_u64 v[192:193], v[224:225], 0, s[10:11]
	s_mov_b32 m0, s60
	s_nop 0
	global_load_lds_dwordx4 v[192:193], off
	s_branch .Lal64_19

.LBB0_705:
	ds_read_b128 v[144:147], v139
	ds_read_b128 v[148:151], v139 offset:1024
	ds_read_b128 v[152:155], v139 offset:2048
	ds_read_b128 v[156:159], v139 offset:3072
	ds_read_b128 v[160:163], v140
	ds_read_b128 v[164:167], v140 offset:1024
	ds_read_b128 v[168:171], v140 offset:2048
	ds_read_b128 v[172:175], v140 offset:3072
	s_add_u32 s42, s40, 0xfff00080
	s_addc_u32 s43, s41, -1
	s_cmp_eq_u32 s67, 60
	s_cselect_b32 s47, s27, s43
	s_cselect_b32 s46, s63, s42
	s_cselect_b32 s43, s25, s66
	s_cselect_b32 s42, s64, s65
	v_lshl_add_u64 v[192:193], s[40:41], 0, v[134:135]
	s_add_i32 m0, s29, 0xc000
	ds_read_b128 v[176:179], v142
	ds_read_b128 v[180:183], v142 offset:1024
	ds_read_b128 v[184:187], v142 offset:2048
	ds_read_b128 v[188:191], v142 offset:3072
	ds_read_b128 v[196:199], v142 offset:4096
	ds_read_b128 v[200:203], v142 offset:5120
	ds_read_b128 v[204:207], v142 offset:6144
	ds_read_b128 v[208:211], v142 offset:7168
	global_load_lds_dwordx4 v[192:193], off
	v_lshl_add_u64 v[192:193], s[40:41], 0, v[136:137]
	s_add_i32 m0, s29, 0xe000
	s_nop 0
	global_load_lds_dwordx4 v[192:193], off
	s_branch .Lal64_20
	s_nop 0
	s_nop 0
	s_nop 0
	s_nop 0
	s_nop 0
	s_nop 0
	s_nop 0
	s_nop 0
	s_nop 0
	s_nop 0
	s_nop 0
	s_nop 0
.Lal64_20:
	s_waitcnt vmcnt(8)
	s_waitcnt lgkmcnt(0)
	s_barrier
	s_setprio 1
	v_mfma_f32_16x16x32_bf16 v[126:129], v[144:147], v[176:179], v[126:129]
	v_mfma_f32_16x16x32_bf16 v[122:125], v[152:155], v[176:179], v[122:125]
	v_mfma_f32_16x16x32_bf16 v[118:121], v[144:147], v[184:187], v[118:121]
	v_mfma_f32_16x16x32_bf16 v[110:113], v[152:155], v[184:187], v[110:113]
	v_mfma_f32_16x16x32_bf16 v[102:105], v[144:147], v[196:199], v[102:105]
	v_mfma_f32_16x16x32_bf16 v[94:97], v[152:155], v[196:199], v[94:97]
	v_mfma_f32_16x16x32_bf16 v[86:89], v[144:147], v[204:207], v[86:89]
	v_mfma_f32_16x16x32_bf16 v[78:81], v[152:155], v[204:207], v[78:81]
	v_mfma_f32_16x16x32_bf16 v[126:129], v[148:151], v[180:183], v[126:129]
	v_mfma_f32_16x16x32_bf16 v[122:125], v[156:159], v[180:183], v[122:125]
	v_mfma_f32_16x16x32_bf16 v[118:121], v[148:151], v[188:191], v[118:121]
	v_mfma_f32_16x16x32_bf16 v[110:113], v[156:159], v[188:191], v[110:113]
	v_mfma_f32_16x16x32_bf16 v[102:105], v[148:151], v[200:203], v[102:105]
	v_mfma_f32_16x16x32_bf16 v[94:97], v[156:159], v[200:203], v[94:97]
	v_mfma_f32_16x16x32_bf16 v[86:89], v[148:151], v[208:211], v[86:89]
	v_mfma_f32_16x16x32_bf16 v[78:81], v[156:159], v[208:211], v[78:81]
	v_mfma_f32_16x16x32_bf16 v[114:117], v[160:163], v[176:179], v[114:117]
	v_mfma_f32_16x16x32_bf16 v[106:109], v[168:171], v[176:179], v[106:109]
	v_mfma_f32_16x16x32_bf16 v[98:101], v[160:163], v[184:187], v[98:101]
	v_mfma_f32_16x16x32_bf16 v[90:93], v[168:171], v[184:187], v[90:93]
	v_mfma_f32_16x16x32_bf16 v[82:85], v[160:163], v[196:199], v[82:85]
	v_mfma_f32_16x16x32_bf16 v[74:77], v[168:171], v[196:199], v[74:77]
	v_mfma_f32_16x16x32_bf16 v[70:73], v[160:163], v[204:207], v[70:73]
	v_mfma_f32_16x16x32_bf16 v[66:69], v[168:171], v[204:207], v[66:69]
	v_mfma_f32_16x16x32_bf16 v[114:117], v[164:167], v[180:183], v[114:117]
	v_mfma_f32_16x16x32_bf16 v[106:109], v[172:175], v[180:183], v[106:109]
	v_mfma_f32_16x16x32_bf16 v[98:101], v[164:167], v[188:191], v[98:101]
	v_mfma_f32_16x16x32_bf16 v[90:93], v[172:175], v[188:191], v[90:93]
	v_mfma_f32_16x16x32_bf16 v[82:85], v[164:167], v[200:203], v[82:85]
	v_mfma_f32_16x16x32_bf16 v[74:77], v[172:175], v[200:203], v[74:77]
	v_mfma_f32_16x16x32_bf16 v[70:73], v[164:167], v[208:211], v[70:73]
	v_mfma_f32_16x16x32_bf16 v[66:69], v[172:175], v[208:211], v[66:69]
	s_setprio 0
	s_barrier
	s_add_i32 s68, s59, s51
	v_lshl_add_u64 v[192:193], s[42:43], 0, v[130:131]
	s_mov_b32 m0, s68
	ds_read_b128 v[176:179], v142 offset:16384
	ds_read_b128 v[180:183], v142 offset:17408
	ds_read_b128 v[184:187], v142 offset:18432
	ds_read_b128 v[188:191], v142 offset:19456
	ds_read_b128 v[196:199], v142 offset:20480
	ds_read_b128 v[200:203], v142 offset:21504
	ds_read_b128 v[204:207], v142 offset:22528
	ds_read_b128 v[208:211], v142 offset:23552
	global_load_lds_dwordx4 v[192:193], off
	s_add_i32 m0, s68, 0x2000
	s_add_u32 s68, s42, 0x100000
	v_lshl_add_u64 v[212:213], s[42:43], 0, v[132:133]
	s_addc_u32 s69, s43, 0
	s_add_i32 s70, s60, s51
	global_load_lds_dwordx4 v[212:213], off
	v_lshl_add_u64 v[214:215], s[68:69], 0, v[130:131]
	s_mov_b32 m0, s70
	v_lshl_add_u64 v[216:217], s[46:47], 0, v[132:133]
	global_load_lds_dwordx4 v[214:215], off
	v_lshl_add_u64 v[214:215], s[68:69], 0, v[132:133]
	s_add_i32 m0, s70, 0x2000
	s_nop 0
	global_load_lds_dwordx4 v[214:215], off
	v_lshl_add_u64 v[214:215], s[46:47], 0, v[130:131]
	s_mov_b32 m0, s29
	s_nop 0
	global_load_lds_dwordx4 v[214:215], off
	s_mov_b32 m0, s52
	s_nop 0
	global_load_lds_dwordx4 v[216:217], off
	s_branch .Lal64_21
	s_nop 0
.Lal64_21:
	s_waitcnt vmcnt(8)
	s_waitcnt lgkmcnt(0)
	s_barrier
	s_setprio 1
	v_mfma_f32_16x16x32_bf16 v[62:65], v[144:147], v[176:179], v[62:65]
	v_mfma_f32_16x16x32_bf16 v[58:61], v[152:155], v[176:179], v[58:61]
	v_mfma_f32_16x16x32_bf16 v[54:57], v[144:147], v[184:187], v[54:57]
	v_mfma_f32_16x16x32_bf16 v[46:49], v[152:155], v[184:187], v[46:49]
	v_mfma_f32_16x16x32_bf16 v[38:41], v[144:147], v[196:199], v[38:41]
	v_mfma_f32_16x16x32_bf16 v[30:33], v[152:155], v[196:199], v[30:33]
	v_mfma_f32_16x16x32_bf16 v[22:25], v[144:147], v[204:207], v[22:25]
	v_mfma_f32_16x16x32_bf16 v[14:17], v[152:155], v[204:207], v[14:17]
	v_mfma_f32_16x16x32_bf16 v[62:65], v[148:151], v[180:183], v[62:65]
	v_mfma_f32_16x16x32_bf16 v[58:61], v[156:159], v[180:183], v[58:61]
	v_mfma_f32_16x16x32_bf16 v[54:57], v[148:151], v[188:191], v[54:57]
	v_mfma_f32_16x16x32_bf16 v[46:49], v[156:159], v[188:191], v[46:49]
	v_mfma_f32_16x16x32_bf16 v[38:41], v[148:151], v[200:203], v[38:41]
	v_mfma_f32_16x16x32_bf16 v[30:33], v[156:159], v[200:203], v[30:33]
	v_mfma_f32_16x16x32_bf16 v[22:25], v[148:151], v[208:211], v[22:25]
	v_mfma_f32_16x16x32_bf16 v[14:17], v[156:159], v[208:211], v[14:17]
	v_mfma_f32_16x16x32_bf16 v[50:53], v[160:163], v[176:179], v[50:53]
	v_mfma_f32_16x16x32_bf16 v[42:45], v[168:171], v[176:179], v[42:45]
	v_mfma_f32_16x16x32_bf16 v[34:37], v[160:163], v[184:187], v[34:37]
	v_mfma_f32_16x16x32_bf16 v[26:29], v[168:171], v[184:187], v[26:29]
	v_mfma_f32_16x16x32_bf16 v[18:21], v[160:163], v[196:199], v[18:21]
	v_mfma_f32_16x16x32_bf16 v[10:13], v[168:171], v[196:199], v[10:13]
	v_mfma_f32_16x16x32_bf16 v[6:9], v[160:163], v[204:207], v[6:9]
	v_mfma_f32_16x16x32_bf16 v[2:5], v[168:171], v[204:207], v[2:5]
	v_mfma_f32_16x16x32_bf16 v[50:53], v[164:167], v[180:183], v[50:53]
	v_mfma_f32_16x16x32_bf16 v[42:45], v[172:175], v[180:183], v[42:45]
	v_mfma_f32_16x16x32_bf16 v[34:37], v[164:167], v[188:191], v[34:37]
	v_mfma_f32_16x16x32_bf16 v[26:29], v[172:175], v[188:191], v[26:29]
	v_mfma_f32_16x16x32_bf16 v[18:21], v[164:167], v[200:203], v[18:21]
	v_mfma_f32_16x16x32_bf16 v[10:13], v[172:175], v[200:203], v[10:13]
	v_mfma_f32_16x16x32_bf16 v[6:9], v[164:167], v[208:211], v[6:9]
	v_mfma_f32_16x16x32_bf16 v[2:5], v[172:175], v[208:211], v[2:5]
	s_setprio 0
	s_barrier
	s_add_i32 s68, 0, 0x18000
	v_add_u32_e32 v143, s68, v1
	s_add_i32 s69, 0, 0x1c000
	ds_read_b128 v[144:147], v143
	ds_read_b128 v[148:151], v143 offset:1024
	ds_read_b128 v[152:155], v143 offset:2048
	ds_read_b128 v[156:159], v143 offset:3072
	v_add_u32_e32 v143, s69, v1
	ds_read_b128 v[160:163], v143
	ds_read_b128 v[164:167], v143 offset:1024
	ds_read_b128 v[168:171], v143 offset:2048
	ds_read_b128 v[172:175], v143 offset:3072
	s_add_u32 s46, s46, 0x100000
	s_addc_u32 s47, s47, 0
	s_mov_b32 m0, s53
	v_lshl_add_u64 v[218:219], s[46:47], 0, v[130:131]
	ds_read_b128 v[176:179], v142 offset:32768
	ds_read_b128 v[180:183], v142 offset:33792
	ds_read_b128 v[184:187], v142 offset:34816
	ds_read_b128 v[188:191], v142 offset:35840
	ds_read_b128 v[196:199], v142 offset:36864
	ds_read_b128 v[200:203], v142 offset:37888
	ds_read_b128 v[204:207], v142 offset:38912
	ds_read_b128 v[208:211], v142 offset:39936
	global_load_lds_dwordx4 v[218:219], off
	v_lshl_add_u64 v[218:219], s[46:47], 0, v[132:133]
	s_mov_b32 m0, s54
	s_nop 0
	global_load_lds_dwordx4 v[218:219], off
	s_branch .Lal64_22
	s_nop 0
	s_nop 0
	s_nop 0
	s_nop 0
	s_nop 0
.Lal64_22:
	s_waitcnt vmcnt(8)
	s_waitcnt lgkmcnt(0)
	s_barrier
	s_setprio 1
	v_mfma_f32_16x16x32_bf16 v[126:129], v[144:147], v[176:179], v[126:129]
	v_mfma_f32_16x16x32_bf16 v[122:125], v[152:155], v[176:179], v[122:125]
	v_mfma_f32_16x16x32_bf16 v[118:121], v[144:147], v[184:187], v[118:121]
	v_mfma_f32_16x16x32_bf16 v[110:113], v[152:155], v[184:187], v[110:113]
	v_mfma_f32_16x16x32_bf16 v[102:105], v[144:147], v[196:199], v[102:105]
	v_mfma_f32_16x16x32_bf16 v[94:97], v[152:155], v[196:199], v[94:97]
	v_mfma_f32_16x16x32_bf16 v[86:89], v[144:147], v[204:207], v[86:89]
	v_mfma_f32_16x16x32_bf16 v[78:81], v[152:155], v[204:207], v[78:81]
	v_mfma_f32_16x16x32_bf16 v[126:129], v[148:151], v[180:183], v[126:129]
	v_mfma_f32_16x16x32_bf16 v[122:125], v[156:159], v[180:183], v[122:125]
	v_mfma_f32_16x16x32_bf16 v[118:121], v[148:151], v[188:191], v[118:121]
	v_mfma_f32_16x16x32_bf16 v[110:113], v[156:159], v[188:191], v[110:113]
	v_mfma_f32_16x16x32_bf16 v[102:105], v[148:151], v[200:203], v[102:105]
	v_mfma_f32_16x16x32_bf16 v[94:97], v[156:159], v[200:203], v[94:97]
	v_mfma_f32_16x16x32_bf16 v[86:89], v[148:151], v[208:211], v[86:89]
	v_mfma_f32_16x16x32_bf16 v[78:81], v[156:159], v[208:211], v[78:81]
	v_mfma_f32_16x16x32_bf16 v[114:117], v[160:163], v[176:179], v[114:117]
	v_mfma_f32_16x16x32_bf16 v[106:109], v[168:171], v[176:179], v[106:109]
	v_mfma_f32_16x16x32_bf16 v[98:101], v[160:163], v[184:187], v[98:101]
	v_mfma_f32_16x16x32_bf16 v[90:93], v[168:171], v[184:187], v[90:93]
	v_mfma_f32_16x16x32_bf16 v[82:85], v[160:163], v[196:199], v[82:85]
	v_mfma_f32_16x16x32_bf16 v[74:77], v[168:171], v[196:199], v[74:77]
	v_mfma_f32_16x16x32_bf16 v[70:73], v[160:163], v[204:207], v[70:73]
	v_mfma_f32_16x16x32_bf16 v[66:69], v[168:171], v[204:207], v[66:69]
	v_mfma_f32_16x16x32_bf16 v[114:117], v[164:167], v[180:183], v[114:117]
	v_mfma_f32_16x16x32_bf16 v[106:109], v[172:175], v[180:183], v[106:109]
	v_mfma_f32_16x16x32_bf16 v[98:101], v[164:167], v[188:191], v[98:101]
	v_mfma_f32_16x16x32_bf16 v[90:93], v[172:175], v[188:191], v[90:93]
	v_mfma_f32_16x16x32_bf16 v[82:85], v[164:167], v[200:203], v[82:85]
	v_mfma_f32_16x16x32_bf16 v[74:77], v[172:175], v[200:203], v[74:77]
	v_mfma_f32_16x16x32_bf16 v[70:73], v[164:167], v[208:211], v[70:73]
	v_mfma_f32_16x16x32_bf16 v[66:69], v[172:175], v[208:211], v[66:69]
	s_setprio 0
	s_barrier
	s_add_i32 s46, s68, s51
	v_lshl_add_u64 v[192:193], v[192:193], 0, s[10:11]
	s_mov_b32 m0, s46
	ds_read_b128 v[176:179], v142 offset:49152
	ds_read_b128 v[180:183], v142 offset:50176
	ds_read_b128 v[184:187], v142 offset:51200
	ds_read_b128 v[188:191], v142 offset:52224
	ds_read_b128 v[196:199], v142 offset:53248
	ds_read_b128 v[200:203], v142 offset:54272
	ds_read_b128 v[204:207], v142 offset:55296
	ds_read_b128 v[208:211], v142 offset:56320
	global_load_lds_dwordx4 v[192:193], off
	s_add_i32 m0, s46, 0x2000
	s_add_u32 s42, s42, 0x100080
	v_lshl_add_u64 v[192:193], v[212:213], 0, s[10:11]
	s_addc_u32 s43, s43, 0
	s_add_i32 s46, s69, s51
	global_load_lds_dwordx4 v[192:193], off
	v_lshl_add_u64 v[192:193], s[42:43], 0, v[130:131]
	s_mov_b32 m0, s46
	s_nop 0
	global_load_lds_dwordx4 v[192:193], off
	v_lshl_add_u64 v[192:193], s[42:43], 0, v[132:133]
	s_add_i32 m0, s46, 0x2000
	s_nop 0
	global_load_lds_dwordx4 v[192:193], off
	v_lshl_add_u64 v[192:193], v[214:215], 0, s[10:11]
	s_mov_b32 m0, s56
	s_nop 0
	global_load_lds_dwordx4 v[192:193], off
	v_lshl_add_u64 v[192:193], v[216:217], 0, s[10:11]
	s_mov_b32 m0, s57
	s_nop 0
	global_load_lds_dwordx4 v[192:193], off
	s_branch .Lal64_23

.LBB0_967:
	ds_read_b128 v[146:149], v152
	ds_read_b128 v[156:159], v152 offset:1024
	ds_read_b128 v[160:163], v152 offset:2048
	ds_read_b128 v[164:167], v152 offset:3072
	ds_read_b128 v[168:171], v153
	ds_read_b128 v[172:175], v153 offset:1024
	ds_read_b128 v[176:179], v153 offset:2048
	ds_read_b128 v[180:183], v153 offset:3072
	s_add_u32 s30, s28, 0xfff80080
	s_addc_u32 s31, s29, -1
	s_cmp_eq_u32 s57, 28
	s_cselect_b32 s35, s21, s31
	s_cselect_b32 s34, s53, s30
	s_cselect_b32 s31, s19, s56
	s_cselect_b32 s30, s54, s55
	v_lshl_add_u64 v[192:193], s[28:29], 0, v[138:139]
	s_add_i32 m0, s27, 0xc000
	ds_read_b128 v[184:187], v154
	ds_read_b128 v[188:191], v154 offset:1024
	ds_read_b128 v[196:199], v154 offset:2048
	ds_read_b128 v[200:203], v154 offset:3072
	ds_read_b128 v[206:209], v154 offset:4096
	ds_read_b128 v[210:213], v154 offset:5120
	ds_read_b128 v[214:217], v154 offset:6144
	ds_read_b128 v[218:221], v154 offset:7168
	global_load_lds_dwordx4 v[192:193], off
	v_lshl_add_u64 v[192:193], s[28:29], 0, v[140:141]
	s_add_i32 m0, s27, 0xe000
	s_nop 0
	global_load_lds_dwordx4 v[192:193], off
	s_branch .Lal64_24
.Lal64_24:
	s_waitcnt vmcnt(8)
	s_waitcnt lgkmcnt(0)
	s_barrier
	s_setprio 1
	v_mfma_f32_16x16x32_bf16 v[126:129], v[146:149], v[184:187], v[126:129]
	v_mfma_f32_16x16x32_bf16 v[122:125], v[160:163], v[184:187], v[122:125]
	v_mfma_f32_16x16x32_bf16 v[110:113], v[146:149], v[196:199], v[110:113]
	v_mfma_f32_16x16x32_bf16 v[106:109], v[160:163], v[196:199], v[106:109]
	v_mfma_f32_16x16x32_bf16 v[98:101], v[146:149], v[206:209], v[98:101]
	v_mfma_f32_16x16x32_bf16 v[90:93], v[160:163], v[206:209], v[90:93]
	v_mfma_f32_16x16x32_bf16 v[78:81], v[146:149], v[214:217], v[78:81]
	v_mfma_f32_16x16x32_bf16 v[74:77], v[160:163], v[214:217], v[74:77]
	v_mfma_f32_16x16x32_bf16 v[126:129], v[156:159], v[188:191], v[126:129]
	v_mfma_f32_16x16x32_bf16 v[122:125], v[164:167], v[188:191], v[122:125]
	v_mfma_f32_16x16x32_bf16 v[110:113], v[156:159], v[200:203], v[110:113]
	v_mfma_f32_16x16x32_bf16 v[106:109], v[164:167], v[200:203], v[106:109]
	v_mfma_f32_16x16x32_bf16 v[98:101], v[156:159], v[210:213], v[98:101]
	v_mfma_f32_16x16x32_bf16 v[90:93], v[164:167], v[210:213], v[90:93]
	v_mfma_f32_16x16x32_bf16 v[78:81], v[156:159], v[218:221], v[78:81]
	v_mfma_f32_16x16x32_bf16 v[74:77], v[164:167], v[218:221], v[74:77]
	v_mfma_f32_16x16x32_bf16 v[118:121], v[168:171], v[184:187], v[118:121]
	v_mfma_f32_16x16x32_bf16 v[114:117], v[176:179], v[184:187], v[114:117]
	v_mfma_f32_16x16x32_bf16 v[102:105], v[168:171], v[196:199], v[102:105]
	v_mfma_f32_16x16x32_bf16 v[94:97], v[176:179], v[196:199], v[94:97]
	v_mfma_f32_16x16x32_bf16 v[86:89], v[168:171], v[206:209], v[86:89]
	v_mfma_f32_16x16x32_bf16 v[82:85], v[176:179], v[206:209], v[82:85]
	v_mfma_f32_16x16x32_bf16 v[70:73], v[168:171], v[214:217], v[70:73]
	v_mfma_f32_16x16x32_bf16 v[66:69], v[176:179], v[214:217], v[66:69]
	v_mfma_f32_16x16x32_bf16 v[118:121], v[172:175], v[188:191], v[118:121]
	v_mfma_f32_16x16x32_bf16 v[114:117], v[180:183], v[188:191], v[114:117]
	v_mfma_f32_16x16x32_bf16 v[102:105], v[172:175], v[200:203], v[102:105]
	v_mfma_f32_16x16x32_bf16 v[94:97], v[180:183], v[200:203], v[94:97]
	v_mfma_f32_16x16x32_bf16 v[86:89], v[172:175], v[210:213], v[86:89]
	v_mfma_f32_16x16x32_bf16 v[82:85], v[180:183], v[210:213], v[82:85]
	v_mfma_f32_16x16x32_bf16 v[70:73], v[172:175], v[218:221], v[70:73]
	v_mfma_f32_16x16x32_bf16 v[66:69], v[180:183], v[218:221], v[66:69]
	s_setprio 0
	s_barrier
	s_add_i32 s58, s50, s40
	v_lshl_add_u64 v[192:193], s[30:31], 0, v[134:135]
	s_mov_b32 m0, s58
	ds_read_b128 v[184:187], v154 offset:16384
	ds_read_b128 v[188:191], v154 offset:17408
	ds_read_b128 v[196:199], v154 offset:18432
	ds_read_b128 v[200:203], v154 offset:19456
	ds_read_b128 v[206:209], v154 offset:20480
	ds_read_b128 v[210:213], v154 offset:21504
	ds_read_b128 v[214:217], v154 offset:22528
	ds_read_b128 v[218:221], v154 offset:23552
	global_load_lds_dwordx4 v[192:193], off
	s_add_i32 m0, s58, 0x2000
	s_add_u32 s58, s30, 0x80000
	v_lshl_add_u64 v[222:223], s[30:31], 0, v[130:131]
	s_addc_u32 s59, s31, 0
	s_add_i32 s60, s51, s40
	global_load_lds_dwordx4 v[222:223], off
	v_lshl_add_u64 v[224:225], s[58:59], 0, v[134:135]
	s_mov_b32 m0, s60
	v_lshl_add_u64 v[226:227], s[34:35], 0, v[132:133]
	global_load_lds_dwordx4 v[224:225], off
	v_lshl_add_u64 v[224:225], s[58:59], 0, v[130:131]
	s_add_i32 m0, s60, 0x2000
	s_nop 0
	global_load_lds_dwordx4 v[224:225], off
	v_lshl_add_u64 v[224:225], s[34:35], 0, v[136:137]
	s_mov_b32 m0, s27
	s_nop 0
	global_load_lds_dwordx4 v[224:225], off
	s_mov_b32 m0, s42
	s_nop 0
	global_load_lds_dwordx4 v[226:227], off
	s_branch .Lal64_25
	s_nop 0
.Lal64_25:
	s_waitcnt vmcnt(8)
	s_waitcnt lgkmcnt(0)
	s_barrier
	s_setprio 1
	v_mfma_f32_16x16x32_bf16 v[62:65], v[146:149], v[184:187], v[62:65]
	v_mfma_f32_16x16x32_bf16 v[58:61], v[160:163], v[184:187], v[58:61]
	v_mfma_f32_16x16x32_bf16 v[46:49], v[146:149], v[196:199], v[46:49]
	v_mfma_f32_16x16x32_bf16 v[42:45], v[160:163], v[196:199], v[42:45]
	v_mfma_f32_16x16x32_bf16 v[30:33], v[146:149], v[206:209], v[30:33]
	v_mfma_f32_16x16x32_bf16 v[26:29], v[160:163], v[206:209], v[26:29]
	v_mfma_f32_16x16x32_bf16 v[14:17], v[146:149], v[214:217], v[14:17]
	v_mfma_f32_16x16x32_bf16 v[10:13], v[160:163], v[214:217], v[10:13]
	v_mfma_f32_16x16x32_bf16 v[62:65], v[156:159], v[188:191], v[62:65]
	v_mfma_f32_16x16x32_bf16 v[58:61], v[164:167], v[188:191], v[58:61]
	v_mfma_f32_16x16x32_bf16 v[46:49], v[156:159], v[200:203], v[46:49]
	v_mfma_f32_16x16x32_bf16 v[42:45], v[164:167], v[200:203], v[42:45]
	v_mfma_f32_16x16x32_bf16 v[30:33], v[156:159], v[210:213], v[30:33]
	v_mfma_f32_16x16x32_bf16 v[26:29], v[164:167], v[210:213], v[26:29]
	v_mfma_f32_16x16x32_bf16 v[14:17], v[156:159], v[218:221], v[14:17]
	v_mfma_f32_16x16x32_bf16 v[10:13], v[164:167], v[218:221], v[10:13]
	v_mfma_f32_16x16x32_bf16 v[54:57], v[168:171], v[184:187], v[54:57]
	v_mfma_f32_16x16x32_bf16 v[50:53], v[176:179], v[184:187], v[50:53]
	v_mfma_f32_16x16x32_bf16 v[38:41], v[168:171], v[196:199], v[38:41]
	v_mfma_f32_16x16x32_bf16 v[34:37], v[176:179], v[196:199], v[34:37]
	v_mfma_f32_16x16x32_bf16 v[22:25], v[168:171], v[206:209], v[22:25]
	v_mfma_f32_16x16x32_bf16 v[18:21], v[176:179], v[206:209], v[18:21]
	v_mfma_f32_16x16x32_bf16 v[6:9], v[168:171], v[214:217], v[6:9]
	v_mfma_f32_16x16x32_bf16 v[2:5], v[176:179], v[214:217], v[2:5]
	v_mfma_f32_16x16x32_bf16 v[54:57], v[172:175], v[188:191], v[54:57]
	v_mfma_f32_16x16x32_bf16 v[50:53], v[180:183], v[188:191], v[50:53]
	v_mfma_f32_16x16x32_bf16 v[38:41], v[172:175], v[200:203], v[38:41]
	v_mfma_f32_16x16x32_bf16 v[34:37], v[180:183], v[200:203], v[34:37]
	v_mfma_f32_16x16x32_bf16 v[22:25], v[172:175], v[210:213], v[22:25]
	v_mfma_f32_16x16x32_bf16 v[18:21], v[180:183], v[210:213], v[18:21]
	v_mfma_f32_16x16x32_bf16 v[6:9], v[172:175], v[218:221], v[6:9]
	v_mfma_f32_16x16x32_bf16 v[2:5], v[180:183], v[218:221], v[2:5]
	s_setprio 0
	s_barrier
	s_add_i32 s58, 0, 0x18000
	v_add_u32_e32 v155, s58, v150
	s_add_i32 s59, 0, 0x1c000
	ds_read_b128 v[146:149], v155
	ds_read_b128 v[156:159], v155 offset:1024
	ds_read_b128 v[160:163], v155 offset:2048
	ds_read_b128 v[164:167], v155 offset:3072
	v_add_u32_e32 v155, s59, v150
	ds_read_b128 v[168:171], v155
	ds_read_b128 v[172:175], v155 offset:1024
	ds_read_b128 v[176:179], v155 offset:2048
	ds_read_b128 v[180:183], v155 offset:3072
	s_add_u32 s34, s34, 0x80000
	s_addc_u32 s35, s35, 0
	s_mov_b32 m0, s43
	v_lshl_add_u64 v[228:229], s[34:35], 0, v[136:137]
	ds_read_b128 v[184:187], v154 offset:32768
	ds_read_b128 v[188:191], v154 offset:33792
	ds_read_b128 v[196:199], v154 offset:34816
	ds_read_b128 v[200:203], v154 offset:35840
	ds_read_b128 v[206:209], v154 offset:36864
	ds_read_b128 v[210:213], v154 offset:37888
	ds_read_b128 v[214:217], v154 offset:38912
	ds_read_b128 v[218:221], v154 offset:39936
	global_load_lds_dwordx4 v[228:229], off
	v_lshl_add_u64 v[228:229], s[34:35], 0, v[132:133]
	s_mov_b32 m0, s45
	s_nop 0
	global_load_lds_dwordx4 v[228:229], off
	s_branch .Lal64_26
	s_nop 0
	s_nop 0
	s_nop 0
	s_nop 0
	s_nop 0
.Lal64_26:
	s_waitcnt vmcnt(8)
	s_waitcnt lgkmcnt(0)
	s_barrier
	s_setprio 1
	v_mfma_f32_16x16x32_bf16 v[126:129], v[146:149], v[184:187], v[126:129]
	v_mfma_f32_16x16x32_bf16 v[122:125], v[160:163], v[184:187], v[122:125]
	v_mfma_f32_16x16x32_bf16 v[110:113], v[146:149], v[196:199], v[110:113]
	v_mfma_f32_16x16x32_bf16 v[106:109], v[160:163], v[196:199], v[106:109]
	v_mfma_f32_16x16x32_bf16 v[98:101], v[146:149], v[206:209], v[98:101]
	v_mfma_f32_16x16x32_bf16 v[90:93], v[160:163], v[206:209], v[90:93]
	v_mfma_f32_16x16x32_bf16 v[78:81], v[146:149], v[214:217], v[78:81]
	v_mfma_f32_16x16x32_bf16 v[74:77], v[160:163], v[214:217], v[74:77]
	v_mfma_f32_16x16x32_bf16 v[126:129], v[156:159], v[188:191], v[126:129]
	v_mfma_f32_16x16x32_bf16 v[122:125], v[164:167], v[188:191], v[122:125]
	v_mfma_f32_16x16x32_bf16 v[110:113], v[156:159], v[200:203], v[110:113]
	v_mfma_f32_16x16x32_bf16 v[106:109], v[164:167], v[200:203], v[106:109]
	v_mfma_f32_16x16x32_bf16 v[98:101], v[156:159], v[210:213], v[98:101]
	v_mfma_f32_16x16x32_bf16 v[90:93], v[164:167], v[210:213], v[90:93]
	v_mfma_f32_16x16x32_bf16 v[78:81], v[156:159], v[218:221], v[78:81]
	v_mfma_f32_16x16x32_bf16 v[74:77], v[164:167], v[218:221], v[74:77]
	v_mfma_f32_16x16x32_bf16 v[118:121], v[168:171], v[184:187], v[118:121]
	v_mfma_f32_16x16x32_bf16 v[114:117], v[176:179], v[184:187], v[114:117]
	v_mfma_f32_16x16x32_bf16 v[102:105], v[168:171], v[196:199], v[102:105]
	v_mfma_f32_16x16x32_bf16 v[94:97], v[176:179], v[196:199], v[94:97]
	v_mfma_f32_16x16x32_bf16 v[86:89], v[168:171], v[206:209], v[86:89]
	v_mfma_f32_16x16x32_bf16 v[82:85], v[176:179], v[206:209], v[82:85]
	v_mfma_f32_16x16x32_bf16 v[70:73], v[168:171], v[214:217], v[70:73]
	v_mfma_f32_16x16x32_bf16 v[66:69], v[176:179], v[214:217], v[66:69]
	v_mfma_f32_16x16x32_bf16 v[118:121], v[172:175], v[188:191], v[118:121]
	v_mfma_f32_16x16x32_bf16 v[114:117], v[180:183], v[188:191], v[114:117]
	v_mfma_f32_16x16x32_bf16 v[102:105], v[172:175], v[200:203], v[102:105]
	v_mfma_f32_16x16x32_bf16 v[94:97], v[180:183], v[200:203], v[94:97]
	v_mfma_f32_16x16x32_bf16 v[86:89], v[172:175], v[210:213], v[86:89]
	v_mfma_f32_16x16x32_bf16 v[82:85], v[180:183], v[210:213], v[82:85]
	v_mfma_f32_16x16x32_bf16 v[70:73], v[172:175], v[218:221], v[70:73]
	v_mfma_f32_16x16x32_bf16 v[66:69], v[180:183], v[218:221], v[66:69]
	s_setprio 0
	s_barrier
	s_add_i32 s34, s58, s40
	v_lshl_add_u64 v[192:193], v[192:193], 0, s[14:15]
	s_mov_b32 m0, s34
	ds_read_b128 v[184:187], v154 offset:49152
	ds_read_b128 v[188:191], v154 offset:50176
	ds_read_b128 v[196:199], v154 offset:51200
	ds_read_b128 v[200:203], v154 offset:52224
	ds_read_b128 v[206:209], v154 offset:53248
	ds_read_b128 v[210:213], v154 offset:54272
	ds_read_b128 v[214:217], v154 offset:55296
	ds_read_b128 v[218:221], v154 offset:56320
	global_load_lds_dwordx4 v[192:193], off
	s_add_i32 m0, s34, 0x2000
	s_add_u32 s30, s30, 0x80080
	v_lshl_add_u64 v[192:193], v[222:223], 0, s[14:15]
	s_addc_u32 s31, s31, 0
	s_add_i32 s34, s59, s40
	global_load_lds_dwordx4 v[192:193], off
	v_lshl_add_u64 v[192:193], s[30:31], 0, v[134:135]
	s_mov_b32 m0, s34
	s_nop 0
	global_load_lds_dwordx4 v[192:193], off
	v_lshl_add_u64 v[192:193], s[30:31], 0, v[130:131]
	s_add_i32 m0, s34, 0x2000
	s_nop 0
	global_load_lds_dwordx4 v[192:193], off
	v_lshl_add_u64 v[192:193], v[224:225], 0, s[14:15]
	s_mov_b32 m0, s47
	s_nop 0
	global_load_lds_dwordx4 v[192:193], off
	v_lshl_add_u64 v[192:193], v[226:227], 0, s[14:15]
	s_mov_b32 m0, s48
	s_nop 0
	global_load_lds_dwordx4 v[192:193], off
	s_branch .Lal64_27
.Lal64_27:
	s_waitcnt vmcnt(8)
	s_waitcnt lgkmcnt(0)
	s_barrier
	s_setprio 1
	v_mfma_f32_16x16x32_bf16 v[62:65], v[146:149], v[184:187], v[62:65]
	v_mfma_f32_16x16x32_bf16 v[58:61], v[160:163], v[184:187], v[58:61]
	v_mfma_f32_16x16x32_bf16 v[46:49], v[146:149], v[196:199], v[46:49]
	v_mfma_f32_16x16x32_bf16 v[42:45], v[160:163], v[196:199], v[42:45]
	v_mfma_f32_16x16x32_bf16 v[30:33], v[146:149], v[206:209], v[30:33]
	v_mfma_f32_16x16x32_bf16 v[26:29], v[160:163], v[206:209], v[26:29]
	v_mfma_f32_16x16x32_bf16 v[14:17], v[146:149], v[214:217], v[14:17]
	v_mfma_f32_16x16x32_bf16 v[10:13], v[160:163], v[214:217], v[10:13]
	v_mfma_f32_16x16x32_bf16 v[62:65], v[156:159], v[188:191], v[62:65]
	v_mfma_f32_16x16x32_bf16 v[58:61], v[164:167], v[188:191], v[58:61]
	v_mfma_f32_16x16x32_bf16 v[46:49], v[156:159], v[200:203], v[46:49]
	v_mfma_f32_16x16x32_bf16 v[42:45], v[164:167], v[200:203], v[42:45]
	v_mfma_f32_16x16x32_bf16 v[30:33], v[156:159], v[210:213], v[30:33]
	v_mfma_f32_16x16x32_bf16 v[26:29], v[164:167], v[210:213], v[26:29]
	v_mfma_f32_16x16x32_bf16 v[14:17], v[156:159], v[218:221], v[14:17]
	v_mfma_f32_16x16x32_bf16 v[10:13], v[164:167], v[218:221], v[10:13]
	v_mfma_f32_16x16x32_bf16 v[54:57], v[168:171], v[184:187], v[54:57]
	v_mfma_f32_16x16x32_bf16 v[50:53], v[176:179], v[184:187], v[50:53]
	v_mfma_f32_16x16x32_bf16 v[38:41], v[168:171], v[196:199], v[38:41]
	v_mfma_f32_16x16x32_bf16 v[34:37], v[176:179], v[196:199], v[34:37]
	v_mfma_f32_16x16x32_bf16 v[22:25], v[168:171], v[206:209], v[22:25]
	v_mfma_f32_16x16x32_bf16 v[18:21], v[176:179], v[206:209], v[18:21]
	v_mfma_f32_16x16x32_bf16 v[6:9], v[168:171], v[214:217], v[6:9]
	v_mfma_f32_16x16x32_bf16 v[2:5], v[176:179], v[214:217], v[2:5]
	v_mfma_f32_16x16x32_bf16 v[54:57], v[172:175], v[188:191], v[54:57]
	v_mfma_f32_16x16x32_bf16 v[50:53], v[180:183], v[188:191], v[50:53]
	v_mfma_f32_16x16x32_bf16 v[38:41], v[172:175], v[200:203], v[38:41]
	v_mfma_f32_16x16x32_bf16 v[34:37], v[180:183], v[200:203], v[34:37]
	v_mfma_f32_16x16x32_bf16 v[22:25], v[172:175], v[210:213], v[22:25]
	v_mfma_f32_16x16x32_bf16 v[18:21], v[180:183], v[210:213], v[18:21]
	v_mfma_f32_16x16x32_bf16 v[6:9], v[172:175], v[218:221], v[6:9]
	v_mfma_f32_16x16x32_bf16 v[2:5], v[180:183], v[218:221], v[2:5]
	s_setprio 0
	s_barrier
	s_add_i32 s57, s57, 2
	s_add_u32 s28, s28, 0x100
	s_addc_u32 s29, s29, 0
	s_add_u32 s55, s55, 0x100
	s_addc_u32 s56, s56, 0
	s_cmp_gt_u32 s57, 29
	s_cbranch_scc0 .LBB0_967
	s_and_b64 vcc, exec, s[16:17]
	s_cbranch_vccz .LBB0_970
	s_barrier

.LBB0_1057:
	ds_read_b128 v[150:153], v158
	ds_read_b128 v[162:165], v158 offset:1024
	ds_read_b128 v[166:169], v158 offset:2048
	ds_read_b128 v[170:173], v158 offset:3072
	ds_read_b128 v[174:177], v159
	ds_read_b128 v[178:181], v159 offset:1024
	ds_read_b128 v[182:185], v159 offset:2048
	ds_read_b128 v[186:189], v159 offset:3072
	s_add_i32 s84, s48, 2
	s_add_u32 s49, s62, 0xfff00080
	s_addc_u32 s64, s63, -1
	s_cmp_eq_u32 s51, s48
	s_cselect_b32 s48, s56, s53
	s_cselect_b32 s65, s9, s64
	s_cselect_b32 s64, s8, s49
	s_cselect_b32 s49, s57, s55
	v_lshl_add_u64 v[154:155], s[62:63], 0, v[138:139]
	s_add_i32 m0, s59, 0xc000
	ds_read_b128 v[190:193], v160
	ds_read_b128 v[196:199], v160 offset:1024
	ds_read_b128 v[200:203], v160 offset:2048
	ds_read_b128 v[206:209], v160 offset:3072
	ds_read_b128 v[210:213], v160 offset:4096
	ds_read_b128 v[214:217], v160 offset:5120
	ds_read_b128 v[218:221], v160 offset:6144
	ds_read_b128 v[222:225], v160 offset:7168
	global_load_lds_dwordx4 v[154:155], off
	v_lshl_add_u64 v[154:155], s[62:63], 0, v[140:141]
	s_add_i32 m0, s59, 0xe000
	s_nop 0
	global_load_lds_dwordx4 v[154:155], off
	s_branch .Lal64_28
	s_nop 0
	s_nop 0
	s_nop 0
	s_nop 0
	s_nop 0
	s_nop 0
.Lal64_28:
	s_waitcnt vmcnt(8)
	s_waitcnt lgkmcnt(0)
	s_barrier
	s_setprio 1
	v_mfma_f32_16x16x32_bf16 v[126:129], v[150:153], v[190:193], v[126:129]
	v_mfma_f32_16x16x32_bf16 v[122:125], v[166:169], v[190:193], v[122:125]
	v_mfma_f32_16x16x32_bf16 v[110:113], v[150:153], v[200:203], v[110:113]
	v_mfma_f32_16x16x32_bf16 v[106:109], v[166:169], v[200:203], v[106:109]
	v_mfma_f32_16x16x32_bf16 v[94:97], v[150:153], v[210:213], v[94:97]
	v_mfma_f32_16x16x32_bf16 v[90:93], v[166:169], v[210:213], v[90:93]
	v_mfma_f32_16x16x32_bf16 v[78:81], v[150:153], v[218:221], v[78:81]
	v_mfma_f32_16x16x32_bf16 v[74:77], v[166:169], v[218:221], v[74:77]
	v_mfma_f32_16x16x32_bf16 v[126:129], v[162:165], v[196:199], v[126:129]
	v_mfma_f32_16x16x32_bf16 v[122:125], v[170:173], v[196:199], v[122:125]
	v_mfma_f32_16x16x32_bf16 v[110:113], v[162:165], v[206:209], v[110:113]
	v_mfma_f32_16x16x32_bf16 v[106:109], v[170:173], v[206:209], v[106:109]
	v_mfma_f32_16x16x32_bf16 v[94:97], v[162:165], v[214:217], v[94:97]
	v_mfma_f32_16x16x32_bf16 v[90:93], v[170:173], v[214:217], v[90:93]
	v_mfma_f32_16x16x32_bf16 v[78:81], v[162:165], v[222:225], v[78:81]
	v_mfma_f32_16x16x32_bf16 v[74:77], v[170:173], v[222:225], v[74:77]
	v_mfma_f32_16x16x32_bf16 v[118:121], v[174:177], v[190:193], v[118:121]
	v_mfma_f32_16x16x32_bf16 v[114:117], v[182:185], v[190:193], v[114:117]
	v_mfma_f32_16x16x32_bf16 v[102:105], v[174:177], v[200:203], v[102:105]
	v_mfma_f32_16x16x32_bf16 v[98:101], v[182:185], v[200:203], v[98:101]
	v_mfma_f32_16x16x32_bf16 v[86:89], v[174:177], v[210:213], v[86:89]
	v_mfma_f32_16x16x32_bf16 v[82:85], v[182:185], v[210:213], v[82:85]
	v_mfma_f32_16x16x32_bf16 v[70:73], v[174:177], v[218:221], v[70:73]
	v_mfma_f32_16x16x32_bf16 v[66:69], v[182:185], v[218:221], v[66:69]
	v_mfma_f32_16x16x32_bf16 v[118:121], v[178:181], v[196:199], v[118:121]
	v_mfma_f32_16x16x32_bf16 v[114:117], v[186:189], v[196:199], v[114:117]
	v_mfma_f32_16x16x32_bf16 v[102:105], v[178:181], v[206:209], v[102:105]
	v_mfma_f32_16x16x32_bf16 v[98:101], v[186:189], v[206:209], v[98:101]
	v_mfma_f32_16x16x32_bf16 v[86:89], v[178:181], v[214:217], v[86:89]
	v_mfma_f32_16x16x32_bf16 v[82:85], v[186:189], v[214:217], v[82:85]
	v_mfma_f32_16x16x32_bf16 v[70:73], v[178:181], v[222:225], v[70:73]
	v_mfma_f32_16x16x32_bf16 v[66:69], v[186:189], v[222:225], v[66:69]
	s_setprio 0
	s_barrier
	s_add_i32 s85, s75, s66
	v_lshl_add_u64 v[154:155], s[48:49], 0, v[132:133]
	s_mov_b32 m0, s85
	ds_read_b128 v[190:193], v160 offset:16384
	ds_read_b128 v[196:199], v160 offset:17408
	ds_read_b128 v[200:203], v160 offset:18432
	ds_read_b128 v[206:209], v160 offset:19456
	ds_read_b128 v[210:213], v160 offset:20480
	ds_read_b128 v[214:217], v160 offset:21504
	ds_read_b128 v[218:221], v160 offset:22528
	ds_read_b128 v[222:225], v160 offset:23552
	global_load_lds_dwordx4 v[154:155], off
	s_add_i32 m0, s85, 0x2000
	s_add_u32 s86, s48, 0x100000
	v_lshl_add_u64 v[226:227], s[48:49], 0, v[136:137]
	s_addc_u32 s87, s49, 0
	s_add_i32 s85, s76, s66
	global_load_lds_dwordx4 v[226:227], off
	v_lshl_add_u64 v[228:229], s[86:87], 0, v[132:133]
	s_mov_b32 m0, s85
	v_lshl_add_u64 v[230:231], s[64:65], 0, v[134:135]
	global_load_lds_dwordx4 v[228:229], off
	v_lshl_add_u64 v[228:229], s[86:87], 0, v[136:137]
	s_add_i32 m0, s85, 0x2000
	s_nop 0
	global_load_lds_dwordx4 v[228:229], off
	v_lshl_add_u64 v[228:229], s[64:65], 0, v[130:131]
	s_mov_b32 m0, s59
	s_nop 0
	global_load_lds_dwordx4 v[228:229], off
	s_mov_b32 m0, s61
	s_nop 0
	global_load_lds_dwordx4 v[230:231], off
	s_branch .Lal64_29
	s_nop 0
.Lal64_29:
	s_waitcnt vmcnt(8)
	s_waitcnt lgkmcnt(0)
	s_barrier
	s_setprio 1
	v_mfma_f32_16x16x32_bf16 v[62:65], v[150:153], v[190:193], v[62:65]
	v_mfma_f32_16x16x32_bf16 v[58:61], v[166:169], v[190:193], v[58:61]
	v_mfma_f32_16x16x32_bf16 v[46:49], v[150:153], v[200:203], v[46:49]
	v_mfma_f32_16x16x32_bf16 v[42:45], v[166:169], v[200:203], v[42:45]
	v_mfma_f32_16x16x32_bf16 v[30:33], v[150:153], v[210:213], v[30:33]
	v_mfma_f32_16x16x32_bf16 v[26:29], v[166:169], v[210:213], v[26:29]
	v_mfma_f32_16x16x32_bf16 v[14:17], v[150:153], v[218:221], v[14:17]
	v_mfma_f32_16x16x32_bf16 v[10:13], v[166:169], v[218:221], v[10:13]
	v_mfma_f32_16x16x32_bf16 v[62:65], v[162:165], v[196:199], v[62:65]
	v_mfma_f32_16x16x32_bf16 v[58:61], v[170:173], v[196:199], v[58:61]
	v_mfma_f32_16x16x32_bf16 v[46:49], v[162:165], v[206:209], v[46:49]
	v_mfma_f32_16x16x32_bf16 v[42:45], v[170:173], v[206:209], v[42:45]
	v_mfma_f32_16x16x32_bf16 v[30:33], v[162:165], v[214:217], v[30:33]
	v_mfma_f32_16x16x32_bf16 v[26:29], v[170:173], v[214:217], v[26:29]
	v_mfma_f32_16x16x32_bf16 v[14:17], v[162:165], v[222:225], v[14:17]
	v_mfma_f32_16x16x32_bf16 v[10:13], v[170:173], v[222:225], v[10:13]
	v_mfma_f32_16x16x32_bf16 v[54:57], v[174:177], v[190:193], v[54:57]
	v_mfma_f32_16x16x32_bf16 v[50:53], v[182:185], v[190:193], v[50:53]
	v_mfma_f32_16x16x32_bf16 v[38:41], v[174:177], v[200:203], v[38:41]
	v_mfma_f32_16x16x32_bf16 v[34:37], v[182:185], v[200:203], v[34:37]
	v_mfma_f32_16x16x32_bf16 v[22:25], v[174:177], v[210:213], v[22:25]
	v_mfma_f32_16x16x32_bf16 v[18:21], v[182:185], v[210:213], v[18:21]
	v_mfma_f32_16x16x32_bf16 v[6:9], v[174:177], v[218:221], v[6:9]
	v_mfma_f32_16x16x32_bf16 v[2:5], v[182:185], v[218:221], v[2:5]
	v_mfma_f32_16x16x32_bf16 v[54:57], v[178:181], v[196:199], v[54:57]
	v_mfma_f32_16x16x32_bf16 v[50:53], v[186:189], v[196:199], v[50:53]
	v_mfma_f32_16x16x32_bf16 v[38:41], v[178:181], v[206:209], v[38:41]
	v_mfma_f32_16x16x32_bf16 v[34:37], v[186:189], v[206:209], v[34:37]
	v_mfma_f32_16x16x32_bf16 v[22:25], v[178:181], v[214:217], v[22:25]
	v_mfma_f32_16x16x32_bf16 v[18:21], v[186:189], v[214:217], v[18:21]
	v_mfma_f32_16x16x32_bf16 v[6:9], v[178:181], v[222:225], v[6:9]
	v_mfma_f32_16x16x32_bf16 v[2:5], v[186:189], v[222:225], v[2:5]
	s_setprio 0
	s_barrier
	s_add_i32 s85, 0, 0x18000
	v_add_u32_e32 v161, s85, v156
	s_add_i32 s86, 0, 0x1c000
	ds_read_b128 v[150:153], v161
	ds_read_b128 v[162:165], v161 offset:1024
	ds_read_b128 v[166:169], v161 offset:2048
	ds_read_b128 v[170:173], v161 offset:3072
	v_add_u32_e32 v161, s86, v156
	ds_read_b128 v[174:177], v161
	ds_read_b128 v[178:181], v161 offset:1024
	ds_read_b128 v[182:185], v161 offset:2048
	ds_read_b128 v[186:189], v161 offset:3072
	s_add_u32 s64, s64, 0x100000
	s_addc_u32 s65, s65, 0
	s_mov_b32 m0, s67
	v_lshl_add_u64 v[232:233], s[64:65], 0, v[130:131]
	ds_read_b128 v[190:193], v160 offset:32768
	ds_read_b128 v[196:199], v160 offset:33792
	ds_read_b128 v[200:203], v160 offset:34816
	ds_read_b128 v[206:209], v160 offset:35840
	ds_read_b128 v[210:213], v160 offset:36864
	ds_read_b128 v[214:217], v160 offset:37888
	ds_read_b128 v[218:221], v160 offset:38912
	ds_read_b128 v[222:225], v160 offset:39936
	global_load_lds_dwordx4 v[232:233], off
	v_lshl_add_u64 v[232:233], s[64:65], 0, v[134:135]
	s_mov_b32 m0, s68
	s_nop 0
	global_load_lds_dwordx4 v[232:233], off
	s_branch .Lal64_30
	s_nop 0
	s_nop 0
	s_nop 0
	s_nop 0
	s_nop 0
.Lal64_30:
	s_waitcnt vmcnt(8)
	s_waitcnt lgkmcnt(0)
	s_barrier
	s_setprio 1
	v_mfma_f32_16x16x32_bf16 v[126:129], v[150:153], v[190:193], v[126:129]
	v_mfma_f32_16x16x32_bf16 v[122:125], v[166:169], v[190:193], v[122:125]
	v_mfma_f32_16x16x32_bf16 v[110:113], v[150:153], v[200:203], v[110:113]
	v_mfma_f32_16x16x32_bf16 v[106:109], v[166:169], v[200:203], v[106:109]
	v_mfma_f32_16x16x32_bf16 v[94:97], v[150:153], v[210:213], v[94:97]
	v_mfma_f32_16x16x32_bf16 v[90:93], v[166:169], v[210:213], v[90:93]
	v_mfma_f32_16x16x32_bf16 v[78:81], v[150:153], v[218:221], v[78:81]
	v_mfma_f32_16x16x32_bf16 v[74:77], v[166:169], v[218:221], v[74:77]
	v_mfma_f32_16x16x32_bf16 v[126:129], v[162:165], v[196:199], v[126:129]
	v_mfma_f32_16x16x32_bf16 v[122:125], v[170:173], v[196:199], v[122:125]
	v_mfma_f32_16x16x32_bf16 v[110:113], v[162:165], v[206:209], v[110:113]
	v_mfma_f32_16x16x32_bf16 v[106:109], v[170:173], v[206:209], v[106:109]
	v_mfma_f32_16x16x32_bf16 v[94:97], v[162:165], v[214:217], v[94:97]
	v_mfma_f32_16x16x32_bf16 v[90:93], v[170:173], v[214:217], v[90:93]
	v_mfma_f32_16x16x32_bf16 v[78:81], v[162:165], v[222:225], v[78:81]
	v_mfma_f32_16x16x32_bf16 v[74:77], v[170:173], v[222:225], v[74:77]
	v_mfma_f32_16x16x32_bf16 v[118:121], v[174:177], v[190:193], v[118:121]
	v_mfma_f32_16x16x32_bf16 v[114:117], v[182:185], v[190:193], v[114:117]
	v_mfma_f32_16x16x32_bf16 v[102:105], v[174:177], v[200:203], v[102:105]
	v_mfma_f32_16x16x32_bf16 v[98:101], v[182:185], v[200:203], v[98:101]
	v_mfma_f32_16x16x32_bf16 v[86:89], v[174:177], v[210:213], v[86:89]
	v_mfma_f32_16x16x32_bf16 v[82:85], v[182:185], v[210:213], v[82:85]
	v_mfma_f32_16x16x32_bf16 v[70:73], v[174:177], v[218:221], v[70:73]
	v_mfma_f32_16x16x32_bf16 v[66:69], v[182:185], v[218:221], v[66:69]
	v_mfma_f32_16x16x32_bf16 v[118:121], v[178:181], v[196:199], v[118:121]
	v_mfma_f32_16x16x32_bf16 v[114:117], v[186:189], v[196:199], v[114:117]
	v_mfma_f32_16x16x32_bf16 v[102:105], v[178:181], v[206:209], v[102:105]
	v_mfma_f32_16x16x32_bf16 v[98:101], v[186:189], v[206:209], v[98:101]
	v_mfma_f32_16x16x32_bf16 v[86:89], v[178:181], v[214:217], v[86:89]
	v_mfma_f32_16x16x32_bf16 v[82:85], v[186:189], v[214:217], v[82:85]
	v_mfma_f32_16x16x32_bf16 v[70:73], v[178:181], v[222:225], v[70:73]
	v_mfma_f32_16x16x32_bf16 v[66:69], v[186:189], v[222:225], v[66:69]
	s_setprio 0
	s_barrier
	s_add_i32 s64, s85, s66
	v_lshl_add_u64 v[154:155], v[154:155], 0, s[20:21]
	s_mov_b32 m0, s64
	ds_read_b128 v[190:193], v160 offset:49152
	ds_read_b128 v[196:199], v160 offset:50176
	ds_read_b128 v[200:203], v160 offset:51200
	ds_read_b128 v[206:209], v160 offset:52224
	ds_read_b128 v[210:213], v160 offset:53248
	ds_read_b128 v[214:217], v160 offset:54272
	ds_read_b128 v[218:221], v160 offset:55296
	ds_read_b128 v[222:225], v160 offset:56320
	global_load_lds_dwordx4 v[154:155], off
	s_add_i32 m0, s64, 0x2000
	s_add_u32 s48, s48, 0x100080
	v_lshl_add_u64 v[154:155], v[226:227], 0, s[20:21]
	s_addc_u32 s49, s49, 0
	s_add_i32 s64, s86, s66
	global_load_lds_dwordx4 v[154:155], off
	v_lshl_add_u64 v[154:155], s[48:49], 0, v[132:133]
	s_mov_b32 m0, s64
	s_nop 0
	global_load_lds_dwordx4 v[154:155], off
	v_lshl_add_u64 v[154:155], s[48:49], 0, v[136:137]
	s_add_i32 m0, s64, 0x2000
	s_nop 0
	global_load_lds_dwordx4 v[154:155], off
	v_lshl_add_u64 v[154:155], v[228:229], 0, s[20:21]
	s_mov_b32 m0, s72
	s_nop 0
	global_load_lds_dwordx4 v[154:155], off
	v_lshl_add_u64 v[154:155], v[230:231], 0, s[20:21]
	s_mov_b32 m0, s73
	s_nop 0
	global_load_lds_dwordx4 v[154:155], off
	s_branch .Lal64_31
.Lal64_31:
	s_waitcnt vmcnt(8)
	s_waitcnt lgkmcnt(0)
	s_barrier
	s_setprio 1
	v_mfma_f32_16x16x32_bf16 v[62:65], v[150:153], v[190:193], v[62:65]
	v_mfma_f32_16x16x32_bf16 v[58:61], v[166:169], v[190:193], v[58:61]
	v_mfma_f32_16x16x32_bf16 v[46:49], v[150:153], v[200:203], v[46:49]
	v_mfma_f32_16x16x32_bf16 v[42:45], v[166:169], v[200:203], v[42:45]
	v_mfma_f32_16x16x32_bf16 v[30:33], v[150:153], v[210:213], v[30:33]
	v_mfma_f32_16x16x32_bf16 v[26:29], v[166:169], v[210:213], v[26:29]
	v_mfma_f32_16x16x32_bf16 v[14:17], v[150:153], v[218:221], v[14:17]
	v_mfma_f32_16x16x32_bf16 v[10:13], v[166:169], v[218:221], v[10:13]
	v_mfma_f32_16x16x32_bf16 v[62:65], v[162:165], v[196:199], v[62:65]
	v_mfma_f32_16x16x32_bf16 v[58:61], v[170:173], v[196:199], v[58:61]
	v_mfma_f32_16x16x32_bf16 v[46:49], v[162:165], v[206:209], v[46:49]
	v_mfma_f32_16x16x32_bf16 v[42:45], v[170:173], v[206:209], v[42:45]
	v_mfma_f32_16x16x32_bf16 v[30:33], v[162:165], v[214:217], v[30:33]
	v_mfma_f32_16x16x32_bf16 v[26:29], v[170:173], v[214:217], v[26:29]
	v_mfma_f32_16x16x32_bf16 v[14:17], v[162:165], v[222:225], v[14:17]
	v_mfma_f32_16x16x32_bf16 v[10:13], v[170:173], v[222:225], v[10:13]
	v_mfma_f32_16x16x32_bf16 v[54:57], v[174:177], v[190:193], v[54:57]
	v_mfma_f32_16x16x32_bf16 v[50:53], v[182:185], v[190:193], v[50:53]
	v_mfma_f32_16x16x32_bf16 v[38:41], v[174:177], v[200:203], v[38:41]
	v_mfma_f32_16x16x32_bf16 v[34:37], v[182:185], v[200:203], v[34:37]
	v_mfma_f32_16x16x32_bf16 v[22:25], v[174:177], v[210:213], v[22:25]
	v_mfma_f32_16x16x32_bf16 v[18:21], v[182:185], v[210:213], v[18:21]
	v_mfma_f32_16x16x32_bf16 v[6:9], v[174:177], v[218:221], v[6:9]
	v_mfma_f32_16x16x32_bf16 v[2:5], v[182:185], v[218:221], v[2:5]
	v_mfma_f32_16x16x32_bf16 v[54:57], v[178:181], v[196:199], v[54:57]
	v_mfma_f32_16x16x32_bf16 v[50:53], v[186:189], v[196:199], v[50:53]
	v_mfma_f32_16x16x32_bf16 v[38:41], v[178:181], v[206:209], v[38:41]
	v_mfma_f32_16x16x32_bf16 v[34:37], v[186:189], v[206:209], v[34:37]
	v_mfma_f32_16x16x32_bf16 v[22:25], v[178:181], v[214:217], v[22:25]
	v_mfma_f32_16x16x32_bf16 v[18:21], v[186:189], v[214:217], v[18:21]
	v_mfma_f32_16x16x32_bf16 v[6:9], v[178:181], v[222:225], v[6:9]
	v_mfma_f32_16x16x32_bf16 v[2:5], v[186:189], v[222:225], v[2:5]
	s_setprio 0
	s_barrier
	s_add_u32 s62, s62, 0x100
	s_addc_u32 s63, s63, 0
	s_add_u32 s53, s53, 0x100
	s_addc_u32 s55, s55, 0
	s_cmp_ge_i32 s84, s83
	s_mov_b32 s48, s84
	s_cbranch_scc0 .LBB0_1057
	s_and_b64 vcc, exec, s[22:23]
	s_cbranch_vccz .LBB0_1060
	s_barrier

.LBB0_1197:
	ds_read_b128 v[162:165], v141
	ds_read_b128 v[166:169], v141 offset:1024
	ds_read_b128 v[170:173], v141 offset:2048
	ds_read_b128 v[174:177], v141 offset:3072
	ds_read_b128 v[178:181], v145
	ds_read_b128 v[182:185], v145 offset:1024
	ds_read_b128 v[186:189], v145 offset:2048
	ds_read_b128 v[190:193], v145 offset:3072
	s_add_i32 s65, s34, 2
	s_add_u32 s35, s30, 0xfff00080
	s_addc_u32 s40, s31, -1
	s_cmp_eq_u32 s62, s34
	s_cselect_b32 s34, s61, s63
	s_cselect_b32 s41, s21, s40
	s_cselect_b32 s40, s25, s35
	s_cselect_b32 s35, s23, s64
	v_lshl_add_u64 v[158:159], s[30:31], 0, v[148:149]
	s_add_i32 m0, s8, 0xc000
	ds_read_b128 v[196:199], v160
	ds_read_b128 v[200:203], v160 offset:1024
	ds_read_b128 v[206:209], v160 offset:2048
	ds_read_b128 v[210:213], v160 offset:3072
	ds_read_b128 v[214:217], v160 offset:4096
	ds_read_b128 v[218:221], v160 offset:5120
	ds_read_b128 v[222:225], v160 offset:6144
	ds_read_b128 v[226:229], v160 offset:7168
	global_load_lds_dwordx4 v[158:159], off
	v_lshl_add_u64 v[158:159], s[30:31], 0, v[150:151]
	s_add_i32 m0, s8, 0xe000
	s_nop 0
	global_load_lds_dwordx4 v[158:159], off
	s_branch .Lal64_32
	s_nop 0
	s_nop 0
	s_nop 0
	s_nop 0
	s_nop 0
	s_nop 0
	s_nop 0
	s_nop 0
	s_nop 0
	s_nop 0
	s_nop 0
	s_nop 0
.Lal64_32:
	s_waitcnt vmcnt(8)
	s_waitcnt lgkmcnt(0)
	s_barrier
	s_setprio 1
	v_mfma_f32_16x16x32_bf16 v[126:129], v[162:165], v[196:199], v[126:129]
	v_mfma_f32_16x16x32_bf16 v[122:125], v[170:173], v[196:199], v[122:125]
	v_mfma_f32_16x16x32_bf16 v[118:121], v[162:165], v[206:209], v[118:121]
	v_mfma_f32_16x16x32_bf16 v[114:117], v[170:173], v[206:209], v[114:117]
	v_mfma_f32_16x16x32_bf16 v[102:105], v[162:165], v[214:217], v[102:105]
	v_mfma_f32_16x16x32_bf16 v[98:101], v[170:173], v[214:217], v[98:101]
	v_mfma_f32_16x16x32_bf16 v[42:45], v[162:165], v[222:225], v[42:45]
	v_mfma_f32_16x16x32_bf16 v[34:37], v[170:173], v[222:225], v[34:37]
	v_mfma_f32_16x16x32_bf16 v[126:129], v[166:169], v[200:203], v[126:129]
	v_mfma_f32_16x16x32_bf16 v[122:125], v[174:177], v[200:203], v[122:125]
	v_mfma_f32_16x16x32_bf16 v[118:121], v[166:169], v[210:213], v[118:121]
	v_mfma_f32_16x16x32_bf16 v[114:117], v[174:177], v[210:213], v[114:117]
	v_mfma_f32_16x16x32_bf16 v[102:105], v[166:169], v[218:221], v[102:105]
	v_mfma_f32_16x16x32_bf16 v[98:101], v[174:177], v[218:221], v[98:101]
	v_mfma_f32_16x16x32_bf16 v[42:45], v[166:169], v[226:229], v[42:45]
	v_mfma_f32_16x16x32_bf16 v[34:37], v[174:177], v[226:229], v[34:37]
	v_mfma_f32_16x16x32_bf16 v[110:113], v[178:181], v[196:199], v[110:113]
	v_mfma_f32_16x16x32_bf16 v[106:109], v[186:189], v[196:199], v[106:109]
	v_mfma_f32_16x16x32_bf16 v[94:97], v[178:181], v[206:209], v[94:97]
	v_mfma_f32_16x16x32_bf16 v[90:93], v[186:189], v[206:209], v[90:93]
	v_mfma_f32_16x16x32_bf16 v[86:89], v[178:181], v[214:217], v[86:89]
	v_mfma_f32_16x16x32_bf16 v[82:85], v[186:189], v[214:217], v[82:85]
	v_mfma_f32_16x16x32_bf16 v[30:33], v[178:181], v[222:225], v[30:33]
	v_mfma_f32_16x16x32_bf16 v[26:29], v[186:189], v[222:225], v[26:29]
	v_mfma_f32_16x16x32_bf16 v[110:113], v[182:185], v[200:203], v[110:113]
	v_mfma_f32_16x16x32_bf16 v[106:109], v[190:193], v[200:203], v[106:109]
	v_mfma_f32_16x16x32_bf16 v[94:97], v[182:185], v[210:213], v[94:97]
	v_mfma_f32_16x16x32_bf16 v[90:93], v[190:193], v[210:213], v[90:93]
	v_mfma_f32_16x16x32_bf16 v[86:89], v[182:185], v[218:221], v[86:89]
	v_mfma_f32_16x16x32_bf16 v[82:85], v[190:193], v[218:221], v[82:85]
	v_mfma_f32_16x16x32_bf16 v[30:33], v[182:185], v[226:229], v[30:33]
	v_mfma_f32_16x16x32_bf16 v[26:29], v[190:193], v[226:229], v[26:29]
	s_setprio 0
	s_barrier
	s_add_i32 s66, s56, s42
	v_lshl_add_u64 v[158:159], s[34:35], 0, v[134:135]
	s_mov_b32 m0, s66
	ds_read_b128 v[196:199], v160 offset:16384
	ds_read_b128 v[200:203], v160 offset:17408
	ds_read_b128 v[206:209], v160 offset:18432
	ds_read_b128 v[210:213], v160 offset:19456
	ds_read_b128 v[214:217], v160 offset:20480
	ds_read_b128 v[218:221], v160 offset:21504
	ds_read_b128 v[222:225], v160 offset:22528
	ds_read_b128 v[226:229], v160 offset:23552
	global_load_lds_dwordx4 v[158:159], off
	s_add_i32 m0, s66, 0x2000
	s_add_u32 s66, s34, 0x100000
	v_lshl_add_u64 v[230:231], s[34:35], 0, v[132:133]
	s_addc_u32 s67, s35, 0
	s_add_i32 s68, s57, s42
	global_load_lds_dwordx4 v[230:231], off
	v_lshl_add_u64 v[232:233], s[66:67], 0, v[134:135]
	s_mov_b32 m0, s68
	v_lshl_add_u64 v[234:235], s[40:41], 0, v[132:133]
	global_load_lds_dwordx4 v[232:233], off
	v_lshl_add_u64 v[232:233], s[66:67], 0, v[132:133]
	s_add_i32 m0, s68, 0x2000
	s_nop 0
	global_load_lds_dwordx4 v[232:233], off
	v_lshl_add_u64 v[232:233], s[40:41], 0, v[134:135]
	s_mov_b32 m0, s8
	s_nop 0
	global_load_lds_dwordx4 v[232:233], off
	s_mov_b32 m0, s15
	s_nop 0
	global_load_lds_dwordx4 v[234:235], off
	s_branch .Lal64_33
	s_nop 0
.Lal64_33:
	s_waitcnt vmcnt(8)
	s_waitcnt lgkmcnt(0)
	s_barrier
	s_setprio 1
	v_mfma_f32_16x16x32_bf16 v[78:81], v[162:165], v[196:199], v[78:81]
	v_mfma_f32_16x16x32_bf16 v[74:77], v[170:173], v[196:199], v[74:77]
	v_mfma_f32_16x16x32_bf16 v[70:73], v[162:165], v[206:209], v[70:73]
	v_mfma_f32_16x16x32_bf16 v[66:69], v[170:173], v[206:209], v[66:69]
	v_mfma_f32_16x16x32_bf16 v[54:57], v[162:165], v[214:217], v[54:57]
	v_mfma_f32_16x16x32_bf16 v[50:53], v[170:173], v[214:217], v[50:53]
	v_mfma_f32_16x16x32_bf16 v[14:17], v[162:165], v[222:225], v[14:17]
	v_mfma_f32_16x16x32_bf16 v[10:13], v[170:173], v[222:225], v[10:13]
	v_mfma_f32_16x16x32_bf16 v[78:81], v[166:169], v[200:203], v[78:81]
	v_mfma_f32_16x16x32_bf16 v[74:77], v[174:177], v[200:203], v[74:77]
	v_mfma_f32_16x16x32_bf16 v[70:73], v[166:169], v[210:213], v[70:73]
	v_mfma_f32_16x16x32_bf16 v[66:69], v[174:177], v[210:213], v[66:69]
	v_mfma_f32_16x16x32_bf16 v[54:57], v[166:169], v[218:221], v[54:57]
	v_mfma_f32_16x16x32_bf16 v[50:53], v[174:177], v[218:221], v[50:53]
	v_mfma_f32_16x16x32_bf16 v[14:17], v[166:169], v[226:229], v[14:17]
	v_mfma_f32_16x16x32_bf16 v[10:13], v[174:177], v[226:229], v[10:13]
	v_mfma_f32_16x16x32_bf16 v[62:65], v[178:181], v[196:199], v[62:65]
	v_mfma_f32_16x16x32_bf16 v[58:61], v[186:189], v[196:199], v[58:61]
	v_mfma_f32_16x16x32_bf16 v[46:49], v[178:181], v[206:209], v[46:49]
	v_mfma_f32_16x16x32_bf16 v[38:41], v[186:189], v[206:209], v[38:41]
	v_mfma_f32_16x16x32_bf16 v[22:25], v[178:181], v[214:217], v[22:25]
	v_mfma_f32_16x16x32_bf16 v[18:21], v[186:189], v[214:217], v[18:21]
	v_mfma_f32_16x16x32_bf16 v[6:9], v[178:181], v[222:225], v[6:9]
	v_mfma_f32_16x16x32_bf16 v[2:5], v[186:189], v[222:225], v[2:5]
	v_mfma_f32_16x16x32_bf16 v[62:65], v[182:185], v[200:203], v[62:65]
	v_mfma_f32_16x16x32_bf16 v[58:61], v[190:193], v[200:203], v[58:61]
	v_mfma_f32_16x16x32_bf16 v[46:49], v[182:185], v[210:213], v[46:49]
	v_mfma_f32_16x16x32_bf16 v[38:41], v[190:193], v[210:213], v[38:41]
	v_mfma_f32_16x16x32_bf16 v[22:25], v[182:185], v[218:221], v[22:25]
	v_mfma_f32_16x16x32_bf16 v[18:21], v[190:193], v[218:221], v[18:21]
	v_mfma_f32_16x16x32_bf16 v[6:9], v[182:185], v[226:229], v[6:9]
	v_mfma_f32_16x16x32_bf16 v[2:5], v[190:193], v[226:229], v[2:5]
	s_setprio 0
	s_barrier
	s_add_i32 s66, 0, 0x18000
	v_add_u32_e32 v161, s66, v1
	s_add_i32 s67, 0, 0x1c000
	ds_read_b128 v[162:165], v161
	ds_read_b128 v[166:169], v161 offset:1024
	ds_read_b128 v[170:173], v161 offset:2048
	ds_read_b128 v[174:177], v161 offset:3072
	v_add_u32_e32 v161, s67, v1
	ds_read_b128 v[178:181], v161
	ds_read_b128 v[182:185], v161 offset:1024
	ds_read_b128 v[186:189], v161 offset:2048
	ds_read_b128 v[190:193], v161 offset:3072
	s_add_u32 s40, s40, 0x100000
	s_addc_u32 s41, s41, 0
	s_mov_b32 m0, s46
	v_lshl_add_u64 v[236:237], s[40:41], 0, v[134:135]
	ds_read_b128 v[196:199], v160 offset:32768
	ds_read_b128 v[200:203], v160 offset:33792
	ds_read_b128 v[206:209], v160 offset:34816
	ds_read_b128 v[210:213], v160 offset:35840
	ds_read_b128 v[214:217], v160 offset:36864
	ds_read_b128 v[218:221], v160 offset:37888
	ds_read_b128 v[222:225], v160 offset:38912
	ds_read_b128 v[226:229], v160 offset:39936
	global_load_lds_dwordx4 v[236:237], off
	v_lshl_add_u64 v[236:237], s[40:41], 0, v[132:133]
	s_mov_b32 m0, s47
	s_nop 0
	global_load_lds_dwordx4 v[236:237], off
	s_branch .Lal64_34
	s_nop 0
	s_nop 0
	s_nop 0
	s_nop 0
	s_nop 0
.Lal64_34:
	s_waitcnt vmcnt(8)
	s_waitcnt lgkmcnt(0)
	s_barrier
	s_setprio 1
	v_mfma_f32_16x16x32_bf16 v[126:129], v[162:165], v[196:199], v[126:129]
	v_mfma_f32_16x16x32_bf16 v[122:125], v[170:173], v[196:199], v[122:125]
	v_mfma_f32_16x16x32_bf16 v[118:121], v[162:165], v[206:209], v[118:121]
	v_mfma_f32_16x16x32_bf16 v[114:117], v[170:173], v[206:209], v[114:117]
	v_mfma_f32_16x16x32_bf16 v[102:105], v[162:165], v[214:217], v[102:105]
	v_mfma_f32_16x16x32_bf16 v[98:101], v[170:173], v[214:217], v[98:101]
	v_mfma_f32_16x16x32_bf16 v[42:45], v[162:165], v[222:225], v[42:45]
	v_mfma_f32_16x16x32_bf16 v[34:37], v[170:173], v[222:225], v[34:37]
	v_mfma_f32_16x16x32_bf16 v[126:129], v[166:169], v[200:203], v[126:129]
	v_mfma_f32_16x16x32_bf16 v[122:125], v[174:177], v[200:203], v[122:125]
	v_mfma_f32_16x16x32_bf16 v[118:121], v[166:169], v[210:213], v[118:121]
	v_mfma_f32_16x16x32_bf16 v[114:117], v[174:177], v[210:213], v[114:117]
	v_mfma_f32_16x16x32_bf16 v[102:105], v[166:169], v[218:221], v[102:105]
	v_mfma_f32_16x16x32_bf16 v[98:101], v[174:177], v[218:221], v[98:101]
	v_mfma_f32_16x16x32_bf16 v[42:45], v[166:169], v[226:229], v[42:45]
	v_mfma_f32_16x16x32_bf16 v[34:37], v[174:177], v[226:229], v[34:37]
	v_mfma_f32_16x16x32_bf16 v[110:113], v[178:181], v[196:199], v[110:113]
	v_mfma_f32_16x16x32_bf16 v[106:109], v[186:189], v[196:199], v[106:109]
	v_mfma_f32_16x16x32_bf16 v[94:97], v[178:181], v[206:209], v[94:97]
	v_mfma_f32_16x16x32_bf16 v[90:93], v[186:189], v[206:209], v[90:93]
	v_mfma_f32_16x16x32_bf16 v[86:89], v[178:181], v[214:217], v[86:89]
	v_mfma_f32_16x16x32_bf16 v[82:85], v[186:189], v[214:217], v[82:85]
	v_mfma_f32_16x16x32_bf16 v[30:33], v[178:181], v[222:225], v[30:33]
	v_mfma_f32_16x16x32_bf16 v[26:29], v[186:189], v[222:225], v[26:29]
	v_mfma_f32_16x16x32_bf16 v[110:113], v[182:185], v[200:203], v[110:113]
	v_mfma_f32_16x16x32_bf16 v[106:109], v[190:193], v[200:203], v[106:109]
	v_mfma_f32_16x16x32_bf16 v[94:97], v[182:185], v[210:213], v[94:97]
	v_mfma_f32_16x16x32_bf16 v[90:93], v[190:193], v[210:213], v[90:93]
	v_mfma_f32_16x16x32_bf16 v[86:89], v[182:185], v[218:221], v[86:89]
	v_mfma_f32_16x16x32_bf16 v[82:85], v[190:193], v[218:221], v[82:85]
	v_mfma_f32_16x16x32_bf16 v[30:33], v[182:185], v[226:229], v[30:33]
	v_mfma_f32_16x16x32_bf16 v[26:29], v[190:193], v[226:229], v[26:29]
	s_setprio 0
	s_barrier
	s_add_i32 s40, s66, s42
	v_lshl_add_u64 v[158:159], v[158:159], 0, s[12:13]
	s_mov_b32 m0, s40
	ds_read_b128 v[196:199], v160 offset:49152
	ds_read_b128 v[200:203], v160 offset:50176
	ds_read_b128 v[206:209], v160 offset:51200
	ds_read_b128 v[210:213], v160 offset:52224
	ds_read_b128 v[214:217], v160 offset:53248
	ds_read_b128 v[218:221], v160 offset:54272
	ds_read_b128 v[222:225], v160 offset:55296
	ds_read_b128 v[226:229], v160 offset:56320
	global_load_lds_dwordx4 v[158:159], off
	s_add_i32 m0, s40, 0x2000
	s_add_u32 s34, s34, 0x100080
	v_lshl_add_u64 v[158:159], v[230:231], 0, s[12:13]
	s_addc_u32 s35, s35, 0
	s_add_i32 s40, s67, s42
	global_load_lds_dwordx4 v[158:159], off
	v_lshl_add_u64 v[158:159], s[34:35], 0, v[134:135]
	s_mov_b32 m0, s40
	s_nop 0
	global_load_lds_dwordx4 v[158:159], off
	v_lshl_add_u64 v[158:159], s[34:35], 0, v[132:133]
	s_add_i32 m0, s40, 0x2000
	s_nop 0
	global_load_lds_dwordx4 v[158:159], off
	v_lshl_add_u64 v[158:159], v[232:233], 0, s[12:13]
	s_mov_b32 m0, s52
	s_nop 0
	global_load_lds_dwordx4 v[158:159], off
	v_lshl_add_u64 v[158:159], v[234:235], 0, s[12:13]
	s_mov_b32 m0, s53
	s_nop 0
	global_load_lds_dwordx4 v[158:159], off
	s_branch .Lal64_35
.Lal64_35:
	s_waitcnt vmcnt(8)
	s_waitcnt lgkmcnt(0)
	s_barrier
	s_setprio 1
	v_mfma_f32_16x16x32_bf16 v[78:81], v[162:165], v[196:199], v[78:81]
	v_mfma_f32_16x16x32_bf16 v[74:77], v[170:173], v[196:199], v[74:77]
	v_mfma_f32_16x16x32_bf16 v[70:73], v[162:165], v[206:209], v[70:73]
	v_mfma_f32_16x16x32_bf16 v[66:69], v[170:173], v[206:209], v[66:69]
	v_mfma_f32_16x16x32_bf16 v[54:57], v[162:165], v[214:217], v[54:57]
	v_mfma_f32_16x16x32_bf16 v[50:53], v[170:173], v[214:217], v[50:53]
	v_mfma_f32_16x16x32_bf16 v[14:17], v[162:165], v[222:225], v[14:17]
	v_mfma_f32_16x16x32_bf16 v[10:13], v[170:173], v[222:225], v[10:13]
	v_mfma_f32_16x16x32_bf16 v[78:81], v[166:169], v[200:203], v[78:81]
	v_mfma_f32_16x16x32_bf16 v[74:77], v[174:177], v[200:203], v[74:77]
	v_mfma_f32_16x16x32_bf16 v[70:73], v[166:169], v[210:213], v[70:73]
	v_mfma_f32_16x16x32_bf16 v[66:69], v[174:177], v[210:213], v[66:69]
	v_mfma_f32_16x16x32_bf16 v[54:57], v[166:169], v[218:221], v[54:57]
	v_mfma_f32_16x16x32_bf16 v[50:53], v[174:177], v[218:221], v[50:53]
	v_mfma_f32_16x16x32_bf16 v[14:17], v[166:169], v[226:229], v[14:17]
	v_mfma_f32_16x16x32_bf16 v[10:13], v[174:177], v[226:229], v[10:13]
	v_mfma_f32_16x16x32_bf16 v[62:65], v[178:181], v[196:199], v[62:65]
	v_mfma_f32_16x16x32_bf16 v[58:61], v[186:189], v[196:199], v[58:61]
	v_mfma_f32_16x16x32_bf16 v[46:49], v[178:181], v[206:209], v[46:49]
	v_mfma_f32_16x16x32_bf16 v[38:41], v[186:189], v[206:209], v[38:41]
	v_mfma_f32_16x16x32_bf16 v[22:25], v[178:181], v[214:217], v[22:25]
	v_mfma_f32_16x16x32_bf16 v[18:21], v[186:189], v[214:217], v[18:21]
	v_mfma_f32_16x16x32_bf16 v[6:9], v[178:181], v[222:225], v[6:9]
	v_mfma_f32_16x16x32_bf16 v[2:5], v[186:189], v[222:225], v[2:5]
	v_mfma_f32_16x16x32_bf16 v[62:65], v[182:185], v[200:203], v[62:65]
	v_mfma_f32_16x16x32_bf16 v[58:61], v[190:193], v[200:203], v[58:61]
	v_mfma_f32_16x16x32_bf16 v[46:49], v[182:185], v[210:213], v[46:49]
	v_mfma_f32_16x16x32_bf16 v[38:41], v[190:193], v[210:213], v[38:41]
	v_mfma_f32_16x16x32_bf16 v[22:25], v[182:185], v[218:221], v[22:25]
	v_mfma_f32_16x16x32_bf16 v[18:21], v[190:193], v[218:221], v[18:21]
	v_mfma_f32_16x16x32_bf16 v[6:9], v[182:185], v[226:229], v[6:9]
	v_mfma_f32_16x16x32_bf16 v[2:5], v[190:193], v[226:229], v[2:5]
	s_setprio 0
	s_barrier
	s_add_u32 s30, s30, 0x100
	s_addc_u32 s31, s31, 0
	s_add_u32 s63, s63, 0x100
	s_addc_u32 s64, s64, 0
	s_cmp_ge_i32 s65, s60
	s_mov_b32 s34, s65
	s_cbranch_scc0 .LBB0_1197
	s_and_b64 vcc, exec, s[18:19]
	s_cbranch_vccz .LBB0_1200
	s_barrier

.LBB0_1391:
	ds_read_b128 v[152:155], v159
	ds_read_b128 v[162:165], v159 offset:1024
	ds_read_b128 v[166:169], v159 offset:2048
	ds_read_b128 v[170:173], v159 offset:3072
	ds_read_b128 v[174:177], v160
	ds_read_b128 v[178:181], v160 offset:1024
	ds_read_b128 v[182:185], v160 offset:2048
	ds_read_b128 v[186:189], v160 offset:3072
	s_add_i32 s82, s48, 2
	s_add_u32 s49, s60, 0xfffe0080
	s_addc_u32 s62, s61, -1
	s_cmp_eq_u32 s47, s48
	s_cselect_b32 s48, s54, s51
	s_cselect_b32 s63, s9, s62
	s_cselect_b32 s62, s8, s49
	s_cselect_b32 s49, s55, s53
	v_lshl_add_u64 v[156:157], s[60:61], 0, v[140:141]
	s_add_i32 m0, s57, 0xc000
	ds_read_b128 v[190:193], v161
	ds_read_b128 v[196:199], v161 offset:1024
	ds_read_b128 v[200:203], v161 offset:2048
	ds_read_b128 v[206:209], v161 offset:3072
	ds_read_b128 v[210:213], v161 offset:4096
	ds_read_b128 v[214:217], v161 offset:5120
	ds_read_b128 v[218:221], v161 offset:6144
	ds_read_b128 v[222:225], v161 offset:7168
	global_load_lds_dwordx4 v[156:157], off
	v_lshl_add_u64 v[156:157], s[60:61], 0, v[142:143]
	s_add_i32 m0, s57, 0xe000
	s_nop 0
	global_load_lds_dwordx4 v[156:157], off
	s_branch .Lal64_36
	s_nop 0
	s_nop 0
	s_nop 0
	s_nop 0
	s_nop 0
	s_nop 0
	s_nop 0
	s_nop 0
	s_nop 0
	s_nop 0
	s_nop 0
	s_nop 0
.Lal64_36:
	s_waitcnt vmcnt(8)
	s_waitcnt lgkmcnt(0)
	s_barrier
	s_setprio 1
	v_mfma_f32_16x16x32_bf16 v[126:129], v[152:155], v[190:193], v[126:129]
	v_mfma_f32_16x16x32_bf16 v[122:125], v[166:169], v[190:193], v[122:125]
	v_mfma_f32_16x16x32_bf16 v[110:113], v[152:155], v[200:203], v[110:113]
	v_mfma_f32_16x16x32_bf16 v[106:109], v[166:169], v[200:203], v[106:109]
	v_mfma_f32_16x16x32_bf16 v[94:97], v[152:155], v[210:213], v[94:97]
	v_mfma_f32_16x16x32_bf16 v[90:93], v[166:169], v[210:213], v[90:93]
	v_mfma_f32_16x16x32_bf16 v[78:81], v[152:155], v[218:221], v[78:81]
	v_mfma_f32_16x16x32_bf16 v[74:77], v[166:169], v[218:221], v[74:77]
	v_mfma_f32_16x16x32_bf16 v[126:129], v[162:165], v[196:199], v[126:129]
	v_mfma_f32_16x16x32_bf16 v[122:125], v[170:173], v[196:199], v[122:125]
	v_mfma_f32_16x16x32_bf16 v[110:113], v[162:165], v[206:209], v[110:113]
	v_mfma_f32_16x16x32_bf16 v[106:109], v[170:173], v[206:209], v[106:109]
	v_mfma_f32_16x16x32_bf16 v[94:97], v[162:165], v[214:217], v[94:97]
	v_mfma_f32_16x16x32_bf16 v[90:93], v[170:173], v[214:217], v[90:93]
	v_mfma_f32_16x16x32_bf16 v[78:81], v[162:165], v[222:225], v[78:81]
	v_mfma_f32_16x16x32_bf16 v[74:77], v[170:173], v[222:225], v[74:77]
	v_mfma_f32_16x16x32_bf16 v[118:121], v[174:177], v[190:193], v[118:121]
	v_mfma_f32_16x16x32_bf16 v[114:117], v[182:185], v[190:193], v[114:117]
	v_mfma_f32_16x16x32_bf16 v[102:105], v[174:177], v[200:203], v[102:105]
	v_mfma_f32_16x16x32_bf16 v[98:101], v[182:185], v[200:203], v[98:101]
	v_mfma_f32_16x16x32_bf16 v[86:89], v[174:177], v[210:213], v[86:89]
	v_mfma_f32_16x16x32_bf16 v[82:85], v[182:185], v[210:213], v[82:85]
	v_mfma_f32_16x16x32_bf16 v[70:73], v[174:177], v[218:221], v[70:73]
	v_mfma_f32_16x16x32_bf16 v[66:69], v[182:185], v[218:221], v[66:69]
	v_mfma_f32_16x16x32_bf16 v[118:121], v[178:181], v[196:199], v[118:121]
	v_mfma_f32_16x16x32_bf16 v[114:117], v[186:189], v[196:199], v[114:117]
	v_mfma_f32_16x16x32_bf16 v[102:105], v[178:181], v[206:209], v[102:105]
	v_mfma_f32_16x16x32_bf16 v[98:101], v[186:189], v[206:209], v[98:101]
	v_mfma_f32_16x16x32_bf16 v[86:89], v[178:181], v[214:217], v[86:89]
	v_mfma_f32_16x16x32_bf16 v[82:85], v[186:189], v[214:217], v[82:85]
	v_mfma_f32_16x16x32_bf16 v[70:73], v[178:181], v[222:225], v[70:73]
	v_mfma_f32_16x16x32_bf16 v[66:69], v[186:189], v[222:225], v[66:69]
	s_setprio 0
	s_barrier
	s_add_i32 s83, s73, s64
	v_lshl_add_u64 v[156:157], s[48:49], 0, v[134:135]
	s_mov_b32 m0, s83
	ds_read_b128 v[190:193], v161 offset:16384
	ds_read_b128 v[196:199], v161 offset:17408
	ds_read_b128 v[200:203], v161 offset:18432
	ds_read_b128 v[206:209], v161 offset:19456
	ds_read_b128 v[210:213], v161 offset:20480
	ds_read_b128 v[214:217], v161 offset:21504
	ds_read_b128 v[218:221], v161 offset:22528
	ds_read_b128 v[222:225], v161 offset:23552
	global_load_lds_dwordx4 v[156:157], off
	s_add_i32 m0, s83, 0x2000
	s_add_u32 s84, s48, 0x20000
	v_lshl_add_u64 v[226:227], s[48:49], 0, v[138:139]
	s_addc_u32 s85, s49, 0
	s_add_i32 s83, s74, s64
	global_load_lds_dwordx4 v[226:227], off
	v_lshl_add_u64 v[228:229], s[84:85], 0, v[134:135]
	s_mov_b32 m0, s83
	v_lshl_add_u64 v[230:231], s[62:63], 0, v[136:137]
	global_load_lds_dwordx4 v[228:229], off
	v_lshl_add_u64 v[228:229], s[84:85], 0, v[138:139]
	s_add_i32 m0, s83, 0x2000
	s_nop 0
	global_load_lds_dwordx4 v[228:229], off
	v_lshl_add_u64 v[228:229], s[62:63], 0, v[132:133]
	s_mov_b32 m0, s57
	s_nop 0
	global_load_lds_dwordx4 v[228:229], off
	s_mov_b32 m0, s59
	s_nop 0
	global_load_lds_dwordx4 v[230:231], off
	s_branch .Lal64_37
	s_nop 0
.Lal64_37:
	s_waitcnt vmcnt(8)
	s_waitcnt lgkmcnt(0)
	s_barrier
	s_setprio 1
	v_mfma_f32_16x16x32_bf16 v[62:65], v[152:155], v[190:193], v[62:65]
	v_mfma_f32_16x16x32_bf16 v[58:61], v[166:169], v[190:193], v[58:61]
	v_mfma_f32_16x16x32_bf16 v[46:49], v[152:155], v[200:203], v[46:49]
	v_mfma_f32_16x16x32_bf16 v[42:45], v[166:169], v[200:203], v[42:45]
	v_mfma_f32_16x16x32_bf16 v[30:33], v[152:155], v[210:213], v[30:33]
	v_mfma_f32_16x16x32_bf16 v[26:29], v[166:169], v[210:213], v[26:29]
	v_mfma_f32_16x16x32_bf16 v[14:17], v[152:155], v[218:221], v[14:17]
	v_mfma_f32_16x16x32_bf16 v[10:13], v[166:169], v[218:221], v[10:13]
	v_mfma_f32_16x16x32_bf16 v[62:65], v[162:165], v[196:199], v[62:65]
	v_mfma_f32_16x16x32_bf16 v[58:61], v[170:173], v[196:199], v[58:61]
	v_mfma_f32_16x16x32_bf16 v[46:49], v[162:165], v[206:209], v[46:49]
	v_mfma_f32_16x16x32_bf16 v[42:45], v[170:173], v[206:209], v[42:45]
	v_mfma_f32_16x16x32_bf16 v[30:33], v[162:165], v[214:217], v[30:33]
	v_mfma_f32_16x16x32_bf16 v[26:29], v[170:173], v[214:217], v[26:29]
	v_mfma_f32_16x16x32_bf16 v[14:17], v[162:165], v[222:225], v[14:17]
	v_mfma_f32_16x16x32_bf16 v[10:13], v[170:173], v[222:225], v[10:13]
	v_mfma_f32_16x16x32_bf16 v[54:57], v[174:177], v[190:193], v[54:57]
	v_mfma_f32_16x16x32_bf16 v[50:53], v[182:185], v[190:193], v[50:53]
	v_mfma_f32_16x16x32_bf16 v[38:41], v[174:177], v[200:203], v[38:41]
	v_mfma_f32_16x16x32_bf16 v[34:37], v[182:185], v[200:203], v[34:37]
	v_mfma_f32_16x16x32_bf16 v[22:25], v[174:177], v[210:213], v[22:25]
	v_mfma_f32_16x16x32_bf16 v[18:21], v[182:185], v[210:213], v[18:21]
	v_mfma_f32_16x16x32_bf16 v[6:9], v[174:177], v[218:221], v[6:9]
	v_mfma_f32_16x16x32_bf16 v[2:5], v[182:185], v[218:221], v[2:5]
	v_mfma_f32_16x16x32_bf16 v[54:57], v[178:181], v[196:199], v[54:57]
	v_mfma_f32_16x16x32_bf16 v[50:53], v[186:189], v[196:199], v[50:53]
	v_mfma_f32_16x16x32_bf16 v[38:41], v[178:181], v[206:209], v[38:41]
	v_mfma_f32_16x16x32_bf16 v[34:37], v[186:189], v[206:209], v[34:37]
	v_mfma_f32_16x16x32_bf16 v[22:25], v[178:181], v[214:217], v[22:25]
	v_mfma_f32_16x16x32_bf16 v[18:21], v[186:189], v[214:217], v[18:21]
	v_mfma_f32_16x16x32_bf16 v[6:9], v[178:181], v[222:225], v[6:9]
	v_mfma_f32_16x16x32_bf16 v[2:5], v[186:189], v[222:225], v[2:5]
	s_setprio 0
	s_barrier
	s_add_i32 s83, 0, 0x18000
	s_add_i32 s84, 0, 0x1c000
	v_add_u32_e32 v170, s83, v131
	v_add_u32_e32 v186, s84, v131
	ds_read_b128 v[152:155], v170
	ds_read_b128 v[162:165], v170 offset:1024
	ds_read_b128 v[166:169], v170 offset:2048
	ds_read_b128 v[170:173], v170 offset:3072
	ds_read_b128 v[174:177], v186
	ds_read_b128 v[178:181], v186 offset:1024
	ds_read_b128 v[182:185], v186 offset:2048
	ds_read_b128 v[186:189], v186 offset:3072
	s_add_u32 s62, s62, 0x20000
	s_addc_u32 s63, s63, 0
	s_mov_b32 m0, s65
	v_lshl_add_u64 v[232:233], s[62:63], 0, v[132:133]
	ds_read_b128 v[190:193], v161 offset:32768
	ds_read_b128 v[196:199], v161 offset:33792
	ds_read_b128 v[200:203], v161 offset:34816
	ds_read_b128 v[206:209], v161 offset:35840
	ds_read_b128 v[210:213], v161 offset:36864
	ds_read_b128 v[214:217], v161 offset:37888
	ds_read_b128 v[218:221], v161 offset:38912
	ds_read_b128 v[222:225], v161 offset:39936
	global_load_lds_dwordx4 v[232:233], off
	v_lshl_add_u64 v[232:233], s[62:63], 0, v[136:137]
	s_mov_b32 m0, s66
	s_nop 0
	global_load_lds_dwordx4 v[232:233], off
	s_branch .Lal64_38
	s_nop 0
	s_nop 0
	s_nop 0
	s_nop 0
	s_nop 0
.Lal64_38:
	s_waitcnt vmcnt(8)
	s_waitcnt lgkmcnt(0)
	s_barrier
	s_setprio 1
	v_mfma_f32_16x16x32_bf16 v[126:129], v[152:155], v[190:193], v[126:129]
	v_mfma_f32_16x16x32_bf16 v[122:125], v[166:169], v[190:193], v[122:125]
	v_mfma_f32_16x16x32_bf16 v[110:113], v[152:155], v[200:203], v[110:113]
	v_mfma_f32_16x16x32_bf16 v[106:109], v[166:169], v[200:203], v[106:109]
	v_mfma_f32_16x16x32_bf16 v[94:97], v[152:155], v[210:213], v[94:97]
	v_mfma_f32_16x16x32_bf16 v[90:93], v[166:169], v[210:213], v[90:93]
	v_mfma_f32_16x16x32_bf16 v[78:81], v[152:155], v[218:221], v[78:81]
	v_mfma_f32_16x16x32_bf16 v[74:77], v[166:169], v[218:221], v[74:77]
	v_mfma_f32_16x16x32_bf16 v[126:129], v[162:165], v[196:199], v[126:129]
	v_mfma_f32_16x16x32_bf16 v[122:125], v[170:173], v[196:199], v[122:125]
	v_mfma_f32_16x16x32_bf16 v[110:113], v[162:165], v[206:209], v[110:113]
	v_mfma_f32_16x16x32_bf16 v[106:109], v[170:173], v[206:209], v[106:109]
	v_mfma_f32_16x16x32_bf16 v[94:97], v[162:165], v[214:217], v[94:97]
	v_mfma_f32_16x16x32_bf16 v[90:93], v[170:173], v[214:217], v[90:93]
	v_mfma_f32_16x16x32_bf16 v[78:81], v[162:165], v[222:225], v[78:81]
	v_mfma_f32_16x16x32_bf16 v[74:77], v[170:173], v[222:225], v[74:77]
	v_mfma_f32_16x16x32_bf16 v[118:121], v[174:177], v[190:193], v[118:121]
	v_mfma_f32_16x16x32_bf16 v[114:117], v[182:185], v[190:193], v[114:117]
	v_mfma_f32_16x16x32_bf16 v[102:105], v[174:177], v[200:203], v[102:105]
	v_mfma_f32_16x16x32_bf16 v[98:101], v[182:185], v[200:203], v[98:101]
	v_mfma_f32_16x16x32_bf16 v[86:89], v[174:177], v[210:213], v[86:89]
	v_mfma_f32_16x16x32_bf16 v[82:85], v[182:185], v[210:213], v[82:85]
	v_mfma_f32_16x16x32_bf16 v[70:73], v[174:177], v[218:221], v[70:73]
	v_mfma_f32_16x16x32_bf16 v[66:69], v[182:185], v[218:221], v[66:69]
	v_mfma_f32_16x16x32_bf16 v[118:121], v[178:181], v[196:199], v[118:121]
	v_mfma_f32_16x16x32_bf16 v[114:117], v[186:189], v[196:199], v[114:117]
	v_mfma_f32_16x16x32_bf16 v[102:105], v[178:181], v[206:209], v[102:105]
	v_mfma_f32_16x16x32_bf16 v[98:101], v[186:189], v[206:209], v[98:101]
	v_mfma_f32_16x16x32_bf16 v[86:89], v[178:181], v[214:217], v[86:89]
	v_mfma_f32_16x16x32_bf16 v[82:85], v[186:189], v[214:217], v[82:85]
	v_mfma_f32_16x16x32_bf16 v[70:73], v[178:181], v[222:225], v[70:73]
	v_mfma_f32_16x16x32_bf16 v[66:69], v[186:189], v[222:225], v[66:69]
	s_setprio 0
	s_barrier
	s_add_i32 s62, s83, s64
	v_lshl_add_u64 v[156:157], v[156:157], 0, s[18:19]
	s_mov_b32 m0, s62
	ds_read_b128 v[190:193], v161 offset:49152
	ds_read_b128 v[196:199], v161 offset:50176
	ds_read_b128 v[200:203], v161 offset:51200
	ds_read_b128 v[206:209], v161 offset:52224
	ds_read_b128 v[210:213], v161 offset:53248
	ds_read_b128 v[214:217], v161 offset:54272
	ds_read_b128 v[218:221], v161 offset:55296
	ds_read_b128 v[222:225], v161 offset:56320
	global_load_lds_dwordx4 v[156:157], off
	s_add_i32 m0, s62, 0x2000
	s_add_u32 s48, s48, 0x20080
	v_lshl_add_u64 v[156:157], v[226:227], 0, s[18:19]
	s_addc_u32 s49, s49, 0
	s_add_i32 s62, s84, s64
	global_load_lds_dwordx4 v[156:157], off
	v_lshl_add_u64 v[156:157], s[48:49], 0, v[134:135]
	s_mov_b32 m0, s62
	s_nop 0
	global_load_lds_dwordx4 v[156:157], off
	v_lshl_add_u64 v[156:157], s[48:49], 0, v[138:139]
	s_add_i32 m0, s62, 0x2000
	s_nop 0
	global_load_lds_dwordx4 v[156:157], off
	v_lshl_add_u64 v[156:157], v[228:229], 0, s[18:19]
	s_mov_b32 m0, s70
	s_nop 0
	global_load_lds_dwordx4 v[156:157], off
	v_lshl_add_u64 v[156:157], v[230:231], 0, s[18:19]
	s_mov_b32 m0, s71
	s_nop 0
	global_load_lds_dwordx4 v[156:157], off
	s_branch .Lal64_39
.Lal64_39:
	s_waitcnt vmcnt(8)
	s_waitcnt lgkmcnt(0)
	s_barrier
	s_setprio 1
	v_mfma_f32_16x16x32_bf16 v[62:65], v[152:155], v[190:193], v[62:65]
	v_mfma_f32_16x16x32_bf16 v[58:61], v[166:169], v[190:193], v[58:61]
	v_mfma_f32_16x16x32_bf16 v[46:49], v[152:155], v[200:203], v[46:49]
	v_mfma_f32_16x16x32_bf16 v[42:45], v[166:169], v[200:203], v[42:45]
	v_mfma_f32_16x16x32_bf16 v[30:33], v[152:155], v[210:213], v[30:33]
	v_mfma_f32_16x16x32_bf16 v[26:29], v[166:169], v[210:213], v[26:29]
	v_mfma_f32_16x16x32_bf16 v[14:17], v[152:155], v[218:221], v[14:17]
	v_mfma_f32_16x16x32_bf16 v[10:13], v[166:169], v[218:221], v[10:13]
	v_mfma_f32_16x16x32_bf16 v[62:65], v[162:165], v[196:199], v[62:65]
	v_mfma_f32_16x16x32_bf16 v[58:61], v[170:173], v[196:199], v[58:61]
	v_mfma_f32_16x16x32_bf16 v[46:49], v[162:165], v[206:209], v[46:49]
	v_mfma_f32_16x16x32_bf16 v[42:45], v[170:173], v[206:209], v[42:45]
	v_mfma_f32_16x16x32_bf16 v[30:33], v[162:165], v[214:217], v[30:33]
	v_mfma_f32_16x16x32_bf16 v[26:29], v[170:173], v[214:217], v[26:29]
	v_mfma_f32_16x16x32_bf16 v[14:17], v[162:165], v[222:225], v[14:17]
	v_mfma_f32_16x16x32_bf16 v[10:13], v[170:173], v[222:225], v[10:13]
	v_mfma_f32_16x16x32_bf16 v[54:57], v[174:177], v[190:193], v[54:57]
	v_mfma_f32_16x16x32_bf16 v[50:53], v[182:185], v[190:193], v[50:53]
	v_mfma_f32_16x16x32_bf16 v[38:41], v[174:177], v[200:203], v[38:41]
	v_mfma_f32_16x16x32_bf16 v[34:37], v[182:185], v[200:203], v[34:37]
	v_mfma_f32_16x16x32_bf16 v[22:25], v[174:177], v[210:213], v[22:25]
	v_mfma_f32_16x16x32_bf16 v[18:21], v[182:185], v[210:213], v[18:21]
	v_mfma_f32_16x16x32_bf16 v[6:9], v[174:177], v[218:221], v[6:9]
	v_mfma_f32_16x16x32_bf16 v[2:5], v[182:185], v[218:221], v[2:5]
	v_mfma_f32_16x16x32_bf16 v[54:57], v[178:181], v[196:199], v[54:57]
	v_mfma_f32_16x16x32_bf16 v[50:53], v[186:189], v[196:199], v[50:53]
	v_mfma_f32_16x16x32_bf16 v[38:41], v[178:181], v[206:209], v[38:41]
	v_mfma_f32_16x16x32_bf16 v[34:37], v[186:189], v[206:209], v[34:37]
	v_mfma_f32_16x16x32_bf16 v[22:25], v[178:181], v[214:217], v[22:25]
	v_mfma_f32_16x16x32_bf16 v[18:21], v[186:189], v[214:217], v[18:21]
	v_mfma_f32_16x16x32_bf16 v[6:9], v[178:181], v[222:225], v[6:9]
	v_mfma_f32_16x16x32_bf16 v[2:5], v[186:189], v[222:225], v[2:5]
	s_setprio 0
	s_barrier
	s_add_u32 s60, s60, 0x100
	s_addc_u32 s61, s61, 0
	s_add_u32 s51, s51, 0x100
	s_addc_u32 s53, s53, 0
	s_cmp_ge_i32 s82, s81
	s_mov_b32 s48, s82
	s_cbranch_scc0 .LBB0_1391
	s_and_b64 vcc, exec, s[20:21]
	s_cbranch_vccz .LBB0_1394
	s_barrier

.LBB0_1553:
	ds_read_b128 v[156:159], v161
	ds_read_b128 v[164:167], v161 offset:1024
	ds_read_b128 v[168:171], v161 offset:2048
	ds_read_b128 v[172:175], v161 offset:3072
	ds_read_b128 v[176:179], v162
	ds_read_b128 v[180:183], v162 offset:1024
	ds_read_b128 v[184:187], v162 offset:2048
	ds_read_b128 v[188:191], v162 offset:3072
	s_add_i32 s76, s48, 2
	s_add_u32 s49, s46, 0xfff00080
	s_addc_u32 s50, s47, -1
	s_cmp_eq_u32 s73, s48
	s_cselect_b32 s48, s29, s74
	s_cselect_b32 s51, s9, s50
	s_cselect_b32 s50, s27, s49
	s_cselect_b32 s49, s25, s75
	v_lshl_add_u64 v[192:193], s[46:47], 0, v[148:149]
	s_add_i32 m0, s43, 0xc000
	ds_read_b128 v[196:199], v163
	ds_read_b128 v[200:203], v163 offset:1024
	ds_read_b128 v[206:209], v163 offset:2048
	ds_read_b128 v[210:213], v163 offset:3072
	ds_read_b128 v[214:217], v163 offset:4096
	ds_read_b128 v[218:221], v163 offset:5120
	ds_read_b128 v[222:225], v163 offset:6144
	ds_read_b128 v[226:229], v163 offset:7168
	global_load_lds_dwordx4 v[192:193], off
	v_lshl_add_u64 v[192:193], s[46:47], 0, v[150:151]
	s_add_i32 m0, s43, 0xe000
	s_nop 0
	global_load_lds_dwordx4 v[192:193], off
	s_branch .Lal64_40
	s_nop 0
	s_nop 0
	s_nop 0
	s_nop 0
	s_nop 0
	s_nop 0
	s_nop 0
	s_nop 0
.Lal64_40:
	s_waitcnt vmcnt(8)
	s_waitcnt lgkmcnt(0)
	s_barrier
	s_setprio 1
	v_mfma_f32_16x16x32_bf16 v[78:81], v[156:159], v[196:199], v[78:81]
	v_mfma_f32_16x16x32_bf16 v[74:77], v[168:171], v[196:199], v[74:77]
	v_mfma_f32_16x16x32_bf16 v[70:73], v[156:159], v[206:209], v[70:73]
	v_mfma_f32_16x16x32_bf16 v[62:65], v[168:171], v[206:209], v[62:65]
	v_mfma_f32_16x16x32_bf16 v[58:61], v[156:159], v[214:217], v[58:61]
	v_mfma_f32_16x16x32_bf16 v[54:57], v[168:171], v[214:217], v[54:57]
	v_mfma_f32_16x16x32_bf16 v[46:49], v[156:159], v[222:225], v[46:49]
	v_mfma_f32_16x16x32_bf16 v[38:41], v[168:171], v[222:225], v[38:41]
	v_mfma_f32_16x16x32_bf16 v[78:81], v[164:167], v[200:203], v[78:81]
	v_mfma_f32_16x16x32_bf16 v[74:77], v[172:175], v[200:203], v[74:77]
	v_mfma_f32_16x16x32_bf16 v[70:73], v[164:167], v[210:213], v[70:73]
	v_mfma_f32_16x16x32_bf16 v[62:65], v[172:175], v[210:213], v[62:65]
	v_mfma_f32_16x16x32_bf16 v[58:61], v[164:167], v[218:221], v[58:61]
	v_mfma_f32_16x16x32_bf16 v[54:57], v[172:175], v[218:221], v[54:57]
	v_mfma_f32_16x16x32_bf16 v[46:49], v[164:167], v[226:229], v[46:49]
	v_mfma_f32_16x16x32_bf16 v[38:41], v[172:175], v[226:229], v[38:41]
	v_mfma_f32_16x16x32_bf16 v[50:53], v[176:179], v[196:199], v[50:53]
	v_mfma_f32_16x16x32_bf16 v[42:45], v[184:187], v[196:199], v[42:45]
	v_mfma_f32_16x16x32_bf16 v[34:37], v[176:179], v[206:209], v[34:37]
	v_mfma_f32_16x16x32_bf16 v[26:29], v[184:187], v[206:209], v[26:29]
	v_mfma_f32_16x16x32_bf16 v[18:21], v[176:179], v[214:217], v[18:21]
	v_mfma_f32_16x16x32_bf16 v[14:17], v[184:187], v[214:217], v[14:17]
	v_mfma_f32_16x16x32_bf16 v[10:13], v[176:179], v[222:225], v[10:13]
	v_mfma_f32_16x16x32_bf16 v[6:9], v[184:187], v[222:225], v[6:9]
	v_mfma_f32_16x16x32_bf16 v[50:53], v[180:183], v[200:203], v[50:53]
	v_mfma_f32_16x16x32_bf16 v[42:45], v[188:191], v[200:203], v[42:45]
	v_mfma_f32_16x16x32_bf16 v[34:37], v[180:183], v[210:213], v[34:37]
	v_mfma_f32_16x16x32_bf16 v[26:29], v[188:191], v[210:213], v[26:29]
	v_mfma_f32_16x16x32_bf16 v[18:21], v[180:183], v[218:221], v[18:21]
	v_mfma_f32_16x16x32_bf16 v[14:17], v[188:191], v[218:221], v[14:17]
	v_mfma_f32_16x16x32_bf16 v[10:13], v[180:183], v[226:229], v[10:13]
	v_mfma_f32_16x16x32_bf16 v[6:9], v[188:191], v[226:229], v[6:9]
	s_setprio 0
	s_barrier
	s_add_i32 s77, s66, s53
	v_lshl_add_u64 v[192:193], s[48:49], 0, v[134:135]
	s_mov_b32 m0, s77
	ds_read_b128 v[196:199], v163 offset:16384
	ds_read_b128 v[200:203], v163 offset:17408
	ds_read_b128 v[206:209], v163 offset:18432
	ds_read_b128 v[210:213], v163 offset:19456
	ds_read_b128 v[214:217], v163 offset:20480
	ds_read_b128 v[218:221], v163 offset:21504
	ds_read_b128 v[222:225], v163 offset:22528
	ds_read_b128 v[226:229], v163 offset:23552
	global_load_lds_dwordx4 v[192:193], off
	s_add_i32 m0, s77, 0x2000
	s_add_u32 s78, s48, 0x100000
	v_lshl_add_u64 v[230:231], s[48:49], 0, v[138:139]
	s_addc_u32 s79, s49, 0
	s_add_i32 s77, s67, s53
	global_load_lds_dwordx4 v[230:231], off
	v_lshl_add_u64 v[232:233], s[78:79], 0, v[134:135]
	s_mov_b32 m0, s77
	v_lshl_add_u64 v[234:235], s[50:51], 0, v[136:137]
	global_load_lds_dwordx4 v[232:233], off
	v_lshl_add_u64 v[232:233], s[78:79], 0, v[138:139]
	s_add_i32 m0, s77, 0x2000
	s_nop 0
	global_load_lds_dwordx4 v[232:233], off
	v_lshl_add_u64 v[232:233], s[50:51], 0, v[132:133]
	s_mov_b32 m0, s43
	s_nop 0
	global_load_lds_dwordx4 v[232:233], off
	s_mov_b32 m0, s54
	s_nop 0
	global_load_lds_dwordx4 v[234:235], off
	s_branch .Lal64_41
	s_nop 0
.Lal64_41:
	s_waitcnt vmcnt(8)
	s_waitcnt lgkmcnt(0)
	s_barrier
	s_setprio 1
	v_mfma_f32_16x16x32_bf16 v[126:129], v[156:159], v[196:199], v[126:129]
	v_mfma_f32_16x16x32_bf16 v[118:121], v[168:171], v[196:199], v[118:121]
	v_mfma_f32_16x16x32_bf16 v[110:113], v[156:159], v[206:209], v[110:113]
	v_mfma_f32_16x16x32_bf16 v[102:105], v[168:171], v[206:209], v[102:105]
	v_mfma_f32_16x16x32_bf16 v[94:97], v[156:159], v[214:217], v[94:97]
	v_mfma_f32_16x16x32_bf16 v[86:89], v[168:171], v[214:217], v[86:89]
	v_mfma_f32_16x16x32_bf16 v[66:69], v[156:159], v[222:225], v[66:69]
	v_mfma_f32_16x16x32_bf16 v[22:25], v[168:171], v[222:225], v[22:25]
	v_mfma_f32_16x16x32_bf16 v[126:129], v[164:167], v[200:203], v[126:129]
	v_mfma_f32_16x16x32_bf16 v[118:121], v[172:175], v[200:203], v[118:121]
	v_mfma_f32_16x16x32_bf16 v[110:113], v[164:167], v[210:213], v[110:113]
	v_mfma_f32_16x16x32_bf16 v[102:105], v[172:175], v[210:213], v[102:105]
	v_mfma_f32_16x16x32_bf16 v[94:97], v[164:167], v[218:221], v[94:97]
	v_mfma_f32_16x16x32_bf16 v[86:89], v[172:175], v[218:221], v[86:89]
	v_mfma_f32_16x16x32_bf16 v[66:69], v[164:167], v[226:229], v[66:69]
	v_mfma_f32_16x16x32_bf16 v[22:25], v[172:175], v[226:229], v[22:25]
	v_mfma_f32_16x16x32_bf16 v[122:125], v[176:179], v[196:199], v[122:125]
	v_mfma_f32_16x16x32_bf16 v[114:117], v[184:187], v[196:199], v[114:117]
	v_mfma_f32_16x16x32_bf16 v[106:109], v[176:179], v[206:209], v[106:109]
	v_mfma_f32_16x16x32_bf16 v[98:101], v[184:187], v[206:209], v[98:101]
	v_mfma_f32_16x16x32_bf16 v[90:93], v[176:179], v[214:217], v[90:93]
	v_mfma_f32_16x16x32_bf16 v[82:85], v[184:187], v[214:217], v[82:85]
	v_mfma_f32_16x16x32_bf16 v[30:33], v[176:179], v[222:225], v[30:33]
	v_mfma_f32_16x16x32_bf16 v[2:5], v[184:187], v[222:225], v[2:5]
	v_mfma_f32_16x16x32_bf16 v[122:125], v[180:183], v[200:203], v[122:125]
	v_mfma_f32_16x16x32_bf16 v[114:117], v[188:191], v[200:203], v[114:117]
	v_mfma_f32_16x16x32_bf16 v[106:109], v[180:183], v[210:213], v[106:109]
	v_mfma_f32_16x16x32_bf16 v[98:101], v[188:191], v[210:213], v[98:101]
	v_mfma_f32_16x16x32_bf16 v[90:93], v[180:183], v[218:221], v[90:93]
	v_mfma_f32_16x16x32_bf16 v[82:85], v[188:191], v[218:221], v[82:85]
	v_mfma_f32_16x16x32_bf16 v[30:33], v[180:183], v[226:229], v[30:33]
	v_mfma_f32_16x16x32_bf16 v[2:5], v[188:191], v[226:229], v[2:5]
	s_setprio 0
	s_barrier
	s_add_i32 s77, 0, 0x18000
	s_add_i32 s78, 0, 0x1c000
	v_add_u32_e32 v172, s77, v131
	v_add_u32_e32 v188, s78, v131
	ds_read_b128 v[156:159], v172
	ds_read_b128 v[164:167], v172 offset:1024
	ds_read_b128 v[168:171], v172 offset:2048
	ds_read_b128 v[172:175], v172 offset:3072
	ds_read_b128 v[176:179], v188
	ds_read_b128 v[180:183], v188 offset:1024
	ds_read_b128 v[184:187], v188 offset:2048
	ds_read_b128 v[188:191], v188 offset:3072
	s_add_u32 s50, s50, 0x100000
	s_addc_u32 s51, s51, 0
	s_mov_b32 m0, s55
	v_lshl_add_u64 v[236:237], s[50:51], 0, v[132:133]
	ds_read_b128 v[196:199], v163 offset:32768
	ds_read_b128 v[200:203], v163 offset:33792
	ds_read_b128 v[206:209], v163 offset:34816
	ds_read_b128 v[210:213], v163 offset:35840
	ds_read_b128 v[214:217], v163 offset:36864
	ds_read_b128 v[218:221], v163 offset:37888
	ds_read_b128 v[222:225], v163 offset:38912
	ds_read_b128 v[226:229], v163 offset:39936
	global_load_lds_dwordx4 v[236:237], off
	v_lshl_add_u64 v[236:237], s[50:51], 0, v[136:137]
	s_mov_b32 m0, s56
	s_nop 0
	global_load_lds_dwordx4 v[236:237], off
	s_branch .Lal64_42
	s_nop 0
	s_nop 0
	s_nop 0
	s_nop 0
	s_nop 0
.Lal64_42:
	s_waitcnt vmcnt(8)
	s_waitcnt lgkmcnt(0)
	s_barrier
	s_setprio 1
	v_mfma_f32_16x16x32_bf16 v[78:81], v[156:159], v[196:199], v[78:81]
	v_mfma_f32_16x16x32_bf16 v[74:77], v[168:171], v[196:199], v[74:77]
	v_mfma_f32_16x16x32_bf16 v[70:73], v[156:159], v[206:209], v[70:73]
	v_mfma_f32_16x16x32_bf16 v[62:65], v[168:171], v[206:209], v[62:65]
	v_mfma_f32_16x16x32_bf16 v[58:61], v[156:159], v[214:217], v[58:61]
	v_mfma_f32_16x16x32_bf16 v[54:57], v[168:171], v[214:217], v[54:57]
	v_mfma_f32_16x16x32_bf16 v[46:49], v[156:159], v[222:225], v[46:49]
	v_mfma_f32_16x16x32_bf16 v[38:41], v[168:171], v[222:225], v[38:41]
	v_mfma_f32_16x16x32_bf16 v[78:81], v[164:167], v[200:203], v[78:81]
	v_mfma_f32_16x16x32_bf16 v[74:77], v[172:175], v[200:203], v[74:77]
	v_mfma_f32_16x16x32_bf16 v[70:73], v[164:167], v[210:213], v[70:73]
	v_mfma_f32_16x16x32_bf16 v[62:65], v[172:175], v[210:213], v[62:65]
	v_mfma_f32_16x16x32_bf16 v[58:61], v[164:167], v[218:221], v[58:61]
	v_mfma_f32_16x16x32_bf16 v[54:57], v[172:175], v[218:221], v[54:57]
	v_mfma_f32_16x16x32_bf16 v[46:49], v[164:167], v[226:229], v[46:49]
	v_mfma_f32_16x16x32_bf16 v[38:41], v[172:175], v[226:229], v[38:41]
	v_mfma_f32_16x16x32_bf16 v[50:53], v[176:179], v[196:199], v[50:53]
	v_mfma_f32_16x16x32_bf16 v[42:45], v[184:187], v[196:199], v[42:45]
	v_mfma_f32_16x16x32_bf16 v[34:37], v[176:179], v[206:209], v[34:37]
	v_mfma_f32_16x16x32_bf16 v[26:29], v[184:187], v[206:209], v[26:29]
	v_mfma_f32_16x16x32_bf16 v[18:21], v[176:179], v[214:217], v[18:21]
	v_mfma_f32_16x16x32_bf16 v[14:17], v[184:187], v[214:217], v[14:17]
	v_mfma_f32_16x16x32_bf16 v[10:13], v[176:179], v[222:225], v[10:13]
	v_mfma_f32_16x16x32_bf16 v[6:9], v[184:187], v[222:225], v[6:9]
	v_mfma_f32_16x16x32_bf16 v[50:53], v[180:183], v[200:203], v[50:53]
	v_mfma_f32_16x16x32_bf16 v[42:45], v[188:191], v[200:203], v[42:45]
	v_mfma_f32_16x16x32_bf16 v[34:37], v[180:183], v[210:213], v[34:37]
	v_mfma_f32_16x16x32_bf16 v[26:29], v[188:191], v[210:213], v[26:29]
	v_mfma_f32_16x16x32_bf16 v[18:21], v[180:183], v[218:221], v[18:21]
	v_mfma_f32_16x16x32_bf16 v[14:17], v[188:191], v[218:221], v[14:17]
	v_mfma_f32_16x16x32_bf16 v[10:13], v[180:183], v[226:229], v[10:13]
	v_mfma_f32_16x16x32_bf16 v[6:9], v[188:191], v[226:229], v[6:9]
	s_setprio 0
	s_barrier
	s_add_i32 s50, s77, s53
	v_lshl_add_u64 v[192:193], v[192:193], 0, s[14:15]
	s_mov_b32 m0, s50
	ds_read_b128 v[196:199], v163 offset:49152
	ds_read_b128 v[200:203], v163 offset:50176
	ds_read_b128 v[206:209], v163 offset:51200
	ds_read_b128 v[210:213], v163 offset:52224
	ds_read_b128 v[214:217], v163 offset:53248
	ds_read_b128 v[218:221], v163 offset:54272
	ds_read_b128 v[222:225], v163 offset:55296
	ds_read_b128 v[226:229], v163 offset:56320
	global_load_lds_dwordx4 v[192:193], off
	s_add_i32 m0, s50, 0x2000
	s_add_u32 s48, s48, 0x100080
	v_lshl_add_u64 v[192:193], v[230:231], 0, s[14:15]
	s_addc_u32 s49, s49, 0
	s_add_i32 s50, s78, s53
	global_load_lds_dwordx4 v[192:193], off
	v_lshl_add_u64 v[192:193], s[48:49], 0, v[134:135]
	s_mov_b32 m0, s50
	s_nop 0
	global_load_lds_dwordx4 v[192:193], off
	v_lshl_add_u64 v[192:193], s[48:49], 0, v[138:139]
	s_add_i32 m0, s50, 0x2000
	s_nop 0
	global_load_lds_dwordx4 v[192:193], off
	v_lshl_add_u64 v[192:193], v[232:233], 0, s[14:15]
	s_mov_b32 m0, s59
	s_nop 0
	global_load_lds_dwordx4 v[192:193], off
	v_lshl_add_u64 v[192:193], v[234:235], 0, s[14:15]
	s_mov_b32 m0, s60
	s_nop 0
	global_load_lds_dwordx4 v[192:193], off
	s_branch .Lal64_43
.Lal64_43:
	s_waitcnt vmcnt(8)
	s_waitcnt lgkmcnt(0)
	s_barrier
	s_setprio 1
	v_mfma_f32_16x16x32_bf16 v[126:129], v[156:159], v[196:199], v[126:129]
	v_mfma_f32_16x16x32_bf16 v[118:121], v[168:171], v[196:199], v[118:121]
	v_mfma_f32_16x16x32_bf16 v[110:113], v[156:159], v[206:209], v[110:113]
	v_mfma_f32_16x16x32_bf16 v[102:105], v[168:171], v[206:209], v[102:105]
	v_mfma_f32_16x16x32_bf16 v[94:97], v[156:159], v[214:217], v[94:97]
	v_mfma_f32_16x16x32_bf16 v[86:89], v[168:171], v[214:217], v[86:89]
	v_mfma_f32_16x16x32_bf16 v[66:69], v[156:159], v[222:225], v[66:69]
	v_mfma_f32_16x16x32_bf16 v[22:25], v[168:171], v[222:225], v[22:25]
	v_mfma_f32_16x16x32_bf16 v[126:129], v[164:167], v[200:203], v[126:129]
	v_mfma_f32_16x16x32_bf16 v[118:121], v[172:175], v[200:203], v[118:121]
	v_mfma_f32_16x16x32_bf16 v[110:113], v[164:167], v[210:213], v[110:113]
	v_mfma_f32_16x16x32_bf16 v[102:105], v[172:175], v[210:213], v[102:105]
	v_mfma_f32_16x16x32_bf16 v[94:97], v[164:167], v[218:221], v[94:97]
	v_mfma_f32_16x16x32_bf16 v[86:89], v[172:175], v[218:221], v[86:89]
	v_mfma_f32_16x16x32_bf16 v[66:69], v[164:167], v[226:229], v[66:69]
	v_mfma_f32_16x16x32_bf16 v[22:25], v[172:175], v[226:229], v[22:25]
	v_mfma_f32_16x16x32_bf16 v[122:125], v[176:179], v[196:199], v[122:125]
	v_mfma_f32_16x16x32_bf16 v[114:117], v[184:187], v[196:199], v[114:117]
	v_mfma_f32_16x16x32_bf16 v[106:109], v[176:179], v[206:209], v[106:109]
	v_mfma_f32_16x16x32_bf16 v[98:101], v[184:187], v[206:209], v[98:101]
	v_mfma_f32_16x16x32_bf16 v[90:93], v[176:179], v[214:217], v[90:93]
	v_mfma_f32_16x16x32_bf16 v[82:85], v[184:187], v[214:217], v[82:85]
	v_mfma_f32_16x16x32_bf16 v[30:33], v[176:179], v[222:225], v[30:33]
	v_mfma_f32_16x16x32_bf16 v[2:5], v[184:187], v[222:225], v[2:5]
	v_mfma_f32_16x16x32_bf16 v[122:125], v[180:183], v[200:203], v[122:125]
	v_mfma_f32_16x16x32_bf16 v[114:117], v[188:191], v[200:203], v[114:117]
	v_mfma_f32_16x16x32_bf16 v[106:109], v[180:183], v[210:213], v[106:109]
	v_mfma_f32_16x16x32_bf16 v[98:101], v[188:191], v[210:213], v[98:101]
	v_mfma_f32_16x16x32_bf16 v[90:93], v[180:183], v[218:221], v[90:93]
	v_mfma_f32_16x16x32_bf16 v[82:85], v[188:191], v[218:221], v[82:85]
	v_mfma_f32_16x16x32_bf16 v[30:33], v[180:183], v[226:229], v[30:33]
	v_mfma_f32_16x16x32_bf16 v[2:5], v[188:191], v[226:229], v[2:5]
	s_setprio 0
	s_barrier
	s_add_u32 s46, s46, 0x100
	s_addc_u32 s47, s47, 0
	s_add_u32 s74, s74, 0x100
	s_addc_u32 s75, s75, 0
	s_cmp_ge_i32 s76, s72
	s_mov_b32 s48, s76
	s_cbranch_scc0 .LBB0_1553
	s_and_b64 vcc, exec, s[16:17]
	s_cbranch_vccz .LBB0_1558
	s_barrier
	s_cmp_lt_i32 s52, 0
	s_mov_b64 s[46:47], -1
	s_cbranch_scc1 .LBB0_1559

.LBB0_1712:
	ds_read_b128 v[152:155], v160
	ds_read_b128 v[164:167], v160 offset:1024
	ds_read_b128 v[168:171], v160 offset:2048
	ds_read_b128 v[172:175], v160 offset:3072
	ds_read_b128 v[176:179], v161
	ds_read_b128 v[180:183], v161 offset:1024
	ds_read_b128 v[184:187], v161 offset:2048
	ds_read_b128 v[188:191], v161 offset:3072
	s_add_i32 s82, s48, 2
	s_add_u32 s49, s52, 0xffd50080
	s_addc_u32 s54, s53, -1
	s_cmp_eq_u32 s47, s48
	s_cselect_b32 s48, s50, s80
	s_cselect_b32 s55, s9, s54
	s_cselect_b32 s54, s8, s49
	s_cselect_b32 s49, s51, s81
	v_lshl_add_u64 v[156:157], s[52:53], 0, v[140:141]
	s_add_i32 m0, s57, 0xc000
	ds_read_b128 v[196:199], v162
	ds_read_b128 v[200:203], v162 offset:1024
	ds_read_b128 v[206:209], v162 offset:2048
	ds_read_b128 v[210:213], v162 offset:3072
	ds_read_b128 v[214:217], v162 offset:4096
	ds_read_b128 v[218:221], v162 offset:5120
	ds_read_b128 v[222:225], v162 offset:6144
	ds_read_b128 v[226:229], v162 offset:7168
	global_load_lds_dwordx4 v[156:157], off
	v_lshl_add_u64 v[156:157], s[52:53], 0, v[142:143]
	s_add_i32 m0, s57, 0xe000
	s_nop 0
	global_load_lds_dwordx4 v[156:157], off
	s_branch .Lal64_44
	s_nop 0
.Lal64_44:
	s_waitcnt vmcnt(8)
	s_waitcnt lgkmcnt(0)
	s_barrier
	s_setprio 1
	v_mfma_f32_16x16x32_bf16 v[126:129], v[152:155], v[196:199], v[126:129]
	v_mfma_f32_16x16x32_bf16 v[122:125], v[168:171], v[196:199], v[122:125]
	v_mfma_f32_16x16x32_bf16 v[110:113], v[152:155], v[206:209], v[110:113]
	v_mfma_f32_16x16x32_bf16 v[106:109], v[168:171], v[206:209], v[106:109]
	v_mfma_f32_16x16x32_bf16 v[94:97], v[152:155], v[214:217], v[94:97]
	v_mfma_f32_16x16x32_bf16 v[90:93], v[168:171], v[214:217], v[90:93]
	v_mfma_f32_16x16x32_bf16 v[78:81], v[152:155], v[222:225], v[78:81]
	v_mfma_f32_16x16x32_bf16 v[74:77], v[168:171], v[222:225], v[74:77]
	v_mfma_f32_16x16x32_bf16 v[126:129], v[164:167], v[200:203], v[126:129]
	v_mfma_f32_16x16x32_bf16 v[122:125], v[172:175], v[200:203], v[122:125]
	v_mfma_f32_16x16x32_bf16 v[110:113], v[164:167], v[210:213], v[110:113]
	v_mfma_f32_16x16x32_bf16 v[106:109], v[172:175], v[210:213], v[106:109]
	v_mfma_f32_16x16x32_bf16 v[94:97], v[164:167], v[218:221], v[94:97]
	v_mfma_f32_16x16x32_bf16 v[90:93], v[172:175], v[218:221], v[90:93]
	v_mfma_f32_16x16x32_bf16 v[78:81], v[164:167], v[226:229], v[78:81]
	v_mfma_f32_16x16x32_bf16 v[74:77], v[172:175], v[226:229], v[74:77]
	v_mfma_f32_16x16x32_bf16 v[118:121], v[176:179], v[196:199], v[118:121]
	v_mfma_f32_16x16x32_bf16 v[114:117], v[184:187], v[196:199], v[114:117]
	v_mfma_f32_16x16x32_bf16 v[102:105], v[176:179], v[206:209], v[102:105]
	v_mfma_f32_16x16x32_bf16 v[98:101], v[184:187], v[206:209], v[98:101]
	v_mfma_f32_16x16x32_bf16 v[86:89], v[176:179], v[214:217], v[86:89]
	v_mfma_f32_16x16x32_bf16 v[82:85], v[184:187], v[214:217], v[82:85]
	v_mfma_f32_16x16x32_bf16 v[70:73], v[176:179], v[222:225], v[70:73]
	v_mfma_f32_16x16x32_bf16 v[66:69], v[184:187], v[222:225], v[66:69]
	v_mfma_f32_16x16x32_bf16 v[118:121], v[180:183], v[200:203], v[118:121]
	v_mfma_f32_16x16x32_bf16 v[114:117], v[188:191], v[200:203], v[114:117]
	v_mfma_f32_16x16x32_bf16 v[102:105], v[180:183], v[210:213], v[102:105]
	v_mfma_f32_16x16x32_bf16 v[98:101], v[188:191], v[210:213], v[98:101]
	v_mfma_f32_16x16x32_bf16 v[86:89], v[180:183], v[218:221], v[86:89]
	v_mfma_f32_16x16x32_bf16 v[82:85], v[188:191], v[218:221], v[82:85]
	v_mfma_f32_16x16x32_bf16 v[70:73], v[180:183], v[226:229], v[70:73]
	v_mfma_f32_16x16x32_bf16 v[66:69], v[188:191], v[226:229], v[66:69]
	s_setprio 0
	s_barrier
	s_add_i32 s83, s67, s56
	v_lshl_add_u64 v[156:157], s[48:49], 0, v[134:135]
	s_mov_b32 m0, s83
	ds_read_b128 v[196:199], v162 offset:16384
	ds_read_b128 v[200:203], v162 offset:17408
	ds_read_b128 v[206:209], v162 offset:18432
	ds_read_b128 v[210:213], v162 offset:19456
	ds_read_b128 v[214:217], v162 offset:20480
	ds_read_b128 v[218:221], v162 offset:21504
	ds_read_b128 v[222:225], v162 offset:22528
	ds_read_b128 v[226:229], v162 offset:23552
	global_load_lds_dwordx4 v[156:157], off
	s_add_i32 m0, s83, 0x2000
	s_add_u32 s84, s48, 0x2b0000
	v_lshl_add_u64 v[192:193], s[48:49], 0, v[138:139]
	s_addc_u32 s85, s49, 0
	s_add_i32 s83, s68, s56
	global_load_lds_dwordx4 v[192:193], off
	v_lshl_add_u64 v[230:231], s[84:85], 0, v[134:135]
	s_mov_b32 m0, s83
	v_lshl_add_u64 v[232:233], s[54:55], 0, v[136:137]
	global_load_lds_dwordx4 v[230:231], off
	v_lshl_add_u64 v[230:231], s[84:85], 0, v[138:139]
	s_add_i32 m0, s83, 0x2000
	s_nop 0
	global_load_lds_dwordx4 v[230:231], off
	v_lshl_add_u64 v[230:231], s[54:55], 0, v[132:133]
	s_mov_b32 m0, s57
	s_nop 0
	global_load_lds_dwordx4 v[230:231], off
	s_mov_b32 m0, s58
	s_nop 0
	global_load_lds_dwordx4 v[232:233], off
	s_branch .Lal64_45
	s_nop 0
.Lal64_45:
	s_waitcnt vmcnt(8)
	s_waitcnt lgkmcnt(0)
	s_barrier
	s_setprio 1
	v_mfma_f32_16x16x32_bf16 v[62:65], v[152:155], v[196:199], v[62:65]
	v_mfma_f32_16x16x32_bf16 v[58:61], v[168:171], v[196:199], v[58:61]
	v_mfma_f32_16x16x32_bf16 v[46:49], v[152:155], v[206:209], v[46:49]
	v_mfma_f32_16x16x32_bf16 v[42:45], v[168:171], v[206:209], v[42:45]
	v_mfma_f32_16x16x32_bf16 v[30:33], v[152:155], v[214:217], v[30:33]
	v_mfma_f32_16x16x32_bf16 v[26:29], v[168:171], v[214:217], v[26:29]
	v_mfma_f32_16x16x32_bf16 v[14:17], v[152:155], v[222:225], v[14:17]
	v_mfma_f32_16x16x32_bf16 v[10:13], v[168:171], v[222:225], v[10:13]
	v_mfma_f32_16x16x32_bf16 v[62:65], v[164:167], v[200:203], v[62:65]
	v_mfma_f32_16x16x32_bf16 v[58:61], v[172:175], v[200:203], v[58:61]
	v_mfma_f32_16x16x32_bf16 v[46:49], v[164:167], v[210:213], v[46:49]
	v_mfma_f32_16x16x32_bf16 v[42:45], v[172:175], v[210:213], v[42:45]
	v_mfma_f32_16x16x32_bf16 v[30:33], v[164:167], v[218:221], v[30:33]
	v_mfma_f32_16x16x32_bf16 v[26:29], v[172:175], v[218:221], v[26:29]
	v_mfma_f32_16x16x32_bf16 v[14:17], v[164:167], v[226:229], v[14:17]
	v_mfma_f32_16x16x32_bf16 v[10:13], v[172:175], v[226:229], v[10:13]
	v_mfma_f32_16x16x32_bf16 v[54:57], v[176:179], v[196:199], v[54:57]
	v_mfma_f32_16x16x32_bf16 v[50:53], v[184:187], v[196:199], v[50:53]
	v_mfma_f32_16x16x32_bf16 v[38:41], v[176:179], v[206:209], v[38:41]
	v_mfma_f32_16x16x32_bf16 v[34:37], v[184:187], v[206:209], v[34:37]
	v_mfma_f32_16x16x32_bf16 v[22:25], v[176:179], v[214:217], v[22:25]
	v_mfma_f32_16x16x32_bf16 v[18:21], v[184:187], v[214:217], v[18:21]
	v_mfma_f32_16x16x32_bf16 v[6:9], v[176:179], v[222:225], v[6:9]
	v_mfma_f32_16x16x32_bf16 v[2:5], v[184:187], v[222:225], v[2:5]
	v_mfma_f32_16x16x32_bf16 v[54:57], v[180:183], v[200:203], v[54:57]
	v_mfma_f32_16x16x32_bf16 v[50:53], v[188:191], v[200:203], v[50:53]
	v_mfma_f32_16x16x32_bf16 v[38:41], v[180:183], v[210:213], v[38:41]
	v_mfma_f32_16x16x32_bf16 v[34:37], v[188:191], v[210:213], v[34:37]
	v_mfma_f32_16x16x32_bf16 v[22:25], v[180:183], v[218:221], v[22:25]
	v_mfma_f32_16x16x32_bf16 v[18:21], v[188:191], v[218:221], v[18:21]
	v_mfma_f32_16x16x32_bf16 v[6:9], v[180:183], v[226:229], v[6:9]
	v_mfma_f32_16x16x32_bf16 v[2:5], v[188:191], v[226:229], v[2:5]
	s_setprio 0
	s_barrier
	s_add_i32 s83, 0, 0x18000
	v_add_u32_e32 v163, s83, v158
	s_add_i32 s84, 0, 0x1c000
	ds_read_b128 v[152:155], v163
	ds_read_b128 v[164:167], v163 offset:1024
	ds_read_b128 v[168:171], v163 offset:2048
	ds_read_b128 v[172:175], v163 offset:3072
	v_add_u32_e32 v163, s84, v158
	ds_read_b128 v[176:179], v163
	ds_read_b128 v[180:183], v163 offset:1024
	ds_read_b128 v[184:187], v163 offset:2048
	ds_read_b128 v[188:191], v163 offset:3072
	s_add_u32 s54, s54, 0x2b0000
	s_addc_u32 s55, s55, 0
	s_mov_b32 m0, s59
	v_lshl_add_u64 v[234:235], s[54:55], 0, v[132:133]
	ds_read_b128 v[196:199], v162 offset:32768
	ds_read_b128 v[200:203], v162 offset:33792
	ds_read_b128 v[206:209], v162 offset:34816
	ds_read_b128 v[210:213], v162 offset:35840
	ds_read_b128 v[214:217], v162 offset:36864
	ds_read_b128 v[218:221], v162 offset:37888
	ds_read_b128 v[222:225], v162 offset:38912
	ds_read_b128 v[226:229], v162 offset:39936
	global_load_lds_dwordx4 v[234:235], off
	v_lshl_add_u64 v[234:235], s[54:55], 0, v[136:137]
	s_mov_b32 m0, s60
	s_nop 0
	global_load_lds_dwordx4 v[234:235], off
	s_branch .Lal64_46
	s_nop 0
	s_nop 0
	s_nop 0
	s_nop 0
	s_nop 0
.Lal64_46:
	s_waitcnt vmcnt(8)
	s_waitcnt lgkmcnt(0)
	s_barrier
	s_setprio 1
	v_mfma_f32_16x16x32_bf16 v[126:129], v[152:155], v[196:199], v[126:129]
	v_mfma_f32_16x16x32_bf16 v[122:125], v[168:171], v[196:199], v[122:125]
	v_mfma_f32_16x16x32_bf16 v[110:113], v[152:155], v[206:209], v[110:113]
	v_mfma_f32_16x16x32_bf16 v[106:109], v[168:171], v[206:209], v[106:109]
	v_mfma_f32_16x16x32_bf16 v[94:97], v[152:155], v[214:217], v[94:97]
	v_mfma_f32_16x16x32_bf16 v[90:93], v[168:171], v[214:217], v[90:93]
	v_mfma_f32_16x16x32_bf16 v[78:81], v[152:155], v[222:225], v[78:81]
	v_mfma_f32_16x16x32_bf16 v[74:77], v[168:171], v[222:225], v[74:77]
	v_mfma_f32_16x16x32_bf16 v[126:129], v[164:167], v[200:203], v[126:129]
	v_mfma_f32_16x16x32_bf16 v[122:125], v[172:175], v[200:203], v[122:125]
	v_mfma_f32_16x16x32_bf16 v[110:113], v[164:167], v[210:213], v[110:113]
	v_mfma_f32_16x16x32_bf16 v[106:109], v[172:175], v[210:213], v[106:109]
	v_mfma_f32_16x16x32_bf16 v[94:97], v[164:167], v[218:221], v[94:97]
	v_mfma_f32_16x16x32_bf16 v[90:93], v[172:175], v[218:221], v[90:93]
	v_mfma_f32_16x16x32_bf16 v[78:81], v[164:167], v[226:229], v[78:81]
	v_mfma_f32_16x16x32_bf16 v[74:77], v[172:175], v[226:229], v[74:77]
	v_mfma_f32_16x16x32_bf16 v[118:121], v[176:179], v[196:199], v[118:121]
	v_mfma_f32_16x16x32_bf16 v[114:117], v[184:187], v[196:199], v[114:117]
	v_mfma_f32_16x16x32_bf16 v[102:105], v[176:179], v[206:209], v[102:105]
	v_mfma_f32_16x16x32_bf16 v[98:101], v[184:187], v[206:209], v[98:101]
	v_mfma_f32_16x16x32_bf16 v[86:89], v[176:179], v[214:217], v[86:89]
	v_mfma_f32_16x16x32_bf16 v[82:85], v[184:187], v[214:217], v[82:85]
	v_mfma_f32_16x16x32_bf16 v[70:73], v[176:179], v[222:225], v[70:73]
	v_mfma_f32_16x16x32_bf16 v[66:69], v[184:187], v[222:225], v[66:69]
	v_mfma_f32_16x16x32_bf16 v[118:121], v[180:183], v[200:203], v[118:121]
	v_mfma_f32_16x16x32_bf16 v[114:117], v[188:191], v[200:203], v[114:117]
	v_mfma_f32_16x16x32_bf16 v[102:105], v[180:183], v[210:213], v[102:105]
	v_mfma_f32_16x16x32_bf16 v[98:101], v[188:191], v[210:213], v[98:101]
	v_mfma_f32_16x16x32_bf16 v[86:89], v[180:183], v[218:221], v[86:89]
	v_mfma_f32_16x16x32_bf16 v[82:85], v[188:191], v[218:221], v[82:85]
	v_mfma_f32_16x16x32_bf16 v[70:73], v[180:183], v[226:229], v[70:73]
	v_mfma_f32_16x16x32_bf16 v[66:69], v[188:191], v[226:229], v[66:69]
	s_setprio 0
	s_barrier
	s_add_i32 s54, s83, s56
	v_lshl_add_u64 v[156:157], v[156:157], 0, s[18:19]
	s_mov_b32 m0, s54
	ds_read_b128 v[196:199], v162 offset:49152
	ds_read_b128 v[200:203], v162 offset:50176
	ds_read_b128 v[206:209], v162 offset:51200
	ds_read_b128 v[210:213], v162 offset:52224
	ds_read_b128 v[214:217], v162 offset:53248
	ds_read_b128 v[218:221], v162 offset:54272
	ds_read_b128 v[222:225], v162 offset:55296
	ds_read_b128 v[226:229], v162 offset:56320
	global_load_lds_dwordx4 v[156:157], off
	s_add_i32 m0, s54, 0x2000
	s_add_u32 s48, s48, 0x2b0080
	v_lshl_add_u64 v[156:157], v[192:193], 0, s[18:19]
	s_addc_u32 s49, s49, 0
	s_add_i32 s54, s84, s56
	global_load_lds_dwordx4 v[156:157], off
	v_lshl_add_u64 v[156:157], s[48:49], 0, v[134:135]
	s_mov_b32 m0, s54
	s_nop 0
	global_load_lds_dwordx4 v[156:157], off
	v_lshl_add_u64 v[156:157], s[48:49], 0, v[138:139]
	s_add_i32 m0, s54, 0x2000
	s_nop 0
	global_load_lds_dwordx4 v[156:157], off
	v_lshl_add_u64 v[156:157], v[230:231], 0, s[18:19]
	s_mov_b32 m0, s64
	s_nop 0
	global_load_lds_dwordx4 v[156:157], off
	v_lshl_add_u64 v[156:157], v[232:233], 0, s[18:19]
	s_mov_b32 m0, s65
	s_nop 0
	global_load_lds_dwordx4 v[156:157], off
	s_branch .Lal64_47
.Lal64_47:
	s_waitcnt vmcnt(8)
	s_waitcnt lgkmcnt(0)
	s_barrier
	s_setprio 1
	v_mfma_f32_16x16x32_bf16 v[62:65], v[152:155], v[196:199], v[62:65]
	v_mfma_f32_16x16x32_bf16 v[58:61], v[168:171], v[196:199], v[58:61]
	v_mfma_f32_16x16x32_bf16 v[46:49], v[152:155], v[206:209], v[46:49]
	v_mfma_f32_16x16x32_bf16 v[42:45], v[168:171], v[206:209], v[42:45]
	v_mfma_f32_16x16x32_bf16 v[30:33], v[152:155], v[214:217], v[30:33]
	v_mfma_f32_16x16x32_bf16 v[26:29], v[168:171], v[214:217], v[26:29]
	v_mfma_f32_16x16x32_bf16 v[14:17], v[152:155], v[222:225], v[14:17]
	v_mfma_f32_16x16x32_bf16 v[10:13], v[168:171], v[222:225], v[10:13]
	v_mfma_f32_16x16x32_bf16 v[62:65], v[164:167], v[200:203], v[62:65]
	v_mfma_f32_16x16x32_bf16 v[58:61], v[172:175], v[200:203], v[58:61]
	v_mfma_f32_16x16x32_bf16 v[46:49], v[164:167], v[210:213], v[46:49]
	v_mfma_f32_16x16x32_bf16 v[42:45], v[172:175], v[210:213], v[42:45]
	v_mfma_f32_16x16x32_bf16 v[30:33], v[164:167], v[218:221], v[30:33]
	v_mfma_f32_16x16x32_bf16 v[26:29], v[172:175], v[218:221], v[26:29]
	v_mfma_f32_16x16x32_bf16 v[14:17], v[164:167], v[226:229], v[14:17]
	v_mfma_f32_16x16x32_bf16 v[10:13], v[172:175], v[226:229], v[10:13]
	v_mfma_f32_16x16x32_bf16 v[54:57], v[176:179], v[196:199], v[54:57]
	v_mfma_f32_16x16x32_bf16 v[50:53], v[184:187], v[196:199], v[50:53]
	v_mfma_f32_16x16x32_bf16 v[38:41], v[176:179], v[206:209], v[38:41]
	v_mfma_f32_16x16x32_bf16 v[34:37], v[184:187], v[206:209], v[34:37]
	v_mfma_f32_16x16x32_bf16 v[22:25], v[176:179], v[214:217], v[22:25]
	v_mfma_f32_16x16x32_bf16 v[18:21], v[184:187], v[214:217], v[18:21]
	v_mfma_f32_16x16x32_bf16 v[6:9], v[176:179], v[222:225], v[6:9]
	v_mfma_f32_16x16x32_bf16 v[2:5], v[184:187], v[222:225], v[2:5]
	v_mfma_f32_16x16x32_bf16 v[54:57], v[180:183], v[200:203], v[54:57]
	v_mfma_f32_16x16x32_bf16 v[50:53], v[188:191], v[200:203], v[50:53]
	v_mfma_f32_16x16x32_bf16 v[38:41], v[180:183], v[210:213], v[38:41]
	v_mfma_f32_16x16x32_bf16 v[34:37], v[188:191], v[210:213], v[34:37]
	v_mfma_f32_16x16x32_bf16 v[22:25], v[180:183], v[218:221], v[22:25]
	v_mfma_f32_16x16x32_bf16 v[18:21], v[188:191], v[218:221], v[18:21]
	v_mfma_f32_16x16x32_bf16 v[6:9], v[180:183], v[226:229], v[6:9]
	v_mfma_f32_16x16x32_bf16 v[2:5], v[188:191], v[226:229], v[2:5]
	s_setprio 0
	s_barrier
	s_add_u32 s52, s52, 0x100
	s_addc_u32 s53, s53, 0
	s_add_u32 s80, s80, 0x100
	s_addc_u32 s81, s81, 0
	s_cmp_ge_i32 s82, s78
	s_mov_b32 s48, s82
	s_cbranch_scc0 .LBB0_1712
	s_and_b64 vcc, exec, s[20:21]
	s_cbranch_vccz .LBB0_1715
	s_barrier

.LBB0_1869:
	ds_read_b128 v[162:165], v168
	s_waitcnt vmcnt(0)
	ds_read_b128 v[172:175], v168 offset:1024
	ds_read_b128 v[176:179], v168 offset:2048
	ds_read_b128 v[180:183], v168 offset:3072
	ds_read_b128 v[184:187], v169
	ds_read_b128 v[188:191], v169 offset:1024
	ds_read_b128 v[196:199], v169 offset:2048
	ds_read_b128 v[200:203], v169 offset:3072
	s_add_i32 s55, s42, 2
	s_add_u32 s43, s8, 0xfff00080
	s_addc_u32 s46, s9, -1
	s_cmp_eq_u32 s48, s42
	s_cselect_b32 s42, s41, s49
	s_cselect_b32 s47, s31, s46
	s_cselect_b32 s46, s33, s43
	s_cselect_b32 s43, s35, s53
	v_lshl_add_u64 v[166:167], s[8:9], 0, v[150:151]
	s_add_i32 m0, s62, 0xc000
	ds_read_b128 v[206:209], v170
	ds_read_b128 v[210:213], v170 offset:1024
	ds_read_b128 v[214:217], v170 offset:2048
	ds_read_b128 v[218:221], v170 offset:3072
	ds_read_b128 v[222:225], v170 offset:4096
	ds_read_b128 v[226:229], v170 offset:5120
	ds_read_b128 v[230:233], v170 offset:6144
	ds_read_b128 v[234:237], v170 offset:7168
	global_load_lds_dwordx4 v[166:167], off
	v_lshl_add_u64 v[166:167], s[8:9], 0, v[152:153]
	s_add_i32 m0, s62, 0xe000
	s_nop 0
	global_load_lds_dwordx4 v[166:167], off
	s_branch .Lal64_48
	s_nop 0
	s_nop 0
	s_nop 0
	s_nop 0
	s_nop 0
	s_nop 0
	s_nop 0
	s_nop 0
	s_nop 0
	s_nop 0
	s_nop 0
	s_nop 0
	s_nop 0
.Lal64_48:
	s_waitcnt vmcnt(8)
	s_waitcnt lgkmcnt(0)
	s_barrier
	s_setprio 1
	v_mfma_f32_16x16x32_bf16 v[66:69], v[162:165], v[206:209], v[66:69]
	v_mfma_f32_16x16x32_bf16 v[62:65], v[176:179], v[206:209], v[62:65]
	v_mfma_f32_16x16x32_bf16 v[58:61], v[162:165], v[214:217], v[58:61]
	v_mfma_f32_16x16x32_bf16 v[54:57], v[176:179], v[214:217], v[54:57]
	v_mfma_f32_16x16x32_bf16 v[50:53], v[162:165], v[222:225], v[50:53]
	v_mfma_f32_16x16x32_bf16 v[46:49], v[176:179], v[222:225], v[46:49]
	v_mfma_f32_16x16x32_bf16 v[38:41], v[162:165], v[230:233], v[38:41]
	v_mfma_f32_16x16x32_bf16 v[30:33], v[176:179], v[230:233], v[30:33]
	v_mfma_f32_16x16x32_bf16 v[66:69], v[172:175], v[210:213], v[66:69]
	v_mfma_f32_16x16x32_bf16 v[62:65], v[180:183], v[210:213], v[62:65]
	v_mfma_f32_16x16x32_bf16 v[58:61], v[172:175], v[218:221], v[58:61]
	v_mfma_f32_16x16x32_bf16 v[54:57], v[180:183], v[218:221], v[54:57]
	v_mfma_f32_16x16x32_bf16 v[50:53], v[172:175], v[226:229], v[50:53]
	v_mfma_f32_16x16x32_bf16 v[46:49], v[180:183], v[226:229], v[46:49]
	v_mfma_f32_16x16x32_bf16 v[38:41], v[172:175], v[234:237], v[38:41]
	v_mfma_f32_16x16x32_bf16 v[30:33], v[180:183], v[234:237], v[30:33]
	v_mfma_f32_16x16x32_bf16 v[42:45], v[184:187], v[206:209], v[42:45]
	v_mfma_f32_16x16x32_bf16 v[34:37], v[196:199], v[206:209], v[34:37]
	v_mfma_f32_16x16x32_bf16 v[26:29], v[184:187], v[214:217], v[26:29]
	v_mfma_f32_16x16x32_bf16 v[22:25], v[196:199], v[214:217], v[22:25]
	v_mfma_f32_16x16x32_bf16 v[18:21], v[184:187], v[222:225], v[18:21]
	v_mfma_f32_16x16x32_bf16 v[14:17], v[196:199], v[222:225], v[14:17]
	v_mfma_f32_16x16x32_bf16 v[10:13], v[184:187], v[230:233], v[10:13]
	v_mfma_f32_16x16x32_bf16 v[6:9], v[196:199], v[230:233], v[6:9]
	v_mfma_f32_16x16x32_bf16 v[42:45], v[188:191], v[210:213], v[42:45]
	v_mfma_f32_16x16x32_bf16 v[34:37], v[200:203], v[210:213], v[34:37]
	v_mfma_f32_16x16x32_bf16 v[26:29], v[188:191], v[218:221], v[26:29]
	v_mfma_f32_16x16x32_bf16 v[22:25], v[200:203], v[218:221], v[22:25]
	v_mfma_f32_16x16x32_bf16 v[18:21], v[188:191], v[226:229], v[18:21]
	v_mfma_f32_16x16x32_bf16 v[14:17], v[200:203], v[226:229], v[14:17]
	v_mfma_f32_16x16x32_bf16 v[10:13], v[188:191], v[234:237], v[10:13]
	v_mfma_f32_16x16x32_bf16 v[6:9], v[200:203], v[234:237], v[6:9]
	s_setprio 0
	s_barrier
	s_add_i32 s80, s72, s61
	v_lshl_add_u64 v[166:167], s[42:43], 0, v[134:135]
	s_mov_b32 m0, s80
	ds_read_b128 v[206:209], v170 offset:16384
	ds_read_b128 v[210:213], v170 offset:17408
	ds_read_b128 v[214:217], v170 offset:18432
	ds_read_b128 v[218:221], v170 offset:19456
	ds_read_b128 v[222:225], v170 offset:20480
	ds_read_b128 v[226:229], v170 offset:21504
	ds_read_b128 v[230:233], v170 offset:22528
	ds_read_b128 v[234:237], v170 offset:23552
	global_load_lds_dwordx4 v[166:167], off
	s_add_i32 m0, s80, 0x2000
	s_add_u32 s80, s42, 0x100000
	v_lshl_add_u64 v[192:193], s[42:43], 0, v[138:139]
	s_addc_u32 s81, s43, 0
	s_add_i32 s82, s73, s61
	global_load_lds_dwordx4 v[192:193], off
	v_lshl_add_u64 v[238:239], s[80:81], 0, v[134:135]
	s_mov_b32 m0, s82
	v_lshl_add_u64 v[240:241], s[46:47], 0, v[136:137]
	global_load_lds_dwordx4 v[238:239], off
	v_lshl_add_u64 v[238:239], s[80:81], 0, v[138:139]
	s_add_i32 m0, s82, 0x2000
	s_nop 0
	global_load_lds_dwordx4 v[238:239], off
	v_lshl_add_u64 v[238:239], s[46:47], 0, v[132:133]
	s_mov_b32 m0, s62
	s_nop 0
	global_load_lds_dwordx4 v[238:239], off
	s_mov_b32 m0, s63
	s_nop 0
	global_load_lds_dwordx4 v[240:241], off
	s_branch .Lal64_49
	s_nop 0
.Lal64_49:
	s_waitcnt vmcnt(8)
	s_waitcnt lgkmcnt(0)
	s_barrier
	s_setprio 1
	v_mfma_f32_16x16x32_bf16 v[126:129], v[162:165], v[206:209], v[126:129]
	v_mfma_f32_16x16x32_bf16 v[122:125], v[176:179], v[206:209], v[122:125]
	v_mfma_f32_16x16x32_bf16 v[110:113], v[162:165], v[214:217], v[110:113]
	v_mfma_f32_16x16x32_bf16 v[106:109], v[176:179], v[214:217], v[106:109]
	v_mfma_f32_16x16x32_bf16 v[94:97], v[162:165], v[222:225], v[94:97]
	v_mfma_f32_16x16x32_bf16 v[90:93], v[176:179], v[222:225], v[90:93]
	v_mfma_f32_16x16x32_bf16 v[78:81], v[162:165], v[230:233], v[78:81]
	v_mfma_f32_16x16x32_bf16 v[74:77], v[176:179], v[230:233], v[74:77]
	v_mfma_f32_16x16x32_bf16 v[126:129], v[172:175], v[210:213], v[126:129]
	v_mfma_f32_16x16x32_bf16 v[122:125], v[180:183], v[210:213], v[122:125]
	v_mfma_f32_16x16x32_bf16 v[110:113], v[172:175], v[218:221], v[110:113]
	v_mfma_f32_16x16x32_bf16 v[106:109], v[180:183], v[218:221], v[106:109]
	v_mfma_f32_16x16x32_bf16 v[94:97], v[172:175], v[226:229], v[94:97]
	v_mfma_f32_16x16x32_bf16 v[90:93], v[180:183], v[226:229], v[90:93]
	v_mfma_f32_16x16x32_bf16 v[78:81], v[172:175], v[234:237], v[78:81]
	v_mfma_f32_16x16x32_bf16 v[74:77], v[180:183], v[234:237], v[74:77]
	v_mfma_f32_16x16x32_bf16 v[118:121], v[184:187], v[206:209], v[118:121]
	v_mfma_f32_16x16x32_bf16 v[114:117], v[196:199], v[206:209], v[114:117]
	v_mfma_f32_16x16x32_bf16 v[102:105], v[184:187], v[214:217], v[102:105]
	v_mfma_f32_16x16x32_bf16 v[98:101], v[196:199], v[214:217], v[98:101]
	v_mfma_f32_16x16x32_bf16 v[86:89], v[184:187], v[222:225], v[86:89]
	v_mfma_f32_16x16x32_bf16 v[82:85], v[196:199], v[222:225], v[82:85]
	v_mfma_f32_16x16x32_bf16 v[70:73], v[184:187], v[230:233], v[70:73]
	v_mfma_f32_16x16x32_bf16 v[2:5], v[196:199], v[230:233], v[2:5]
	v_mfma_f32_16x16x32_bf16 v[118:121], v[188:191], v[210:213], v[118:121]
	v_mfma_f32_16x16x32_bf16 v[114:117], v[200:203], v[210:213], v[114:117]
	v_mfma_f32_16x16x32_bf16 v[102:105], v[188:191], v[218:221], v[102:105]
	v_mfma_f32_16x16x32_bf16 v[98:101], v[200:203], v[218:221], v[98:101]
	v_mfma_f32_16x16x32_bf16 v[86:89], v[188:191], v[226:229], v[86:89]
	v_mfma_f32_16x16x32_bf16 v[82:85], v[200:203], v[226:229], v[82:85]
	v_mfma_f32_16x16x32_bf16 v[70:73], v[188:191], v[234:237], v[70:73]
	v_mfma_f32_16x16x32_bf16 v[2:5], v[200:203], v[234:237], v[2:5]
	s_setprio 0
	s_barrier
	s_add_i32 s80, 0, 0x18000
	s_add_i32 s81, 0, 0x1c000
	v_add_u32_e32 v180, s80, v131
	v_add_u32_e32 v200, s81, v131
	ds_read_b128 v[162:165], v180
	ds_read_b128 v[172:175], v180 offset:1024
	ds_read_b128 v[176:179], v180 offset:2048
	ds_read_b128 v[180:183], v180 offset:3072
	ds_read_b128 v[184:187], v200
	ds_read_b128 v[188:191], v200 offset:1024
	ds_read_b128 v[196:199], v200 offset:2048
	ds_read_b128 v[200:203], v200 offset:3072
	s_add_u32 s46, s46, 0x100000
	s_addc_u32 s47, s47, 0
	s_mov_b32 m0, s64
	v_lshl_add_u64 v[242:243], s[46:47], 0, v[132:133]
	ds_read_b128 v[206:209], v170 offset:32768
	ds_read_b128 v[210:213], v170 offset:33792
	ds_read_b128 v[214:217], v170 offset:34816
	ds_read_b128 v[218:221], v170 offset:35840
	ds_read_b128 v[222:225], v170 offset:36864
	ds_read_b128 v[226:229], v170 offset:37888
	ds_read_b128 v[230:233], v170 offset:38912
	ds_read_b128 v[234:237], v170 offset:39936
	global_load_lds_dwordx4 v[242:243], off
	v_lshl_add_u64 v[242:243], s[46:47], 0, v[136:137]
	s_mov_b32 m0, s65
	s_nop 0
	global_load_lds_dwordx4 v[242:243], off
	s_branch .Lal64_50
	s_nop 0
	s_nop 0
	s_nop 0
	s_nop 0
	s_nop 0
.Lal64_50:
	s_waitcnt vmcnt(8)
	s_waitcnt lgkmcnt(0)
	s_barrier
	s_setprio 1
	v_mfma_f32_16x16x32_bf16 v[66:69], v[162:165], v[206:209], v[66:69]
	v_mfma_f32_16x16x32_bf16 v[62:65], v[176:179], v[206:209], v[62:65]
	v_mfma_f32_16x16x32_bf16 v[58:61], v[162:165], v[214:217], v[58:61]
	v_mfma_f32_16x16x32_bf16 v[54:57], v[176:179], v[214:217], v[54:57]
	v_mfma_f32_16x16x32_bf16 v[50:53], v[162:165], v[222:225], v[50:53]
	v_mfma_f32_16x16x32_bf16 v[46:49], v[176:179], v[222:225], v[46:49]
	v_mfma_f32_16x16x32_bf16 v[38:41], v[162:165], v[230:233], v[38:41]
	v_mfma_f32_16x16x32_bf16 v[30:33], v[176:179], v[230:233], v[30:33]
	v_mfma_f32_16x16x32_bf16 v[66:69], v[172:175], v[210:213], v[66:69]
	v_mfma_f32_16x16x32_bf16 v[62:65], v[180:183], v[210:213], v[62:65]
	v_mfma_f32_16x16x32_bf16 v[58:61], v[172:175], v[218:221], v[58:61]
	v_mfma_f32_16x16x32_bf16 v[54:57], v[180:183], v[218:221], v[54:57]
	v_mfma_f32_16x16x32_bf16 v[50:53], v[172:175], v[226:229], v[50:53]
	v_mfma_f32_16x16x32_bf16 v[46:49], v[180:183], v[226:229], v[46:49]
	v_mfma_f32_16x16x32_bf16 v[38:41], v[172:175], v[234:237], v[38:41]
	v_mfma_f32_16x16x32_bf16 v[30:33], v[180:183], v[234:237], v[30:33]
	v_mfma_f32_16x16x32_bf16 v[42:45], v[184:187], v[206:209], v[42:45]
	v_mfma_f32_16x16x32_bf16 v[34:37], v[196:199], v[206:209], v[34:37]
	v_mfma_f32_16x16x32_bf16 v[26:29], v[184:187], v[214:217], v[26:29]
	v_mfma_f32_16x16x32_bf16 v[22:25], v[196:199], v[214:217], v[22:25]
	v_mfma_f32_16x16x32_bf16 v[18:21], v[184:187], v[222:225], v[18:21]
	v_mfma_f32_16x16x32_bf16 v[14:17], v[196:199], v[222:225], v[14:17]
	v_mfma_f32_16x16x32_bf16 v[10:13], v[184:187], v[230:233], v[10:13]
	v_mfma_f32_16x16x32_bf16 v[6:9], v[196:199], v[230:233], v[6:9]
	v_mfma_f32_16x16x32_bf16 v[42:45], v[188:191], v[210:213], v[42:45]
	v_mfma_f32_16x16x32_bf16 v[34:37], v[200:203], v[210:213], v[34:37]
	v_mfma_f32_16x16x32_bf16 v[26:29], v[188:191], v[218:221], v[26:29]
	v_mfma_f32_16x16x32_bf16 v[22:25], v[200:203], v[218:221], v[22:25]
	v_mfma_f32_16x16x32_bf16 v[18:21], v[188:191], v[226:229], v[18:21]
	v_mfma_f32_16x16x32_bf16 v[14:17], v[200:203], v[226:229], v[14:17]
	v_mfma_f32_16x16x32_bf16 v[10:13], v[188:191], v[234:237], v[10:13]
	v_mfma_f32_16x16x32_bf16 v[6:9], v[200:203], v[234:237], v[6:9]
	s_setprio 0
	s_barrier
	s_add_i32 s46, s80, s61
	v_lshl_add_u64 v[166:167], v[166:167], 0, s[18:19]
	s_mov_b32 m0, s46
	ds_read_b128 v[206:209], v170 offset:49152
	ds_read_b128 v[210:213], v170 offset:50176
	ds_read_b128 v[214:217], v170 offset:51200
	ds_read_b128 v[218:221], v170 offset:52224
	ds_read_b128 v[222:225], v170 offset:53248
	ds_read_b128 v[226:229], v170 offset:54272
	ds_read_b128 v[230:233], v170 offset:55296
	ds_read_b128 v[234:237], v170 offset:56320
	global_load_lds_dwordx4 v[166:167], off
	s_add_i32 m0, s46, 0x2000
	s_add_u32 s42, s42, 0x100080
	v_lshl_add_u64 v[166:167], v[192:193], 0, s[18:19]
	s_addc_u32 s43, s43, 0
	s_add_i32 s46, s81, s61
	global_load_lds_dwordx4 v[166:167], off
	v_lshl_add_u64 v[166:167], s[42:43], 0, v[134:135]
	s_mov_b32 m0, s46
	s_nop 0
	global_load_lds_dwordx4 v[166:167], off
	v_lshl_add_u64 v[166:167], s[42:43], 0, v[138:139]
	s_add_i32 m0, s46, 0x2000
	s_nop 0
	global_load_lds_dwordx4 v[166:167], off
	v_lshl_add_u64 v[166:167], v[238:239], 0, s[18:19]
	s_mov_b32 m0, s69
	s_nop 0
	global_load_lds_dwordx4 v[166:167], off
	v_lshl_add_u64 v[166:167], v[240:241], 0, s[18:19]
	s_mov_b32 m0, s70
	s_nop 0
	global_load_lds_dwordx4 v[166:167], off
	s_branch .Lal64_51
.Lal64_51:
	s_waitcnt vmcnt(8)
	s_waitcnt lgkmcnt(0)
	s_barrier
	s_setprio 1
	v_mfma_f32_16x16x32_bf16 v[126:129], v[162:165], v[206:209], v[126:129]
	v_mfma_f32_16x16x32_bf16 v[122:125], v[176:179], v[206:209], v[122:125]
	v_mfma_f32_16x16x32_bf16 v[110:113], v[162:165], v[214:217], v[110:113]
	v_mfma_f32_16x16x32_bf16 v[106:109], v[176:179], v[214:217], v[106:109]
	v_mfma_f32_16x16x32_bf16 v[94:97], v[162:165], v[222:225], v[94:97]
	v_mfma_f32_16x16x32_bf16 v[90:93], v[176:179], v[222:225], v[90:93]
	v_mfma_f32_16x16x32_bf16 v[78:81], v[162:165], v[230:233], v[78:81]
	v_mfma_f32_16x16x32_bf16 v[74:77], v[176:179], v[230:233], v[74:77]
	v_mfma_f32_16x16x32_bf16 v[126:129], v[172:175], v[210:213], v[126:129]
	v_mfma_f32_16x16x32_bf16 v[122:125], v[180:183], v[210:213], v[122:125]
	v_mfma_f32_16x16x32_bf16 v[110:113], v[172:175], v[218:221], v[110:113]
	v_mfma_f32_16x16x32_bf16 v[106:109], v[180:183], v[218:221], v[106:109]
	v_mfma_f32_16x16x32_bf16 v[94:97], v[172:175], v[226:229], v[94:97]
	v_mfma_f32_16x16x32_bf16 v[90:93], v[180:183], v[226:229], v[90:93]
	v_mfma_f32_16x16x32_bf16 v[78:81], v[172:175], v[234:237], v[78:81]
	v_mfma_f32_16x16x32_bf16 v[74:77], v[180:183], v[234:237], v[74:77]
	v_mfma_f32_16x16x32_bf16 v[118:121], v[184:187], v[206:209], v[118:121]
	v_mfma_f32_16x16x32_bf16 v[114:117], v[196:199], v[206:209], v[114:117]
	v_mfma_f32_16x16x32_bf16 v[102:105], v[184:187], v[214:217], v[102:105]
	v_mfma_f32_16x16x32_bf16 v[98:101], v[196:199], v[214:217], v[98:101]
	v_mfma_f32_16x16x32_bf16 v[86:89], v[184:187], v[222:225], v[86:89]
	v_mfma_f32_16x16x32_bf16 v[82:85], v[196:199], v[222:225], v[82:85]
	v_mfma_f32_16x16x32_bf16 v[70:73], v[184:187], v[230:233], v[70:73]
	v_mfma_f32_16x16x32_bf16 v[2:5], v[196:199], v[230:233], v[2:5]
	v_mfma_f32_16x16x32_bf16 v[118:121], v[188:191], v[210:213], v[118:121]
	v_mfma_f32_16x16x32_bf16 v[114:117], v[200:203], v[210:213], v[114:117]
	v_mfma_f32_16x16x32_bf16 v[102:105], v[188:191], v[218:221], v[102:105]
	v_mfma_f32_16x16x32_bf16 v[98:101], v[200:203], v[218:221], v[98:101]
	v_mfma_f32_16x16x32_bf16 v[86:89], v[188:191], v[226:229], v[86:89]
	v_mfma_f32_16x16x32_bf16 v[82:85], v[200:203], v[226:229], v[82:85]
	v_mfma_f32_16x16x32_bf16 v[70:73], v[188:191], v[234:237], v[70:73]
	v_mfma_f32_16x16x32_bf16 v[2:5], v[200:203], v[234:237], v[2:5]
	s_setprio 0
	s_barrier
	s_add_u32 s8, s8, 0x100
	s_addc_u32 s9, s9, 0
	s_add_u32 s49, s49, 0x100
	s_addc_u32 s53, s53, 0
	s_cmp_ge_i32 s55, s3
	s_mov_b32 s42, s55
	s_cbranch_scc0 .LBB0_1869
	s_and_b64 vcc, exec, s[20:21]
	s_cbranch_vccz .LBB0_1874
	s_barrier
	v_lshl_or_b32 v162, s40, 8, v141
	s_cmp_lt_i32 s10, 0
	s_mov_b64 s[8:9], -1
	s_cbranch_scc1 .LBB0_1875

.LBB0_3649:
	ds_read_b128 v[152:155], v162
	ds_read_b128 v[156:159], v162 offset:1024
	ds_read_b128 v[168:171], v162 offset:2048
	ds_read_b128 v[172:175], v162 offset:3072
	ds_read_b128 v[176:179], v163
	ds_read_b128 v[180:183], v163 offset:1024
	ds_read_b128 v[184:187], v163 offset:2048
	ds_read_b128 v[188:191], v163 offset:3072
	s_add_i32 s86, s48, 2
	s_add_u32 s49, s6, 0xfff00080
	s_addc_u32 s64, s7, -1
	s_cmp_eq_u32 s51, s48
	s_cselect_b32 s48, s58, s53
	s_cselect_b32 s65, s57, s64
	s_cselect_b32 s64, s56, s49
	s_cselect_b32 s49, s59, s55
	v_lshl_add_u64 v[192:193], s[6:7], 0, v[140:141]
	s_add_i32 m0, s61, 0xc000
	ds_read_b128 v[196:199], v164
	ds_read_b128 v[200:203], v164 offset:1024
	ds_read_b128 v[206:209], v164 offset:2048
	ds_read_b128 v[210:213], v164 offset:3072
	ds_read_b128 v[214:217], v164 offset:4096
	ds_read_b128 v[218:221], v164 offset:5120
	ds_read_b128 v[222:225], v164 offset:6144
	ds_read_b128 v[226:229], v164 offset:7168
	global_load_lds_dwordx4 v[192:193], off
	v_lshl_add_u64 v[192:193], s[6:7], 0, v[142:143]
	s_add_i32 m0, s61, 0xe000
	s_nop 0
	global_load_lds_dwordx4 v[192:193], off
	s_branch .Lal64_52
	s_nop 0
	s_nop 0
	s_nop 0
	s_nop 0
	s_nop 0
	s_nop 0
	s_nop 0
	s_nop 0
	s_nop 0
	s_nop 0
	s_nop 0
	s_nop 0
	s_nop 0
	s_nop 0
.Lal64_52:
	s_waitcnt vmcnt(8)
	s_waitcnt lgkmcnt(0)
	s_barrier
	s_setprio 1
	v_mfma_f32_16x16x32_bf16 v[126:129], v[152:155], v[196:199], v[126:129]
	v_mfma_f32_16x16x32_bf16 v[122:125], v[168:171], v[196:199], v[122:125]
	v_mfma_f32_16x16x32_bf16 v[110:113], v[152:155], v[206:209], v[110:113]
	v_mfma_f32_16x16x32_bf16 v[106:109], v[168:171], v[206:209], v[106:109]
	v_mfma_f32_16x16x32_bf16 v[94:97], v[152:155], v[214:217], v[94:97]
	v_mfma_f32_16x16x32_bf16 v[90:93], v[168:171], v[214:217], v[90:93]
	v_mfma_f32_16x16x32_bf16 v[78:81], v[152:155], v[222:225], v[78:81]
	v_mfma_f32_16x16x32_bf16 v[74:77], v[168:171], v[222:225], v[74:77]
	v_mfma_f32_16x16x32_bf16 v[126:129], v[156:159], v[200:203], v[126:129]
	v_mfma_f32_16x16x32_bf16 v[122:125], v[172:175], v[200:203], v[122:125]
	v_mfma_f32_16x16x32_bf16 v[110:113], v[156:159], v[210:213], v[110:113]
	v_mfma_f32_16x16x32_bf16 v[106:109], v[172:175], v[210:213], v[106:109]
	v_mfma_f32_16x16x32_bf16 v[94:97], v[156:159], v[218:221], v[94:97]
	v_mfma_f32_16x16x32_bf16 v[90:93], v[172:175], v[218:221], v[90:93]
	v_mfma_f32_16x16x32_bf16 v[78:81], v[156:159], v[226:229], v[78:81]
	v_mfma_f32_16x16x32_bf16 v[74:77], v[172:175], v[226:229], v[74:77]
	v_mfma_f32_16x16x32_bf16 v[118:121], v[176:179], v[196:199], v[118:121]
	v_mfma_f32_16x16x32_bf16 v[114:117], v[184:187], v[196:199], v[114:117]
	v_mfma_f32_16x16x32_bf16 v[102:105], v[176:179], v[206:209], v[102:105]
	v_mfma_f32_16x16x32_bf16 v[98:101], v[184:187], v[206:209], v[98:101]
	v_mfma_f32_16x16x32_bf16 v[86:89], v[176:179], v[214:217], v[86:89]
	v_mfma_f32_16x16x32_bf16 v[82:85], v[184:187], v[214:217], v[82:85]
	v_mfma_f32_16x16x32_bf16 v[70:73], v[176:179], v[222:225], v[70:73]
	v_mfma_f32_16x16x32_bf16 v[66:69], v[184:187], v[222:225], v[66:69]
	v_mfma_f32_16x16x32_bf16 v[118:121], v[180:183], v[200:203], v[118:121]
	v_mfma_f32_16x16x32_bf16 v[114:117], v[188:191], v[200:203], v[114:117]
	v_mfma_f32_16x16x32_bf16 v[102:105], v[180:183], v[210:213], v[102:105]
	v_mfma_f32_16x16x32_bf16 v[98:101], v[188:191], v[210:213], v[98:101]
	v_mfma_f32_16x16x32_bf16 v[86:89], v[180:183], v[218:221], v[86:89]
	v_mfma_f32_16x16x32_bf16 v[82:85], v[188:191], v[218:221], v[82:85]
	v_mfma_f32_16x16x32_bf16 v[70:73], v[180:183], v[226:229], v[70:73]
	v_mfma_f32_16x16x32_bf16 v[66:69], v[188:191], v[226:229], v[66:69]
	s_setprio 0
	s_barrier
	s_add_i32 s87, s75, s66
	v_lshl_add_u64 v[192:193], s[48:49], 0, v[134:135]
	s_mov_b32 m0, s87
	ds_read_b128 v[196:199], v164 offset:16384
	ds_read_b128 v[200:203], v164 offset:17408
	ds_read_b128 v[206:209], v164 offset:18432
	ds_read_b128 v[210:213], v164 offset:19456
	ds_read_b128 v[214:217], v164 offset:20480
	ds_read_b128 v[218:221], v164 offset:21504
	ds_read_b128 v[222:225], v164 offset:22528
	ds_read_b128 v[226:229], v164 offset:23552
	global_load_lds_dwordx4 v[192:193], off
	s_add_i32 m0, s87, 0x2000
	s_add_u32 s88, s48, 0x100000
	v_lshl_add_u64 v[230:231], s[48:49], 0, v[138:139]
	s_addc_u32 s89, s49, 0
	s_add_i32 s87, s76, s66
	global_load_lds_dwordx4 v[230:231], off
	v_lshl_add_u64 v[232:233], s[88:89], 0, v[134:135]
	s_mov_b32 m0, s87
	v_lshl_add_u64 v[234:235], s[64:65], 0, v[136:137]
	global_load_lds_dwordx4 v[232:233], off
	v_lshl_add_u64 v[232:233], s[88:89], 0, v[138:139]
	s_add_i32 m0, s87, 0x2000
	s_nop 0
	global_load_lds_dwordx4 v[232:233], off
	v_lshl_add_u64 v[232:233], s[64:65], 0, v[132:133]
	s_mov_b32 m0, s61
	s_nop 0
	global_load_lds_dwordx4 v[232:233], off
	s_mov_b32 m0, s63
	s_nop 0
	global_load_lds_dwordx4 v[234:235], off
	s_branch .Lal64_53
	s_nop 0
.Lal64_53:
	s_waitcnt vmcnt(8)
	s_waitcnt lgkmcnt(0)
	s_barrier
	s_setprio 1
	v_mfma_f32_16x16x32_bf16 v[62:65], v[152:155], v[196:199], v[62:65]
	v_mfma_f32_16x16x32_bf16 v[58:61], v[168:171], v[196:199], v[58:61]
	v_mfma_f32_16x16x32_bf16 v[46:49], v[152:155], v[206:209], v[46:49]
	v_mfma_f32_16x16x32_bf16 v[42:45], v[168:171], v[206:209], v[42:45]
	v_mfma_f32_16x16x32_bf16 v[30:33], v[152:155], v[214:217], v[30:33]
	v_mfma_f32_16x16x32_bf16 v[26:29], v[168:171], v[214:217], v[26:29]
	v_mfma_f32_16x16x32_bf16 v[14:17], v[152:155], v[222:225], v[14:17]
	v_mfma_f32_16x16x32_bf16 v[10:13], v[168:171], v[222:225], v[10:13]
	v_mfma_f32_16x16x32_bf16 v[62:65], v[156:159], v[200:203], v[62:65]
	v_mfma_f32_16x16x32_bf16 v[58:61], v[172:175], v[200:203], v[58:61]
	v_mfma_f32_16x16x32_bf16 v[46:49], v[156:159], v[210:213], v[46:49]
	v_mfma_f32_16x16x32_bf16 v[42:45], v[172:175], v[210:213], v[42:45]
	v_mfma_f32_16x16x32_bf16 v[30:33], v[156:159], v[218:221], v[30:33]
	v_mfma_f32_16x16x32_bf16 v[26:29], v[172:175], v[218:221], v[26:29]
	v_mfma_f32_16x16x32_bf16 v[14:17], v[156:159], v[226:229], v[14:17]
	v_mfma_f32_16x16x32_bf16 v[10:13], v[172:175], v[226:229], v[10:13]
	v_mfma_f32_16x16x32_bf16 v[54:57], v[176:179], v[196:199], v[54:57]
	v_mfma_f32_16x16x32_bf16 v[50:53], v[184:187], v[196:199], v[50:53]
	v_mfma_f32_16x16x32_bf16 v[38:41], v[176:179], v[206:209], v[38:41]
	v_mfma_f32_16x16x32_bf16 v[34:37], v[184:187], v[206:209], v[34:37]
	v_mfma_f32_16x16x32_bf16 v[22:25], v[176:179], v[214:217], v[22:25]
	v_mfma_f32_16x16x32_bf16 v[18:21], v[184:187], v[214:217], v[18:21]
	v_mfma_f32_16x16x32_bf16 v[6:9], v[176:179], v[222:225], v[6:9]
	v_mfma_f32_16x16x32_bf16 v[2:5], v[184:187], v[222:225], v[2:5]
	v_mfma_f32_16x16x32_bf16 v[54:57], v[180:183], v[200:203], v[54:57]
	v_mfma_f32_16x16x32_bf16 v[50:53], v[188:191], v[200:203], v[50:53]
	v_mfma_f32_16x16x32_bf16 v[38:41], v[180:183], v[210:213], v[38:41]
	v_mfma_f32_16x16x32_bf16 v[34:37], v[188:191], v[210:213], v[34:37]
	v_mfma_f32_16x16x32_bf16 v[22:25], v[180:183], v[218:221], v[22:25]
	v_mfma_f32_16x16x32_bf16 v[18:21], v[188:191], v[218:221], v[18:21]
	v_mfma_f32_16x16x32_bf16 v[6:9], v[180:183], v[226:229], v[6:9]
	v_mfma_f32_16x16x32_bf16 v[2:5], v[188:191], v[226:229], v[2:5]
	s_setprio 0
	s_barrier
	s_add_i32 s87, 0, 0x18000
	v_add_u32_e32 v167, s87, v160
	s_add_i32 s88, 0, 0x1c000
	ds_read_b128 v[152:155], v167
	ds_read_b128 v[156:159], v167 offset:1024
	ds_read_b128 v[168:171], v167 offset:2048
	ds_read_b128 v[172:175], v167 offset:3072
	v_add_u32_e32 v167, s88, v160
	ds_read_b128 v[176:179], v167
	ds_read_b128 v[180:183], v167 offset:1024
	ds_read_b128 v[184:187], v167 offset:2048
	ds_read_b128 v[188:191], v167 offset:3072
	s_add_u32 s64, s64, 0x100000
	s_addc_u32 s65, s65, 0
	s_mov_b32 m0, s67
	v_lshl_add_u64 v[236:237], s[64:65], 0, v[132:133]
	ds_read_b128 v[196:199], v164 offset:32768
	ds_read_b128 v[200:203], v164 offset:33792
	ds_read_b128 v[206:209], v164 offset:34816
	ds_read_b128 v[210:213], v164 offset:35840
	ds_read_b128 v[214:217], v164 offset:36864
	ds_read_b128 v[218:221], v164 offset:37888
	ds_read_b128 v[222:225], v164 offset:38912
	ds_read_b128 v[226:229], v164 offset:39936
	global_load_lds_dwordx4 v[236:237], off
	v_lshl_add_u64 v[236:237], s[64:65], 0, v[136:137]
	s_mov_b32 m0, s68
	s_nop 0
	global_load_lds_dwordx4 v[236:237], off
	s_branch .Lal64_54
	s_nop 0
	s_nop 0
	s_nop 0
	s_nop 0
	s_nop 0
.Lal64_54:
	s_waitcnt vmcnt(8)
	s_waitcnt lgkmcnt(0)
	s_barrier
	s_setprio 1
	v_mfma_f32_16x16x32_bf16 v[126:129], v[152:155], v[196:199], v[126:129]
	v_mfma_f32_16x16x32_bf16 v[122:125], v[168:171], v[196:199], v[122:125]
	v_mfma_f32_16x16x32_bf16 v[110:113], v[152:155], v[206:209], v[110:113]
	v_mfma_f32_16x16x32_bf16 v[106:109], v[168:171], v[206:209], v[106:109]
	v_mfma_f32_16x16x32_bf16 v[94:97], v[152:155], v[214:217], v[94:97]
	v_mfma_f32_16x16x32_bf16 v[90:93], v[168:171], v[214:217], v[90:93]
	v_mfma_f32_16x16x32_bf16 v[78:81], v[152:155], v[222:225], v[78:81]
	v_mfma_f32_16x16x32_bf16 v[74:77], v[168:171], v[222:225], v[74:77]
	v_mfma_f32_16x16x32_bf16 v[126:129], v[156:159], v[200:203], v[126:129]
	v_mfma_f32_16x16x32_bf16 v[122:125], v[172:175], v[200:203], v[122:125]
	v_mfma_f32_16x16x32_bf16 v[110:113], v[156:159], v[210:213], v[110:113]
	v_mfma_f32_16x16x32_bf16 v[106:109], v[172:175], v[210:213], v[106:109]
	v_mfma_f32_16x16x32_bf16 v[94:97], v[156:159], v[218:221], v[94:97]
	v_mfma_f32_16x16x32_bf16 v[90:93], v[172:175], v[218:221], v[90:93]
	v_mfma_f32_16x16x32_bf16 v[78:81], v[156:159], v[226:229], v[78:81]
	v_mfma_f32_16x16x32_bf16 v[74:77], v[172:175], v[226:229], v[74:77]
	v_mfma_f32_16x16x32_bf16 v[118:121], v[176:179], v[196:199], v[118:121]
	v_mfma_f32_16x16x32_bf16 v[114:117], v[184:187], v[196:199], v[114:117]
	v_mfma_f32_16x16x32_bf16 v[102:105], v[176:179], v[206:209], v[102:105]
	v_mfma_f32_16x16x32_bf16 v[98:101], v[184:187], v[206:209], v[98:101]
	v_mfma_f32_16x16x32_bf16 v[86:89], v[176:179], v[214:217], v[86:89]
	v_mfma_f32_16x16x32_bf16 v[82:85], v[184:187], v[214:217], v[82:85]
	v_mfma_f32_16x16x32_bf16 v[70:73], v[176:179], v[222:225], v[70:73]
	v_mfma_f32_16x16x32_bf16 v[66:69], v[184:187], v[222:225], v[66:69]
	v_mfma_f32_16x16x32_bf16 v[118:121], v[180:183], v[200:203], v[118:121]
	v_mfma_f32_16x16x32_bf16 v[114:117], v[188:191], v[200:203], v[114:117]
	v_mfma_f32_16x16x32_bf16 v[102:105], v[180:183], v[210:213], v[102:105]
	v_mfma_f32_16x16x32_bf16 v[98:101], v[188:191], v[210:213], v[98:101]
	v_mfma_f32_16x16x32_bf16 v[86:89], v[180:183], v[218:221], v[86:89]
	v_mfma_f32_16x16x32_bf16 v[82:85], v[188:191], v[218:221], v[82:85]
	v_mfma_f32_16x16x32_bf16 v[70:73], v[180:183], v[226:229], v[70:73]
	v_mfma_f32_16x16x32_bf16 v[66:69], v[188:191], v[226:229], v[66:69]
	s_setprio 0
	s_barrier
	s_add_i32 s64, s87, s66
	v_lshl_add_u64 v[192:193], v[192:193], 0, s[20:21]
	s_mov_b32 m0, s64
	ds_read_b128 v[196:199], v164 offset:49152
	ds_read_b128 v[200:203], v164 offset:50176
	ds_read_b128 v[206:209], v164 offset:51200
	ds_read_b128 v[210:213], v164 offset:52224
	ds_read_b128 v[214:217], v164 offset:53248
	ds_read_b128 v[218:221], v164 offset:54272
	ds_read_b128 v[222:225], v164 offset:55296
	ds_read_b128 v[226:229], v164 offset:56320
	global_load_lds_dwordx4 v[192:193], off
	s_add_i32 m0, s64, 0x2000
	s_add_u32 s48, s48, 0x100080
	v_lshl_add_u64 v[192:193], v[230:231], 0, s[20:21]
	s_addc_u32 s49, s49, 0
	s_add_i32 s64, s88, s66
	global_load_lds_dwordx4 v[192:193], off
	v_lshl_add_u64 v[192:193], s[48:49], 0, v[134:135]
	s_mov_b32 m0, s64
	s_nop 0
	global_load_lds_dwordx4 v[192:193], off
	v_lshl_add_u64 v[192:193], s[48:49], 0, v[138:139]
	s_add_i32 m0, s64, 0x2000
	s_nop 0
	global_load_lds_dwordx4 v[192:193], off
	v_lshl_add_u64 v[192:193], v[232:233], 0, s[20:21]
	s_mov_b32 m0, s72
	s_nop 0
	global_load_lds_dwordx4 v[192:193], off
	v_lshl_add_u64 v[192:193], v[234:235], 0, s[20:21]
	s_mov_b32 m0, s73
	s_nop 0
	global_load_lds_dwordx4 v[192:193], off
	s_branch .Lal64_55
.Lal64_55:
	s_waitcnt vmcnt(8)
	s_waitcnt lgkmcnt(0)
	s_barrier
	s_setprio 1
	v_mfma_f32_16x16x32_bf16 v[62:65], v[152:155], v[196:199], v[62:65]
	v_mfma_f32_16x16x32_bf16 v[58:61], v[168:171], v[196:199], v[58:61]
	v_mfma_f32_16x16x32_bf16 v[46:49], v[152:155], v[206:209], v[46:49]
	v_mfma_f32_16x16x32_bf16 v[42:45], v[168:171], v[206:209], v[42:45]
	v_mfma_f32_16x16x32_bf16 v[30:33], v[152:155], v[214:217], v[30:33]
	v_mfma_f32_16x16x32_bf16 v[26:29], v[168:171], v[214:217], v[26:29]
	v_mfma_f32_16x16x32_bf16 v[14:17], v[152:155], v[222:225], v[14:17]
	v_mfma_f32_16x16x32_bf16 v[10:13], v[168:171], v[222:225], v[10:13]
	v_mfma_f32_16x16x32_bf16 v[62:65], v[156:159], v[200:203], v[62:65]
	v_mfma_f32_16x16x32_bf16 v[58:61], v[172:175], v[200:203], v[58:61]
	v_mfma_f32_16x16x32_bf16 v[46:49], v[156:159], v[210:213], v[46:49]
	v_mfma_f32_16x16x32_bf16 v[42:45], v[172:175], v[210:213], v[42:45]
	v_mfma_f32_16x16x32_bf16 v[30:33], v[156:159], v[218:221], v[30:33]
	v_mfma_f32_16x16x32_bf16 v[26:29], v[172:175], v[218:221], v[26:29]
	v_mfma_f32_16x16x32_bf16 v[14:17], v[156:159], v[226:229], v[14:17]
	v_mfma_f32_16x16x32_bf16 v[10:13], v[172:175], v[226:229], v[10:13]
	v_mfma_f32_16x16x32_bf16 v[54:57], v[176:179], v[196:199], v[54:57]
	v_mfma_f32_16x16x32_bf16 v[50:53], v[184:187], v[196:199], v[50:53]
	v_mfma_f32_16x16x32_bf16 v[38:41], v[176:179], v[206:209], v[38:41]
	v_mfma_f32_16x16x32_bf16 v[34:37], v[184:187], v[206:209], v[34:37]
	v_mfma_f32_16x16x32_bf16 v[22:25], v[176:179], v[214:217], v[22:25]
	v_mfma_f32_16x16x32_bf16 v[18:21], v[184:187], v[214:217], v[18:21]
	v_mfma_f32_16x16x32_bf16 v[6:9], v[176:179], v[222:225], v[6:9]
	v_mfma_f32_16x16x32_bf16 v[2:5], v[184:187], v[222:225], v[2:5]
	v_mfma_f32_16x16x32_bf16 v[54:57], v[180:183], v[200:203], v[54:57]
	v_mfma_f32_16x16x32_bf16 v[50:53], v[188:191], v[200:203], v[50:53]
	v_mfma_f32_16x16x32_bf16 v[38:41], v[180:183], v[210:213], v[38:41]
	v_mfma_f32_16x16x32_bf16 v[34:37], v[188:191], v[210:213], v[34:37]
	v_mfma_f32_16x16x32_bf16 v[22:25], v[180:183], v[218:221], v[22:25]
	v_mfma_f32_16x16x32_bf16 v[18:21], v[188:191], v[218:221], v[18:21]
	v_mfma_f32_16x16x32_bf16 v[6:9], v[180:183], v[226:229], v[6:9]
	v_mfma_f32_16x16x32_bf16 v[2:5], v[188:191], v[226:229], v[2:5]
	s_setprio 0
	s_barrier
	s_add_u32 s6, s6, 0x100
	s_addc_u32 s7, s7, 0
	s_add_u32 s53, s53, 0x100
	s_addc_u32 s55, s55, 0
	s_cmp_ge_i32 s86, s85
	s_mov_b32 s48, s86
	s_cbranch_scc0 .LBB0_3649
	s_and_b64 vcc, exec, s[22:23]
	s_cbranch_vccz .LBB0_3652
	s_barrier

.LBB0_3789:
	ds_read_b128 v[162:165], v145
	ds_read_b128 v[166:169], v145 offset:1024
	ds_read_b128 v[170:173], v145 offset:2048
	ds_read_b128 v[174:177], v145 offset:3072
	ds_read_b128 v[178:181], v160
	ds_read_b128 v[182:185], v160 offset:1024
	ds_read_b128 v[186:189], v160 offset:2048
	ds_read_b128 v[190:193], v160 offset:3072
	s_add_i32 s63, s30, 2
	s_add_u32 s31, s28, 0xfff00080
	s_addc_u32 s34, s29, -1
	s_cmp_eq_u32 s60, s30
	s_cselect_b32 s30, s59, s61
	s_cselect_b32 s35, s19, s34
	s_cselect_b32 s34, s23, s31
	s_cselect_b32 s31, s21, s62
	v_lshl_add_u64 v[158:159], s[28:29], 0, v[148:149]
	s_add_i32 m0, s6, 0xc000
	ds_read_b128 v[196:199], v161
	ds_read_b128 v[200:203], v161 offset:1024
	ds_read_b128 v[206:209], v161 offset:2048
	ds_read_b128 v[210:213], v161 offset:3072
	ds_read_b128 v[214:217], v161 offset:4096
	ds_read_b128 v[218:221], v161 offset:5120
	ds_read_b128 v[222:225], v161 offset:6144
	ds_read_b128 v[226:229], v161 offset:7168
	global_load_lds_dwordx4 v[158:159], off
	v_lshl_add_u64 v[158:159], s[28:29], 0, v[150:151]
	s_add_i32 m0, s6, 0xe000
	s_nop 0
	global_load_lds_dwordx4 v[158:159], off
	s_branch .Lal64_56
	s_nop 0
	s_nop 0
	s_nop 0
.Lal64_56:
	s_waitcnt vmcnt(8)
	s_waitcnt lgkmcnt(0)
	s_barrier
	s_setprio 1
	v_mfma_f32_16x16x32_bf16 v[126:129], v[162:165], v[196:199], v[126:129]
	v_mfma_f32_16x16x32_bf16 v[122:125], v[170:173], v[196:199], v[122:125]
	v_mfma_f32_16x16x32_bf16 v[118:121], v[162:165], v[206:209], v[118:121]
	v_mfma_f32_16x16x32_bf16 v[114:117], v[170:173], v[206:209], v[114:117]
	v_mfma_f32_16x16x32_bf16 v[102:105], v[162:165], v[214:217], v[102:105]
	v_mfma_f32_16x16x32_bf16 v[98:101], v[170:173], v[214:217], v[98:101]
	v_mfma_f32_16x16x32_bf16 v[42:45], v[162:165], v[222:225], v[42:45]
	v_mfma_f32_16x16x32_bf16 v[34:37], v[170:173], v[222:225], v[34:37]
	v_mfma_f32_16x16x32_bf16 v[126:129], v[166:169], v[200:203], v[126:129]
	v_mfma_f32_16x16x32_bf16 v[122:125], v[174:177], v[200:203], v[122:125]
	v_mfma_f32_16x16x32_bf16 v[118:121], v[166:169], v[210:213], v[118:121]
	v_mfma_f32_16x16x32_bf16 v[114:117], v[174:177], v[210:213], v[114:117]
	v_mfma_f32_16x16x32_bf16 v[102:105], v[166:169], v[218:221], v[102:105]
	v_mfma_f32_16x16x32_bf16 v[98:101], v[174:177], v[218:221], v[98:101]
	v_mfma_f32_16x16x32_bf16 v[42:45], v[166:169], v[226:229], v[42:45]
	v_mfma_f32_16x16x32_bf16 v[34:37], v[174:177], v[226:229], v[34:37]
	v_mfma_f32_16x16x32_bf16 v[110:113], v[178:181], v[196:199], v[110:113]
	v_mfma_f32_16x16x32_bf16 v[106:109], v[186:189], v[196:199], v[106:109]
	v_mfma_f32_16x16x32_bf16 v[94:97], v[178:181], v[206:209], v[94:97]
	v_mfma_f32_16x16x32_bf16 v[90:93], v[186:189], v[206:209], v[90:93]
	v_mfma_f32_16x16x32_bf16 v[86:89], v[178:181], v[214:217], v[86:89]
	v_mfma_f32_16x16x32_bf16 v[82:85], v[186:189], v[214:217], v[82:85]
	v_mfma_f32_16x16x32_bf16 v[30:33], v[178:181], v[222:225], v[30:33]
	v_mfma_f32_16x16x32_bf16 v[26:29], v[186:189], v[222:225], v[26:29]
	v_mfma_f32_16x16x32_bf16 v[110:113], v[182:185], v[200:203], v[110:113]
	v_mfma_f32_16x16x32_bf16 v[106:109], v[190:193], v[200:203], v[106:109]
	v_mfma_f32_16x16x32_bf16 v[94:97], v[182:185], v[210:213], v[94:97]
	v_mfma_f32_16x16x32_bf16 v[90:93], v[190:193], v[210:213], v[90:93]
	v_mfma_f32_16x16x32_bf16 v[86:89], v[182:185], v[218:221], v[86:89]
	v_mfma_f32_16x16x32_bf16 v[82:85], v[190:193], v[218:221], v[82:85]
	v_mfma_f32_16x16x32_bf16 v[30:33], v[182:185], v[226:229], v[30:33]
	v_mfma_f32_16x16x32_bf16 v[26:29], v[190:193], v[226:229], v[26:29]
	s_setprio 0
	s_barrier
	s_add_i32 s64, s54, s40
	v_lshl_add_u64 v[158:159], s[30:31], 0, v[134:135]
	s_mov_b32 m0, s64
	ds_read_b128 v[196:199], v161 offset:16384
	ds_read_b128 v[200:203], v161 offset:17408
	ds_read_b128 v[206:209], v161 offset:18432
	ds_read_b128 v[210:213], v161 offset:19456
	ds_read_b128 v[214:217], v161 offset:20480
	ds_read_b128 v[218:221], v161 offset:21504
	ds_read_b128 v[222:225], v161 offset:22528
	ds_read_b128 v[226:229], v161 offset:23552
	global_load_lds_dwordx4 v[158:159], off
	s_add_i32 m0, s64, 0x2000
	s_add_u32 s64, s30, 0x100000
	v_lshl_add_u64 v[230:231], s[30:31], 0, v[132:133]
	s_addc_u32 s65, s31, 0
	s_add_i32 s66, s55, s40
	global_load_lds_dwordx4 v[230:231], off
	v_lshl_add_u64 v[232:233], s[64:65], 0, v[134:135]
	s_mov_b32 m0, s66
	v_lshl_add_u64 v[234:235], s[34:35], 0, v[132:133]
	global_load_lds_dwordx4 v[232:233], off
	v_lshl_add_u64 v[232:233], s[64:65], 0, v[132:133]
	s_add_i32 m0, s66, 0x2000
	s_nop 0
	global_load_lds_dwordx4 v[232:233], off
	v_lshl_add_u64 v[232:233], s[34:35], 0, v[134:135]
	s_mov_b32 m0, s6
	s_nop 0
	global_load_lds_dwordx4 v[232:233], off
	s_mov_b32 m0, s13
	s_nop 0
	global_load_lds_dwordx4 v[234:235], off
	s_branch .Lal64_57
	s_nop 0
.Lal64_57:
	s_waitcnt vmcnt(8)
	s_waitcnt lgkmcnt(0)
	s_barrier
	s_setprio 1
	v_mfma_f32_16x16x32_bf16 v[78:81], v[162:165], v[196:199], v[78:81]
	v_mfma_f32_16x16x32_bf16 v[74:77], v[170:173], v[196:199], v[74:77]
	v_mfma_f32_16x16x32_bf16 v[70:73], v[162:165], v[206:209], v[70:73]
	v_mfma_f32_16x16x32_bf16 v[66:69], v[170:173], v[206:209], v[66:69]
	v_mfma_f32_16x16x32_bf16 v[54:57], v[162:165], v[214:217], v[54:57]
	v_mfma_f32_16x16x32_bf16 v[50:53], v[170:173], v[214:217], v[50:53]
	v_mfma_f32_16x16x32_bf16 v[14:17], v[162:165], v[222:225], v[14:17]
	v_mfma_f32_16x16x32_bf16 v[10:13], v[170:173], v[222:225], v[10:13]
	v_mfma_f32_16x16x32_bf16 v[78:81], v[166:169], v[200:203], v[78:81]
	v_mfma_f32_16x16x32_bf16 v[74:77], v[174:177], v[200:203], v[74:77]
	v_mfma_f32_16x16x32_bf16 v[70:73], v[166:169], v[210:213], v[70:73]
	v_mfma_f32_16x16x32_bf16 v[66:69], v[174:177], v[210:213], v[66:69]
	v_mfma_f32_16x16x32_bf16 v[54:57], v[166:169], v[218:221], v[54:57]
	v_mfma_f32_16x16x32_bf16 v[50:53], v[174:177], v[218:221], v[50:53]
	v_mfma_f32_16x16x32_bf16 v[14:17], v[166:169], v[226:229], v[14:17]
	v_mfma_f32_16x16x32_bf16 v[10:13], v[174:177], v[226:229], v[10:13]
	v_mfma_f32_16x16x32_bf16 v[62:65], v[178:181], v[196:199], v[62:65]
	v_mfma_f32_16x16x32_bf16 v[58:61], v[186:189], v[196:199], v[58:61]
	v_mfma_f32_16x16x32_bf16 v[46:49], v[178:181], v[206:209], v[46:49]
	v_mfma_f32_16x16x32_bf16 v[38:41], v[186:189], v[206:209], v[38:41]
	v_mfma_f32_16x16x32_bf16 v[22:25], v[178:181], v[214:217], v[22:25]
	v_mfma_f32_16x16x32_bf16 v[18:21], v[186:189], v[214:217], v[18:21]
	v_mfma_f32_16x16x32_bf16 v[6:9], v[178:181], v[222:225], v[6:9]
	v_mfma_f32_16x16x32_bf16 v[2:5], v[186:189], v[222:225], v[2:5]
	v_mfma_f32_16x16x32_bf16 v[62:65], v[182:185], v[200:203], v[62:65]
	v_mfma_f32_16x16x32_bf16 v[58:61], v[190:193], v[200:203], v[58:61]
	v_mfma_f32_16x16x32_bf16 v[46:49], v[182:185], v[210:213], v[46:49]
	v_mfma_f32_16x16x32_bf16 v[38:41], v[190:193], v[210:213], v[38:41]
	v_mfma_f32_16x16x32_bf16 v[22:25], v[182:185], v[218:221], v[22:25]
	v_mfma_f32_16x16x32_bf16 v[18:21], v[190:193], v[218:221], v[18:21]
	v_mfma_f32_16x16x32_bf16 v[6:9], v[182:185], v[226:229], v[6:9]
	v_mfma_f32_16x16x32_bf16 v[2:5], v[190:193], v[226:229], v[2:5]
	s_setprio 0
	s_barrier
	s_add_i32 s64, 0, 0x18000
	s_add_i32 s65, 0, 0x1c000
	v_add_u32_e32 v174, s64, v131
	v_add_u32_e32 v190, s65, v131
	ds_read_b128 v[162:165], v174
	ds_read_b128 v[166:169], v174 offset:1024
	ds_read_b128 v[170:173], v174 offset:2048
	ds_read_b128 v[174:177], v174 offset:3072
	ds_read_b128 v[178:181], v190
	ds_read_b128 v[182:185], v190 offset:1024
	ds_read_b128 v[186:189], v190 offset:2048
	ds_read_b128 v[190:193], v190 offset:3072
	s_add_u32 s34, s34, 0x100000
	s_addc_u32 s35, s35, 0
	s_mov_b32 m0, s43
	v_lshl_add_u64 v[236:237], s[34:35], 0, v[134:135]
	ds_read_b128 v[196:199], v161 offset:32768
	ds_read_b128 v[200:203], v161 offset:33792
	ds_read_b128 v[206:209], v161 offset:34816
	ds_read_b128 v[210:213], v161 offset:35840
	ds_read_b128 v[214:217], v161 offset:36864
	ds_read_b128 v[218:221], v161 offset:37888
	ds_read_b128 v[222:225], v161 offset:38912
	ds_read_b128 v[226:229], v161 offset:39936
	global_load_lds_dwordx4 v[236:237], off
	v_lshl_add_u64 v[236:237], s[34:35], 0, v[132:133]
	s_mov_b32 m0, s45
	s_nop 0
	global_load_lds_dwordx4 v[236:237], off
	s_branch .Lal64_58
	s_nop 0
	s_nop 0
	s_nop 0
	s_nop 0
	s_nop 0
.Lal64_58:
	s_waitcnt vmcnt(8)
	s_waitcnt lgkmcnt(0)
	s_barrier
	s_setprio 1
	v_mfma_f32_16x16x32_bf16 v[126:129], v[162:165], v[196:199], v[126:129]
	v_mfma_f32_16x16x32_bf16 v[122:125], v[170:173], v[196:199], v[122:125]
	v_mfma_f32_16x16x32_bf16 v[118:121], v[162:165], v[206:209], v[118:121]
	v_mfma_f32_16x16x32_bf16 v[114:117], v[170:173], v[206:209], v[114:117]
	v_mfma_f32_16x16x32_bf16 v[102:105], v[162:165], v[214:217], v[102:105]
	v_mfma_f32_16x16x32_bf16 v[98:101], v[170:173], v[214:217], v[98:101]
	v_mfma_f32_16x16x32_bf16 v[42:45], v[162:165], v[222:225], v[42:45]
	v_mfma_f32_16x16x32_bf16 v[34:37], v[170:173], v[222:225], v[34:37]
	v_mfma_f32_16x16x32_bf16 v[126:129], v[166:169], v[200:203], v[126:129]
	v_mfma_f32_16x16x32_bf16 v[122:125], v[174:177], v[200:203], v[122:125]
	v_mfma_f32_16x16x32_bf16 v[118:121], v[166:169], v[210:213], v[118:121]
	v_mfma_f32_16x16x32_bf16 v[114:117], v[174:177], v[210:213], v[114:117]
	v_mfma_f32_16x16x32_bf16 v[102:105], v[166:169], v[218:221], v[102:105]
	v_mfma_f32_16x16x32_bf16 v[98:101], v[174:177], v[218:221], v[98:101]
	v_mfma_f32_16x16x32_bf16 v[42:45], v[166:169], v[226:229], v[42:45]
	v_mfma_f32_16x16x32_bf16 v[34:37], v[174:177], v[226:229], v[34:37]
	v_mfma_f32_16x16x32_bf16 v[110:113], v[178:181], v[196:199], v[110:113]
	v_mfma_f32_16x16x32_bf16 v[106:109], v[186:189], v[196:199], v[106:109]
	v_mfma_f32_16x16x32_bf16 v[94:97], v[178:181], v[206:209], v[94:97]
	v_mfma_f32_16x16x32_bf16 v[90:93], v[186:189], v[206:209], v[90:93]
	v_mfma_f32_16x16x32_bf16 v[86:89], v[178:181], v[214:217], v[86:89]
	v_mfma_f32_16x16x32_bf16 v[82:85], v[186:189], v[214:217], v[82:85]
	v_mfma_f32_16x16x32_bf16 v[30:33], v[178:181], v[222:225], v[30:33]
	v_mfma_f32_16x16x32_bf16 v[26:29], v[186:189], v[222:225], v[26:29]
	v_mfma_f32_16x16x32_bf16 v[110:113], v[182:185], v[200:203], v[110:113]
	v_mfma_f32_16x16x32_bf16 v[106:109], v[190:193], v[200:203], v[106:109]
	v_mfma_f32_16x16x32_bf16 v[94:97], v[182:185], v[210:213], v[94:97]
	v_mfma_f32_16x16x32_bf16 v[90:93], v[190:193], v[210:213], v[90:93]
	v_mfma_f32_16x16x32_bf16 v[86:89], v[182:185], v[218:221], v[86:89]
	v_mfma_f32_16x16x32_bf16 v[82:85], v[190:193], v[218:221], v[82:85]
	v_mfma_f32_16x16x32_bf16 v[30:33], v[182:185], v[226:229], v[30:33]
	v_mfma_f32_16x16x32_bf16 v[26:29], v[190:193], v[226:229], v[26:29]
	s_setprio 0
	s_barrier
	s_add_i32 s34, s64, s40
	v_lshl_add_u64 v[158:159], v[158:159], 0, s[10:11]
	s_mov_b32 m0, s34
	ds_read_b128 v[196:199], v161 offset:49152
	ds_read_b128 v[200:203], v161 offset:50176
	ds_read_b128 v[206:209], v161 offset:51200
	ds_read_b128 v[210:213], v161 offset:52224
	ds_read_b128 v[214:217], v161 offset:53248
	ds_read_b128 v[218:221], v161 offset:54272
	ds_read_b128 v[222:225], v161 offset:55296
	ds_read_b128 v[226:229], v161 offset:56320
	global_load_lds_dwordx4 v[158:159], off
	s_add_i32 m0, s34, 0x2000
	s_add_u32 s30, s30, 0x100080
	v_lshl_add_u64 v[158:159], v[230:231], 0, s[10:11]
	s_addc_u32 s31, s31, 0
	s_add_i32 s34, s65, s40
	global_load_lds_dwordx4 v[158:159], off
	v_lshl_add_u64 v[158:159], s[30:31], 0, v[134:135]
	s_mov_b32 m0, s34
	s_nop 0
	global_load_lds_dwordx4 v[158:159], off
	v_lshl_add_u64 v[158:159], s[30:31], 0, v[132:133]
	s_add_i32 m0, s34, 0x2000
	s_nop 0
	global_load_lds_dwordx4 v[158:159], off
	v_lshl_add_u64 v[158:159], v[232:233], 0, s[10:11]
	s_mov_b32 m0, s50
	s_nop 0
	global_load_lds_dwordx4 v[158:159], off
	v_lshl_add_u64 v[158:159], v[234:235], 0, s[10:11]
	s_mov_b32 m0, s51
	s_nop 0
	global_load_lds_dwordx4 v[158:159], off
	s_branch .Lal64_59
.Lal64_59:
	s_waitcnt vmcnt(8)
	s_waitcnt lgkmcnt(0)
	s_barrier
	s_setprio 1
	v_mfma_f32_16x16x32_bf16 v[78:81], v[162:165], v[196:199], v[78:81]
	v_mfma_f32_16x16x32_bf16 v[74:77], v[170:173], v[196:199], v[74:77]
	v_mfma_f32_16x16x32_bf16 v[70:73], v[162:165], v[206:209], v[70:73]
	v_mfma_f32_16x16x32_bf16 v[66:69], v[170:173], v[206:209], v[66:69]
	v_mfma_f32_16x16x32_bf16 v[54:57], v[162:165], v[214:217], v[54:57]
	v_mfma_f32_16x16x32_bf16 v[50:53], v[170:173], v[214:217], v[50:53]
	v_mfma_f32_16x16x32_bf16 v[14:17], v[162:165], v[222:225], v[14:17]
	v_mfma_f32_16x16x32_bf16 v[10:13], v[170:173], v[222:225], v[10:13]
	v_mfma_f32_16x16x32_bf16 v[78:81], v[166:169], v[200:203], v[78:81]
	v_mfma_f32_16x16x32_bf16 v[74:77], v[174:177], v[200:203], v[74:77]
	v_mfma_f32_16x16x32_bf16 v[70:73], v[166:169], v[210:213], v[70:73]
	v_mfma_f32_16x16x32_bf16 v[66:69], v[174:177], v[210:213], v[66:69]
	v_mfma_f32_16x16x32_bf16 v[54:57], v[166:169], v[218:221], v[54:57]
	v_mfma_f32_16x16x32_bf16 v[50:53], v[174:177], v[218:221], v[50:53]
	v_mfma_f32_16x16x32_bf16 v[14:17], v[166:169], v[226:229], v[14:17]
	v_mfma_f32_16x16x32_bf16 v[10:13], v[174:177], v[226:229], v[10:13]
	v_mfma_f32_16x16x32_bf16 v[62:65], v[178:181], v[196:199], v[62:65]
	v_mfma_f32_16x16x32_bf16 v[58:61], v[186:189], v[196:199], v[58:61]
	v_mfma_f32_16x16x32_bf16 v[46:49], v[178:181], v[206:209], v[46:49]
	v_mfma_f32_16x16x32_bf16 v[38:41], v[186:189], v[206:209], v[38:41]
	v_mfma_f32_16x16x32_bf16 v[22:25], v[178:181], v[214:217], v[22:25]
	v_mfma_f32_16x16x32_bf16 v[18:21], v[186:189], v[214:217], v[18:21]
	v_mfma_f32_16x16x32_bf16 v[6:9], v[178:181], v[222:225], v[6:9]
	v_mfma_f32_16x16x32_bf16 v[2:5], v[186:189], v[222:225], v[2:5]
	v_mfma_f32_16x16x32_bf16 v[62:65], v[182:185], v[200:203], v[62:65]
	v_mfma_f32_16x16x32_bf16 v[58:61], v[190:193], v[200:203], v[58:61]
	v_mfma_f32_16x16x32_bf16 v[46:49], v[182:185], v[210:213], v[46:49]
	v_mfma_f32_16x16x32_bf16 v[38:41], v[190:193], v[210:213], v[38:41]
	v_mfma_f32_16x16x32_bf16 v[22:25], v[182:185], v[218:221], v[22:25]
	v_mfma_f32_16x16x32_bf16 v[18:21], v[190:193], v[218:221], v[18:21]
	v_mfma_f32_16x16x32_bf16 v[6:9], v[182:185], v[226:229], v[6:9]
	v_mfma_f32_16x16x32_bf16 v[2:5], v[190:193], v[226:229], v[2:5]
	s_setprio 0
	s_barrier
	s_add_u32 s28, s28, 0x100
	s_addc_u32 s29, s29, 0
	s_add_u32 s61, s61, 0x100
	s_addc_u32 s62, s62, 0
	s_cmp_ge_i32 s63, s58
	s_mov_b32 s30, s63
	s_cbranch_scc0 .LBB0_3789
	s_and_b64 vcc, exec, s[16:17]
	s_cbranch_vccz .LBB0_3792
	s_barrier

.LBB0_3983:
	ds_read_b128 v[152:155], v160
	ds_read_b128 v[164:167], v160 offset:1024
	ds_read_b128 v[168:171], v160 offset:2048
	ds_read_b128 v[172:175], v160 offset:3072
	ds_read_b128 v[176:179], v161
	ds_read_b128 v[180:183], v161 offset:1024
	ds_read_b128 v[184:187], v161 offset:2048
	ds_read_b128 v[188:191], v161 offset:3072
	s_add_i32 s80, s48, 2
	s_add_u32 s49, s58, 0xfffe0080
	s_addc_u32 s60, s59, -1
	s_cmp_eq_u32 s43, s48
	s_cselect_b32 s48, s52, s47
	s_cselect_b32 s61, s5, s60
	s_cselect_b32 s60, s4, s49
	s_cselect_b32 s49, s53, s51
	v_lshl_add_u64 v[156:157], s[58:59], 0, v[140:141]
	s_add_i32 m0, s55, 0xc000
	ds_read_b128 v[196:199], v162
	ds_read_b128 v[200:203], v162 offset:1024
	ds_read_b128 v[204:207], v162 offset:2048
	ds_read_b128 v[208:211], v162 offset:3072
	ds_read_b128 v[212:215], v162 offset:4096
	ds_read_b128 v[216:219], v162 offset:5120
	ds_read_b128 v[220:223], v162 offset:6144
	ds_read_b128 v[224:227], v162 offset:7168
	global_load_lds_dwordx4 v[156:157], off
	v_lshl_add_u64 v[156:157], s[58:59], 0, v[142:143]
	s_add_i32 m0, s55, 0xe000
	s_nop 0
	global_load_lds_dwordx4 v[156:157], off
	s_branch .Lal64_60
	s_nop 0
	s_nop 0
	s_nop 0
	s_nop 0
	s_nop 0
	s_nop 0
	s_nop 0
	s_nop 0
	s_nop 0
	s_nop 0
	s_nop 0
.Lal64_60:
	s_waitcnt vmcnt(8)
	s_waitcnt lgkmcnt(0)
	s_barrier
	s_setprio 1
	v_mfma_f32_16x16x32_bf16 v[126:129], v[152:155], v[196:199], v[126:129]
	v_mfma_f32_16x16x32_bf16 v[122:125], v[168:171], v[196:199], v[122:125]
	v_mfma_f32_16x16x32_bf16 v[110:113], v[152:155], v[204:207], v[110:113]
	v_mfma_f32_16x16x32_bf16 v[106:109], v[168:171], v[204:207], v[106:109]
	v_mfma_f32_16x16x32_bf16 v[94:97], v[152:155], v[212:215], v[94:97]
	v_mfma_f32_16x16x32_bf16 v[90:93], v[168:171], v[212:215], v[90:93]
	v_mfma_f32_16x16x32_bf16 v[78:81], v[152:155], v[220:223], v[78:81]
	v_mfma_f32_16x16x32_bf16 v[74:77], v[168:171], v[220:223], v[74:77]
	v_mfma_f32_16x16x32_bf16 v[126:129], v[164:167], v[200:203], v[126:129]
	v_mfma_f32_16x16x32_bf16 v[122:125], v[172:175], v[200:203], v[122:125]
	v_mfma_f32_16x16x32_bf16 v[110:113], v[164:167], v[208:211], v[110:113]
	v_mfma_f32_16x16x32_bf16 v[106:109], v[172:175], v[208:211], v[106:109]
	v_mfma_f32_16x16x32_bf16 v[94:97], v[164:167], v[216:219], v[94:97]
	v_mfma_f32_16x16x32_bf16 v[90:93], v[172:175], v[216:219], v[90:93]
	v_mfma_f32_16x16x32_bf16 v[78:81], v[164:167], v[224:227], v[78:81]
	v_mfma_f32_16x16x32_bf16 v[74:77], v[172:175], v[224:227], v[74:77]
	v_mfma_f32_16x16x32_bf16 v[118:121], v[176:179], v[196:199], v[118:121]
	v_mfma_f32_16x16x32_bf16 v[114:117], v[184:187], v[196:199], v[114:117]
	v_mfma_f32_16x16x32_bf16 v[102:105], v[176:179], v[204:207], v[102:105]
	v_mfma_f32_16x16x32_bf16 v[98:101], v[184:187], v[204:207], v[98:101]
	v_mfma_f32_16x16x32_bf16 v[86:89], v[176:179], v[212:215], v[86:89]
	v_mfma_f32_16x16x32_bf16 v[82:85], v[184:187], v[212:215], v[82:85]
	v_mfma_f32_16x16x32_bf16 v[70:73], v[176:179], v[220:223], v[70:73]
	v_mfma_f32_16x16x32_bf16 v[66:69], v[184:187], v[220:223], v[66:69]
	v_mfma_f32_16x16x32_bf16 v[118:121], v[180:183], v[200:203], v[118:121]
	v_mfma_f32_16x16x32_bf16 v[114:117], v[188:191], v[200:203], v[114:117]
	v_mfma_f32_16x16x32_bf16 v[102:105], v[180:183], v[208:211], v[102:105]
	v_mfma_f32_16x16x32_bf16 v[98:101], v[188:191], v[208:211], v[98:101]
	v_mfma_f32_16x16x32_bf16 v[86:89], v[180:183], v[216:219], v[86:89]
	v_mfma_f32_16x16x32_bf16 v[82:85], v[188:191], v[216:219], v[82:85]
	v_mfma_f32_16x16x32_bf16 v[70:73], v[180:183], v[224:227], v[70:73]
	v_mfma_f32_16x16x32_bf16 v[66:69], v[188:191], v[224:227], v[66:69]
	s_setprio 0
	s_barrier
	s_add_i32 s81, s71, s62
	v_lshl_add_u64 v[156:157], s[48:49], 0, v[134:135]
	s_mov_b32 m0, s81
	ds_read_b128 v[196:199], v162 offset:16384
	ds_read_b128 v[200:203], v162 offset:17408
	ds_read_b128 v[204:207], v162 offset:18432
	ds_read_b128 v[208:211], v162 offset:19456
	ds_read_b128 v[212:215], v162 offset:20480
	ds_read_b128 v[216:219], v162 offset:21504
	ds_read_b128 v[220:223], v162 offset:22528
	ds_read_b128 v[224:227], v162 offset:23552
	global_load_lds_dwordx4 v[156:157], off
	s_add_i32 m0, s81, 0x2000
	s_add_u32 s82, s48, 0x20000
	v_lshl_add_u64 v[192:193], s[48:49], 0, v[138:139]
	s_addc_u32 s83, s49, 0
	s_add_i32 s81, s72, s62
	global_load_lds_dwordx4 v[192:193], off
	v_lshl_add_u64 v[228:229], s[82:83], 0, v[134:135]
	s_mov_b32 m0, s81
	v_lshl_add_u64 v[230:231], s[60:61], 0, v[136:137]
	global_load_lds_dwordx4 v[228:229], off
	v_lshl_add_u64 v[228:229], s[82:83], 0, v[138:139]
	s_add_i32 m0, s81, 0x2000
	s_nop 0
	global_load_lds_dwordx4 v[228:229], off
	v_lshl_add_u64 v[228:229], s[60:61], 0, v[132:133]
	s_mov_b32 m0, s55
	s_nop 0
	global_load_lds_dwordx4 v[228:229], off
	s_mov_b32 m0, s57
	s_nop 0
	global_load_lds_dwordx4 v[230:231], off
	s_branch .Lal64_61
	s_nop 0
.Lal64_61:
	s_waitcnt vmcnt(8)
	s_waitcnt lgkmcnt(0)
	s_barrier
	s_setprio 1
	v_mfma_f32_16x16x32_bf16 v[62:65], v[152:155], v[196:199], v[62:65]
	v_mfma_f32_16x16x32_bf16 v[58:61], v[168:171], v[196:199], v[58:61]
	v_mfma_f32_16x16x32_bf16 v[46:49], v[152:155], v[204:207], v[46:49]
	v_mfma_f32_16x16x32_bf16 v[42:45], v[168:171], v[204:207], v[42:45]
	v_mfma_f32_16x16x32_bf16 v[30:33], v[152:155], v[212:215], v[30:33]
	v_mfma_f32_16x16x32_bf16 v[26:29], v[168:171], v[212:215], v[26:29]
	v_mfma_f32_16x16x32_bf16 v[14:17], v[152:155], v[220:223], v[14:17]
	v_mfma_f32_16x16x32_bf16 v[10:13], v[168:171], v[220:223], v[10:13]
	v_mfma_f32_16x16x32_bf16 v[62:65], v[164:167], v[200:203], v[62:65]
	v_mfma_f32_16x16x32_bf16 v[58:61], v[172:175], v[200:203], v[58:61]
	v_mfma_f32_16x16x32_bf16 v[46:49], v[164:167], v[208:211], v[46:49]
	v_mfma_f32_16x16x32_bf16 v[42:45], v[172:175], v[208:211], v[42:45]
	v_mfma_f32_16x16x32_bf16 v[30:33], v[164:167], v[216:219], v[30:33]
	v_mfma_f32_16x16x32_bf16 v[26:29], v[172:175], v[216:219], v[26:29]
	v_mfma_f32_16x16x32_bf16 v[14:17], v[164:167], v[224:227], v[14:17]
	v_mfma_f32_16x16x32_bf16 v[10:13], v[172:175], v[224:227], v[10:13]
	v_mfma_f32_16x16x32_bf16 v[54:57], v[176:179], v[196:199], v[54:57]
	v_mfma_f32_16x16x32_bf16 v[50:53], v[184:187], v[196:199], v[50:53]
	v_mfma_f32_16x16x32_bf16 v[38:41], v[176:179], v[204:207], v[38:41]
	v_mfma_f32_16x16x32_bf16 v[34:37], v[184:187], v[204:207], v[34:37]
	v_mfma_f32_16x16x32_bf16 v[22:25], v[176:179], v[212:215], v[22:25]
	v_mfma_f32_16x16x32_bf16 v[18:21], v[184:187], v[212:215], v[18:21]
	v_mfma_f32_16x16x32_bf16 v[6:9], v[176:179], v[220:223], v[6:9]
	v_mfma_f32_16x16x32_bf16 v[2:5], v[184:187], v[220:223], v[2:5]
	v_mfma_f32_16x16x32_bf16 v[54:57], v[180:183], v[200:203], v[54:57]
	v_mfma_f32_16x16x32_bf16 v[50:53], v[188:191], v[200:203], v[50:53]
	v_mfma_f32_16x16x32_bf16 v[38:41], v[180:183], v[208:211], v[38:41]
	v_mfma_f32_16x16x32_bf16 v[34:37], v[188:191], v[208:211], v[34:37]
	v_mfma_f32_16x16x32_bf16 v[22:25], v[180:183], v[216:219], v[22:25]
	v_mfma_f32_16x16x32_bf16 v[18:21], v[188:191], v[216:219], v[18:21]
	v_mfma_f32_16x16x32_bf16 v[6:9], v[180:183], v[224:227], v[6:9]
	v_mfma_f32_16x16x32_bf16 v[2:5], v[188:191], v[224:227], v[2:5]
	s_setprio 0
	s_barrier
	s_add_i32 s81, 0, 0x18000
	v_add_u32_e32 v163, s81, v158
	s_add_i32 s82, 0, 0x1c000
	ds_read_b128 v[152:155], v163
	ds_read_b128 v[164:167], v163 offset:1024
	ds_read_b128 v[168:171], v163 offset:2048
	ds_read_b128 v[172:175], v163 offset:3072
	v_add_u32_e32 v163, s82, v158
	ds_read_b128 v[176:179], v163
	ds_read_b128 v[180:183], v163 offset:1024
	ds_read_b128 v[184:187], v163 offset:2048
	ds_read_b128 v[188:191], v163 offset:3072
	s_add_u32 s60, s60, 0x20000
	s_addc_u32 s61, s61, 0
	s_mov_b32 m0, s63
	v_lshl_add_u64 v[232:233], s[60:61], 0, v[132:133]
	ds_read_b128 v[196:199], v162 offset:32768
	ds_read_b128 v[200:203], v162 offset:33792
	ds_read_b128 v[204:207], v162 offset:34816
	ds_read_b128 v[208:211], v162 offset:35840
	ds_read_b128 v[212:215], v162 offset:36864
	ds_read_b128 v[216:219], v162 offset:37888
	ds_read_b128 v[220:223], v162 offset:38912
	ds_read_b128 v[224:227], v162 offset:39936
	global_load_lds_dwordx4 v[232:233], off
	v_lshl_add_u64 v[232:233], s[60:61], 0, v[136:137]
	s_mov_b32 m0, s64
	s_nop 0
	global_load_lds_dwordx4 v[232:233], off
	s_branch .Lal64_62
	s_nop 0
	s_nop 0
	s_nop 0
	s_nop 0
	s_nop 0
.Lal64_62:
	s_waitcnt vmcnt(8)
	s_waitcnt lgkmcnt(0)
	s_barrier
	s_setprio 1
	v_mfma_f32_16x16x32_bf16 v[126:129], v[152:155], v[196:199], v[126:129]
	v_mfma_f32_16x16x32_bf16 v[122:125], v[168:171], v[196:199], v[122:125]
	v_mfma_f32_16x16x32_bf16 v[110:113], v[152:155], v[204:207], v[110:113]
	v_mfma_f32_16x16x32_bf16 v[106:109], v[168:171], v[204:207], v[106:109]
	v_mfma_f32_16x16x32_bf16 v[94:97], v[152:155], v[212:215], v[94:97]
	v_mfma_f32_16x16x32_bf16 v[90:93], v[168:171], v[212:215], v[90:93]
	v_mfma_f32_16x16x32_bf16 v[78:81], v[152:155], v[220:223], v[78:81]
	v_mfma_f32_16x16x32_bf16 v[74:77], v[168:171], v[220:223], v[74:77]
	v_mfma_f32_16x16x32_bf16 v[126:129], v[164:167], v[200:203], v[126:129]
	v_mfma_f32_16x16x32_bf16 v[122:125], v[172:175], v[200:203], v[122:125]
	v_mfma_f32_16x16x32_bf16 v[110:113], v[164:167], v[208:211], v[110:113]
	v_mfma_f32_16x16x32_bf16 v[106:109], v[172:175], v[208:211], v[106:109]
	v_mfma_f32_16x16x32_bf16 v[94:97], v[164:167], v[216:219], v[94:97]
	v_mfma_f32_16x16x32_bf16 v[90:93], v[172:175], v[216:219], v[90:93]
	v_mfma_f32_16x16x32_bf16 v[78:81], v[164:167], v[224:227], v[78:81]
	v_mfma_f32_16x16x32_bf16 v[74:77], v[172:175], v[224:227], v[74:77]
	v_mfma_f32_16x16x32_bf16 v[118:121], v[176:179], v[196:199], v[118:121]
	v_mfma_f32_16x16x32_bf16 v[114:117], v[184:187], v[196:199], v[114:117]
	v_mfma_f32_16x16x32_bf16 v[102:105], v[176:179], v[204:207], v[102:105]
	v_mfma_f32_16x16x32_bf16 v[98:101], v[184:187], v[204:207], v[98:101]
	v_mfma_f32_16x16x32_bf16 v[86:89], v[176:179], v[212:215], v[86:89]
	v_mfma_f32_16x16x32_bf16 v[82:85], v[184:187], v[212:215], v[82:85]
	v_mfma_f32_16x16x32_bf16 v[70:73], v[176:179], v[220:223], v[70:73]
	v_mfma_f32_16x16x32_bf16 v[66:69], v[184:187], v[220:223], v[66:69]
	v_mfma_f32_16x16x32_bf16 v[118:121], v[180:183], v[200:203], v[118:121]
	v_mfma_f32_16x16x32_bf16 v[114:117], v[188:191], v[200:203], v[114:117]
	v_mfma_f32_16x16x32_bf16 v[102:105], v[180:183], v[208:211], v[102:105]
	v_mfma_f32_16x16x32_bf16 v[98:101], v[188:191], v[208:211], v[98:101]
	v_mfma_f32_16x16x32_bf16 v[86:89], v[180:183], v[216:219], v[86:89]
	v_mfma_f32_16x16x32_bf16 v[82:85], v[188:191], v[216:219], v[82:85]
	v_mfma_f32_16x16x32_bf16 v[70:73], v[180:183], v[224:227], v[70:73]
	v_mfma_f32_16x16x32_bf16 v[66:69], v[188:191], v[224:227], v[66:69]
	s_setprio 0
	s_barrier
	s_add_i32 s60, s81, s62
	v_lshl_add_u64 v[156:157], v[156:157], 0, s[14:15]
	s_mov_b32 m0, s60
	ds_read_b128 v[196:199], v162 offset:49152
	ds_read_b128 v[200:203], v162 offset:50176
	ds_read_b128 v[204:207], v162 offset:51200
	ds_read_b128 v[208:211], v162 offset:52224
	ds_read_b128 v[212:215], v162 offset:53248
	ds_read_b128 v[216:219], v162 offset:54272
	ds_read_b128 v[220:223], v162 offset:55296
	ds_read_b128 v[224:227], v162 offset:56320
	global_load_lds_dwordx4 v[156:157], off
	s_add_i32 m0, s60, 0x2000
	s_add_u32 s48, s48, 0x20080
	v_lshl_add_u64 v[156:157], v[192:193], 0, s[14:15]
	s_addc_u32 s49, s49, 0
	s_add_i32 s60, s82, s62
	global_load_lds_dwordx4 v[156:157], off
	v_lshl_add_u64 v[156:157], s[48:49], 0, v[134:135]
	s_mov_b32 m0, s60
	s_nop 0
	global_load_lds_dwordx4 v[156:157], off
	v_lshl_add_u64 v[156:157], s[48:49], 0, v[138:139]
	s_add_i32 m0, s60, 0x2000
	s_nop 0
	global_load_lds_dwordx4 v[156:157], off
	v_lshl_add_u64 v[156:157], v[228:229], 0, s[14:15]
	s_mov_b32 m0, s68
	s_nop 0
	global_load_lds_dwordx4 v[156:157], off
	v_lshl_add_u64 v[156:157], v[230:231], 0, s[14:15]
	s_mov_b32 m0, s69
	s_nop 0
	global_load_lds_dwordx4 v[156:157], off
	s_branch .Lal64_63
.Lal64_63:
	s_waitcnt vmcnt(8)
	s_waitcnt lgkmcnt(0)
	s_barrier
	s_setprio 1
	v_mfma_f32_16x16x32_bf16 v[62:65], v[152:155], v[196:199], v[62:65]
	v_mfma_f32_16x16x32_bf16 v[58:61], v[168:171], v[196:199], v[58:61]
	v_mfma_f32_16x16x32_bf16 v[46:49], v[152:155], v[204:207], v[46:49]
	v_mfma_f32_16x16x32_bf16 v[42:45], v[168:171], v[204:207], v[42:45]
	v_mfma_f32_16x16x32_bf16 v[30:33], v[152:155], v[212:215], v[30:33]
	v_mfma_f32_16x16x32_bf16 v[26:29], v[168:171], v[212:215], v[26:29]
	v_mfma_f32_16x16x32_bf16 v[14:17], v[152:155], v[220:223], v[14:17]
	v_mfma_f32_16x16x32_bf16 v[10:13], v[168:171], v[220:223], v[10:13]
	v_mfma_f32_16x16x32_bf16 v[62:65], v[164:167], v[200:203], v[62:65]
	v_mfma_f32_16x16x32_bf16 v[58:61], v[172:175], v[200:203], v[58:61]
	v_mfma_f32_16x16x32_bf16 v[46:49], v[164:167], v[208:211], v[46:49]
	v_mfma_f32_16x16x32_bf16 v[42:45], v[172:175], v[208:211], v[42:45]
	v_mfma_f32_16x16x32_bf16 v[30:33], v[164:167], v[216:219], v[30:33]
	v_mfma_f32_16x16x32_bf16 v[26:29], v[172:175], v[216:219], v[26:29]
	v_mfma_f32_16x16x32_bf16 v[14:17], v[164:167], v[224:227], v[14:17]
	v_mfma_f32_16x16x32_bf16 v[10:13], v[172:175], v[224:227], v[10:13]
	v_mfma_f32_16x16x32_bf16 v[54:57], v[176:179], v[196:199], v[54:57]
	v_mfma_f32_16x16x32_bf16 v[50:53], v[184:187], v[196:199], v[50:53]
	v_mfma_f32_16x16x32_bf16 v[38:41], v[176:179], v[204:207], v[38:41]
	v_mfma_f32_16x16x32_bf16 v[34:37], v[184:187], v[204:207], v[34:37]
	v_mfma_f32_16x16x32_bf16 v[22:25], v[176:179], v[212:215], v[22:25]
	v_mfma_f32_16x16x32_bf16 v[18:21], v[184:187], v[212:215], v[18:21]
	v_mfma_f32_16x16x32_bf16 v[6:9], v[176:179], v[220:223], v[6:9]
	v_mfma_f32_16x16x32_bf16 v[2:5], v[184:187], v[220:223], v[2:5]
	v_mfma_f32_16x16x32_bf16 v[54:57], v[180:183], v[200:203], v[54:57]
	v_mfma_f32_16x16x32_bf16 v[50:53], v[188:191], v[200:203], v[50:53]
	v_mfma_f32_16x16x32_bf16 v[38:41], v[180:183], v[208:211], v[38:41]
	v_mfma_f32_16x16x32_bf16 v[34:37], v[188:191], v[208:211], v[34:37]
	v_mfma_f32_16x16x32_bf16 v[22:25], v[180:183], v[216:219], v[22:25]
	v_mfma_f32_16x16x32_bf16 v[18:21], v[188:191], v[216:219], v[18:21]
	v_mfma_f32_16x16x32_bf16 v[6:9], v[180:183], v[224:227], v[6:9]
	v_mfma_f32_16x16x32_bf16 v[2:5], v[188:191], v[224:227], v[2:5]
	s_setprio 0
	s_barrier
	s_add_u32 s58, s58, 0x100
	s_addc_u32 s59, s59, 0
	s_add_u32 s47, s47, 0x100
	s_addc_u32 s51, s51, 0
	s_cmp_ge_i32 s80, s79
	s_mov_b32 s48, s80
	s_cbranch_scc0 .LBB0_3983
	s_and_b64 vcc, exec, s[16:17]
	s_cbranch_vccz .LBB0_3986
	s_barrier

.LBB0_4145:
	ds_read_b128 v[156:159], v162
	ds_read_b128 v[166:169], v162 offset:1024
	ds_read_b128 v[170:173], v162 offset:2048
	ds_read_b128 v[174:177], v162 offset:3072
	ds_read_b128 v[178:181], v163
	ds_read_b128 v[182:185], v163 offset:1024
	ds_read_b128 v[186:189], v163 offset:2048
	ds_read_b128 v[190:193], v163 offset:3072
	s_add_i32 s72, s42, 2
	s_add_u32 s43, s40, 0xfff00080
	s_addc_u32 s46, s41, -1
	s_cmp_eq_u32 s69, s42
	s_cselect_b32 s42, s25, s70
	s_cselect_b32 s47, s5, s46
	s_cselect_b32 s46, s23, s43
	s_cselect_b32 s43, s21, s71
	v_lshl_add_u64 v[228:229], s[40:41], 0, v[148:149]
	s_add_i32 m0, s35, 0xc000
	ds_read_b128 v[196:199], v164
	ds_read_b128 v[200:203], v164 offset:1024
	ds_read_b128 v[204:207], v164 offset:2048
	ds_read_b128 v[208:211], v164 offset:3072
	ds_read_b128 v[212:215], v164 offset:4096
	ds_read_b128 v[216:219], v164 offset:5120
	ds_read_b128 v[220:223], v164 offset:6144
	ds_read_b128 v[224:227], v164 offset:7168
	global_load_lds_dwordx4 v[228:229], off
	v_lshl_add_u64 v[228:229], s[40:41], 0, v[150:151]
	s_add_i32 m0, s35, 0xe000
	s_nop 0
	global_load_lds_dwordx4 v[228:229], off
	s_branch .Lal64_64
	s_nop 0
	s_nop 0
	s_nop 0
	s_nop 0
	s_nop 0
	s_nop 0
	s_nop 0
	s_nop 0
.Lal64_64:
	s_waitcnt vmcnt(8)
	s_waitcnt lgkmcnt(0)
	s_barrier
	s_setprio 1
	v_mfma_f32_16x16x32_bf16 v[78:81], v[156:159], v[196:199], v[78:81]
	v_mfma_f32_16x16x32_bf16 v[74:77], v[170:173], v[196:199], v[74:77]
	v_mfma_f32_16x16x32_bf16 v[70:73], v[156:159], v[204:207], v[70:73]
	v_mfma_f32_16x16x32_bf16 v[62:65], v[170:173], v[204:207], v[62:65]
	v_mfma_f32_16x16x32_bf16 v[58:61], v[156:159], v[212:215], v[58:61]
	v_mfma_f32_16x16x32_bf16 v[54:57], v[170:173], v[212:215], v[54:57]
	v_mfma_f32_16x16x32_bf16 v[46:49], v[156:159], v[220:223], v[46:49]
	v_mfma_f32_16x16x32_bf16 v[38:41], v[170:173], v[220:223], v[38:41]
	v_mfma_f32_16x16x32_bf16 v[78:81], v[166:169], v[200:203], v[78:81]
	v_mfma_f32_16x16x32_bf16 v[74:77], v[174:177], v[200:203], v[74:77]
	v_mfma_f32_16x16x32_bf16 v[70:73], v[166:169], v[208:211], v[70:73]
	v_mfma_f32_16x16x32_bf16 v[62:65], v[174:177], v[208:211], v[62:65]
	v_mfma_f32_16x16x32_bf16 v[58:61], v[166:169], v[216:219], v[58:61]
	v_mfma_f32_16x16x32_bf16 v[54:57], v[174:177], v[216:219], v[54:57]
	v_mfma_f32_16x16x32_bf16 v[46:49], v[166:169], v[224:227], v[46:49]
	v_mfma_f32_16x16x32_bf16 v[38:41], v[174:177], v[224:227], v[38:41]
	v_mfma_f32_16x16x32_bf16 v[50:53], v[178:181], v[196:199], v[50:53]
	v_mfma_f32_16x16x32_bf16 v[42:45], v[186:189], v[196:199], v[42:45]
	v_mfma_f32_16x16x32_bf16 v[34:37], v[178:181], v[204:207], v[34:37]
	v_mfma_f32_16x16x32_bf16 v[26:29], v[186:189], v[204:207], v[26:29]
	v_mfma_f32_16x16x32_bf16 v[18:21], v[178:181], v[212:215], v[18:21]
	v_mfma_f32_16x16x32_bf16 v[14:17], v[186:189], v[212:215], v[14:17]
	v_mfma_f32_16x16x32_bf16 v[10:13], v[178:181], v[220:223], v[10:13]
	v_mfma_f32_16x16x32_bf16 v[6:9], v[186:189], v[220:223], v[6:9]
	v_mfma_f32_16x16x32_bf16 v[50:53], v[182:185], v[200:203], v[50:53]
	v_mfma_f32_16x16x32_bf16 v[42:45], v[190:193], v[200:203], v[42:45]
	v_mfma_f32_16x16x32_bf16 v[34:37], v[182:185], v[208:211], v[34:37]
	v_mfma_f32_16x16x32_bf16 v[26:29], v[190:193], v[208:211], v[26:29]
	v_mfma_f32_16x16x32_bf16 v[18:21], v[182:185], v[216:219], v[18:21]
	v_mfma_f32_16x16x32_bf16 v[14:17], v[190:193], v[216:219], v[14:17]
	v_mfma_f32_16x16x32_bf16 v[10:13], v[182:185], v[224:227], v[10:13]
	v_mfma_f32_16x16x32_bf16 v[6:9], v[190:193], v[224:227], v[6:9]
	s_setprio 0
	s_barrier
	s_add_i32 s73, s62, s49
	v_lshl_add_u64 v[228:229], s[42:43], 0, v[134:135]
	s_mov_b32 m0, s73
	ds_read_b128 v[196:199], v164 offset:16384
	ds_read_b128 v[200:203], v164 offset:17408
	ds_read_b128 v[204:207], v164 offset:18432
	ds_read_b128 v[208:211], v164 offset:19456
	ds_read_b128 v[212:215], v164 offset:20480
	ds_read_b128 v[216:219], v164 offset:21504
	ds_read_b128 v[220:223], v164 offset:22528
	ds_read_b128 v[224:227], v164 offset:23552
	global_load_lds_dwordx4 v[228:229], off
	s_add_i32 m0, s73, 0x2000
	s_add_u32 s74, s42, 0x100000
	v_lshl_add_u64 v[230:231], s[42:43], 0, v[138:139]
	s_addc_u32 s75, s43, 0
	s_add_i32 s73, s63, s49
	global_load_lds_dwordx4 v[230:231], off
	v_lshl_add_u64 v[232:233], s[74:75], 0, v[134:135]
	s_mov_b32 m0, s73
	v_lshl_add_u64 v[234:235], s[46:47], 0, v[136:137]
	global_load_lds_dwordx4 v[232:233], off
	v_lshl_add_u64 v[232:233], s[74:75], 0, v[138:139]
	s_add_i32 m0, s73, 0x2000
	s_nop 0
	global_load_lds_dwordx4 v[232:233], off
	v_lshl_add_u64 v[232:233], s[46:47], 0, v[132:133]
	s_mov_b32 m0, s35
	s_nop 0
	global_load_lds_dwordx4 v[232:233], off
	s_mov_b32 m0, s50
	s_nop 0
	global_load_lds_dwordx4 v[234:235], off
	s_branch .Lal64_65
	s_nop 0
.Lal64_65:
	s_waitcnt vmcnt(8)
	s_waitcnt lgkmcnt(0)
	s_barrier
	s_setprio 1
	v_mfma_f32_16x16x32_bf16 v[126:129], v[156:159], v[196:199], v[126:129]
	v_mfma_f32_16x16x32_bf16 v[118:121], v[170:173], v[196:199], v[118:121]
	v_mfma_f32_16x16x32_bf16 v[110:113], v[156:159], v[204:207], v[110:113]
	v_mfma_f32_16x16x32_bf16 v[102:105], v[170:173], v[204:207], v[102:105]
	v_mfma_f32_16x16x32_bf16 v[94:97], v[156:159], v[212:215], v[94:97]
	v_mfma_f32_16x16x32_bf16 v[86:89], v[170:173], v[212:215], v[86:89]
	v_mfma_f32_16x16x32_bf16 v[66:69], v[156:159], v[220:223], v[66:69]
	v_mfma_f32_16x16x32_bf16 v[22:25], v[170:173], v[220:223], v[22:25]
	v_mfma_f32_16x16x32_bf16 v[126:129], v[166:169], v[200:203], v[126:129]
	v_mfma_f32_16x16x32_bf16 v[118:121], v[174:177], v[200:203], v[118:121]
	v_mfma_f32_16x16x32_bf16 v[110:113], v[166:169], v[208:211], v[110:113]
	v_mfma_f32_16x16x32_bf16 v[102:105], v[174:177], v[208:211], v[102:105]
	v_mfma_f32_16x16x32_bf16 v[94:97], v[166:169], v[216:219], v[94:97]
	v_mfma_f32_16x16x32_bf16 v[86:89], v[174:177], v[216:219], v[86:89]
	v_mfma_f32_16x16x32_bf16 v[66:69], v[166:169], v[224:227], v[66:69]
	v_mfma_f32_16x16x32_bf16 v[22:25], v[174:177], v[224:227], v[22:25]
	v_mfma_f32_16x16x32_bf16 v[122:125], v[178:181], v[196:199], v[122:125]
	v_mfma_f32_16x16x32_bf16 v[114:117], v[186:189], v[196:199], v[114:117]
	v_mfma_f32_16x16x32_bf16 v[106:109], v[178:181], v[204:207], v[106:109]
	v_mfma_f32_16x16x32_bf16 v[98:101], v[186:189], v[204:207], v[98:101]
	v_mfma_f32_16x16x32_bf16 v[90:93], v[178:181], v[212:215], v[90:93]
	v_mfma_f32_16x16x32_bf16 v[82:85], v[186:189], v[212:215], v[82:85]
	v_mfma_f32_16x16x32_bf16 v[30:33], v[178:181], v[220:223], v[30:33]
	v_mfma_f32_16x16x32_bf16 v[2:5], v[186:189], v[220:223], v[2:5]
	v_mfma_f32_16x16x32_bf16 v[122:125], v[182:185], v[200:203], v[122:125]
	v_mfma_f32_16x16x32_bf16 v[114:117], v[190:193], v[200:203], v[114:117]
	v_mfma_f32_16x16x32_bf16 v[106:109], v[182:185], v[208:211], v[106:109]
	v_mfma_f32_16x16x32_bf16 v[98:101], v[190:193], v[208:211], v[98:101]
	v_mfma_f32_16x16x32_bf16 v[90:93], v[182:185], v[216:219], v[90:93]
	v_mfma_f32_16x16x32_bf16 v[82:85], v[190:193], v[216:219], v[82:85]
	v_mfma_f32_16x16x32_bf16 v[30:33], v[182:185], v[224:227], v[30:33]
	v_mfma_f32_16x16x32_bf16 v[2:5], v[190:193], v[224:227], v[2:5]
	s_setprio 0
	s_barrier
	s_add_i32 s73, 0, 0x18000
	v_add_u32_e32 v165, s73, v160
	s_add_i32 s74, 0, 0x1c000
	ds_read_b128 v[156:159], v165
	ds_read_b128 v[166:169], v165 offset:1024
	ds_read_b128 v[170:173], v165 offset:2048
	ds_read_b128 v[174:177], v165 offset:3072
	v_add_u32_e32 v165, s74, v160
	ds_read_b128 v[178:181], v165
	ds_read_b128 v[182:185], v165 offset:1024
	ds_read_b128 v[186:189], v165 offset:2048
	ds_read_b128 v[190:193], v165 offset:3072
	s_add_u32 s46, s46, 0x100000
	s_addc_u32 s47, s47, 0
	s_mov_b32 m0, s51
	v_lshl_add_u64 v[236:237], s[46:47], 0, v[132:133]
	ds_read_b128 v[196:199], v164 offset:32768
	ds_read_b128 v[200:203], v164 offset:33792
	ds_read_b128 v[204:207], v164 offset:34816
	ds_read_b128 v[208:211], v164 offset:35840
	ds_read_b128 v[212:215], v164 offset:36864
	ds_read_b128 v[216:219], v164 offset:37888
	ds_read_b128 v[220:223], v164 offset:38912
	ds_read_b128 v[224:227], v164 offset:39936
	global_load_lds_dwordx4 v[236:237], off
	v_lshl_add_u64 v[236:237], s[46:47], 0, v[136:137]
	s_mov_b32 m0, s52
	s_nop 0
	global_load_lds_dwordx4 v[236:237], off
	s_branch .Lal64_66
	s_nop 0
	s_nop 0
	s_nop 0
	s_nop 0
	s_nop 0
.Lal64_66:
	s_waitcnt vmcnt(8)
	s_waitcnt lgkmcnt(0)
	s_barrier
	s_setprio 1
	v_mfma_f32_16x16x32_bf16 v[78:81], v[156:159], v[196:199], v[78:81]
	v_mfma_f32_16x16x32_bf16 v[74:77], v[170:173], v[196:199], v[74:77]
	v_mfma_f32_16x16x32_bf16 v[70:73], v[156:159], v[204:207], v[70:73]
	v_mfma_f32_16x16x32_bf16 v[62:65], v[170:173], v[204:207], v[62:65]
	v_mfma_f32_16x16x32_bf16 v[58:61], v[156:159], v[212:215], v[58:61]
	v_mfma_f32_16x16x32_bf16 v[54:57], v[170:173], v[212:215], v[54:57]
	v_mfma_f32_16x16x32_bf16 v[46:49], v[156:159], v[220:223], v[46:49]
	v_mfma_f32_16x16x32_bf16 v[38:41], v[170:173], v[220:223], v[38:41]
	v_mfma_f32_16x16x32_bf16 v[78:81], v[166:169], v[200:203], v[78:81]
	v_mfma_f32_16x16x32_bf16 v[74:77], v[174:177], v[200:203], v[74:77]
	v_mfma_f32_16x16x32_bf16 v[70:73], v[166:169], v[208:211], v[70:73]
	v_mfma_f32_16x16x32_bf16 v[62:65], v[174:177], v[208:211], v[62:65]
	v_mfma_f32_16x16x32_bf16 v[58:61], v[166:169], v[216:219], v[58:61]
	v_mfma_f32_16x16x32_bf16 v[54:57], v[174:177], v[216:219], v[54:57]
	v_mfma_f32_16x16x32_bf16 v[46:49], v[166:169], v[224:227], v[46:49]
	v_mfma_f32_16x16x32_bf16 v[38:41], v[174:177], v[224:227], v[38:41]
	v_mfma_f32_16x16x32_bf16 v[50:53], v[178:181], v[196:199], v[50:53]
	v_mfma_f32_16x16x32_bf16 v[42:45], v[186:189], v[196:199], v[42:45]
	v_mfma_f32_16x16x32_bf16 v[34:37], v[178:181], v[204:207], v[34:37]
	v_mfma_f32_16x16x32_bf16 v[26:29], v[186:189], v[204:207], v[26:29]
	v_mfma_f32_16x16x32_bf16 v[18:21], v[178:181], v[212:215], v[18:21]
	v_mfma_f32_16x16x32_bf16 v[14:17], v[186:189], v[212:215], v[14:17]
	v_mfma_f32_16x16x32_bf16 v[10:13], v[178:181], v[220:223], v[10:13]
	v_mfma_f32_16x16x32_bf16 v[6:9], v[186:189], v[220:223], v[6:9]
	v_mfma_f32_16x16x32_bf16 v[50:53], v[182:185], v[200:203], v[50:53]
	v_mfma_f32_16x16x32_bf16 v[42:45], v[190:193], v[200:203], v[42:45]
	v_mfma_f32_16x16x32_bf16 v[34:37], v[182:185], v[208:211], v[34:37]
	v_mfma_f32_16x16x32_bf16 v[26:29], v[190:193], v[208:211], v[26:29]
	v_mfma_f32_16x16x32_bf16 v[18:21], v[182:185], v[216:219], v[18:21]
	v_mfma_f32_16x16x32_bf16 v[14:17], v[190:193], v[216:219], v[14:17]
	v_mfma_f32_16x16x32_bf16 v[10:13], v[182:185], v[224:227], v[10:13]
	v_mfma_f32_16x16x32_bf16 v[6:9], v[190:193], v[224:227], v[6:9]
	s_setprio 0
	s_barrier
	s_add_i32 s46, s73, s49
	v_lshl_add_u64 v[228:229], v[228:229], 0, s[10:11]
	s_mov_b32 m0, s46
	ds_read_b128 v[196:199], v164 offset:49152
	ds_read_b128 v[200:203], v164 offset:50176
	ds_read_b128 v[204:207], v164 offset:51200
	ds_read_b128 v[208:211], v164 offset:52224
	ds_read_b128 v[212:215], v164 offset:53248
	ds_read_b128 v[216:219], v164 offset:54272
	ds_read_b128 v[220:223], v164 offset:55296
	ds_read_b128 v[224:227], v164 offset:56320
	global_load_lds_dwordx4 v[228:229], off
	s_add_i32 m0, s46, 0x2000
	s_add_u32 s42, s42, 0x100080
	v_lshl_add_u64 v[228:229], v[230:231], 0, s[10:11]
	s_addc_u32 s43, s43, 0
	s_add_i32 s46, s74, s49
	global_load_lds_dwordx4 v[228:229], off
	v_lshl_add_u64 v[228:229], s[42:43], 0, v[134:135]
	s_mov_b32 m0, s46
	s_nop 0
	global_load_lds_dwordx4 v[228:229], off
	v_lshl_add_u64 v[228:229], s[42:43], 0, v[138:139]
	s_add_i32 m0, s46, 0x2000
	s_nop 0
	global_load_lds_dwordx4 v[228:229], off
	v_lshl_add_u64 v[228:229], v[232:233], 0, s[10:11]
	s_mov_b32 m0, s55
	s_nop 0
	global_load_lds_dwordx4 v[228:229], off
	v_lshl_add_u64 v[228:229], v[234:235], 0, s[10:11]
	s_mov_b32 m0, s56
	s_nop 0
	global_load_lds_dwordx4 v[228:229], off
	s_branch .Lal64_67
.Lal64_67:
	s_waitcnt vmcnt(8)
	s_waitcnt lgkmcnt(0)
	s_barrier
	s_setprio 1
	v_mfma_f32_16x16x32_bf16 v[126:129], v[156:159], v[196:199], v[126:129]
	v_mfma_f32_16x16x32_bf16 v[118:121], v[170:173], v[196:199], v[118:121]
	v_mfma_f32_16x16x32_bf16 v[110:113], v[156:159], v[204:207], v[110:113]
	v_mfma_f32_16x16x32_bf16 v[102:105], v[170:173], v[204:207], v[102:105]
	v_mfma_f32_16x16x32_bf16 v[94:97], v[156:159], v[212:215], v[94:97]
	v_mfma_f32_16x16x32_bf16 v[86:89], v[170:173], v[212:215], v[86:89]
	v_mfma_f32_16x16x32_bf16 v[66:69], v[156:159], v[220:223], v[66:69]
	v_mfma_f32_16x16x32_bf16 v[22:25], v[170:173], v[220:223], v[22:25]
	v_mfma_f32_16x16x32_bf16 v[126:129], v[166:169], v[200:203], v[126:129]
	v_mfma_f32_16x16x32_bf16 v[118:121], v[174:177], v[200:203], v[118:121]
	v_mfma_f32_16x16x32_bf16 v[110:113], v[166:169], v[208:211], v[110:113]
	v_mfma_f32_16x16x32_bf16 v[102:105], v[174:177], v[208:211], v[102:105]
	v_mfma_f32_16x16x32_bf16 v[94:97], v[166:169], v[216:219], v[94:97]
	v_mfma_f32_16x16x32_bf16 v[86:89], v[174:177], v[216:219], v[86:89]
	v_mfma_f32_16x16x32_bf16 v[66:69], v[166:169], v[224:227], v[66:69]
	v_mfma_f32_16x16x32_bf16 v[22:25], v[174:177], v[224:227], v[22:25]
	v_mfma_f32_16x16x32_bf16 v[122:125], v[178:181], v[196:199], v[122:125]
	v_mfma_f32_16x16x32_bf16 v[114:117], v[186:189], v[196:199], v[114:117]
	v_mfma_f32_16x16x32_bf16 v[106:109], v[178:181], v[204:207], v[106:109]
	v_mfma_f32_16x16x32_bf16 v[98:101], v[186:189], v[204:207], v[98:101]
	v_mfma_f32_16x16x32_bf16 v[90:93], v[178:181], v[212:215], v[90:93]
	v_mfma_f32_16x16x32_bf16 v[82:85], v[186:189], v[212:215], v[82:85]
	v_mfma_f32_16x16x32_bf16 v[30:33], v[178:181], v[220:223], v[30:33]
	v_mfma_f32_16x16x32_bf16 v[2:5], v[186:189], v[220:223], v[2:5]
	v_mfma_f32_16x16x32_bf16 v[122:125], v[182:185], v[200:203], v[122:125]
	v_mfma_f32_16x16x32_bf16 v[114:117], v[190:193], v[200:203], v[114:117]
	v_mfma_f32_16x16x32_bf16 v[106:109], v[182:185], v[208:211], v[106:109]
	v_mfma_f32_16x16x32_bf16 v[98:101], v[190:193], v[208:211], v[98:101]
	v_mfma_f32_16x16x32_bf16 v[90:93], v[182:185], v[216:219], v[90:93]
	v_mfma_f32_16x16x32_bf16 v[82:85], v[190:193], v[216:219], v[82:85]
	v_mfma_f32_16x16x32_bf16 v[30:33], v[182:185], v[224:227], v[30:33]
	v_mfma_f32_16x16x32_bf16 v[2:5], v[190:193], v[224:227], v[2:5]
	s_setprio 0
	s_barrier
	s_add_u32 s40, s40, 0x100
	s_addc_u32 s41, s41, 0
	s_add_u32 s70, s70, 0x100
	s_addc_u32 s71, s71, 0
	s_cmp_ge_i32 s72, s68
	s_mov_b32 s42, s72
	s_cbranch_scc0 .LBB0_4145
	s_and_b64 vcc, exec, s[12:13]
	s_cbranch_vccz .LBB0_4150
	s_barrier
	s_cmp_lt_i32 s48, 0
	s_mov_b64 s[40:41], -1
	s_cbranch_scc1 .LBB0_4151

.LBB0_4304:
	ds_read_b128 v[150:153], v158
	ds_read_b128 v[162:165], v158 offset:1024
	ds_read_b128 v[166:169], v158 offset:2048
	ds_read_b128 v[170:173], v158 offset:3072
	ds_read_b128 v[174:177], v159
	ds_read_b128 v[178:181], v159 offset:1024
	ds_read_b128 v[182:185], v159 offset:2048
	ds_read_b128 v[186:189], v159 offset:3072
	s_add_i32 s80, s48, 2
	s_add_u32 s49, s50, 0xffd50080
	s_addc_u32 s52, s51, -1
	s_cmp_eq_u32 s43, s48
	s_cselect_b32 s48, s46, s78
	s_cselect_b32 s53, s5, s52
	s_cselect_b32 s52, s4, s49
	s_cselect_b32 s49, s47, s79
	v_lshl_add_u64 v[154:155], s[50:51], 0, v[138:139]
	s_add_i32 m0, s55, 0xc000
	ds_read_b128 v[190:193], v160
	ds_read_b128 v[196:199], v160 offset:1024
	ds_read_b128 v[200:203], v160 offset:2048
	ds_read_b128 v[204:207], v160 offset:3072
	ds_read_b128 v[208:211], v160 offset:4096
	ds_read_b128 v[212:215], v160 offset:5120
	ds_read_b128 v[216:219], v160 offset:6144
	ds_read_b128 v[220:223], v160 offset:7168
	global_load_lds_dwordx4 v[154:155], off
	v_lshl_add_u64 v[154:155], s[50:51], 0, v[140:141]
	s_add_i32 m0, s55, 0xe000
	s_nop 0
	global_load_lds_dwordx4 v[154:155], off
	s_branch .Lal64_68
	s_nop 0
	s_nop 0
	s_nop 0
	s_nop 0
	s_nop 0
	s_nop 0
	s_nop 0
	s_nop 0
	s_nop 0
	s_nop 0
.Lal64_68:
	s_waitcnt vmcnt(8)
	s_waitcnt lgkmcnt(0)
	s_barrier
	s_setprio 1
	v_mfma_f32_16x16x32_bf16 v[124:127], v[150:153], v[190:193], v[124:127]
	v_mfma_f32_16x16x32_bf16 v[120:123], v[166:169], v[190:193], v[120:123]
	v_mfma_f32_16x16x32_bf16 v[108:111], v[150:153], v[200:203], v[108:111]
	v_mfma_f32_16x16x32_bf16 v[104:107], v[166:169], v[200:203], v[104:107]
	v_mfma_f32_16x16x32_bf16 v[92:95], v[150:153], v[208:211], v[92:95]
	v_mfma_f32_16x16x32_bf16 v[88:91], v[166:169], v[208:211], v[88:91]
	v_mfma_f32_16x16x32_bf16 v[76:79], v[150:153], v[216:219], v[76:79]
	v_mfma_f32_16x16x32_bf16 v[72:75], v[166:169], v[216:219], v[72:75]
	v_mfma_f32_16x16x32_bf16 v[124:127], v[162:165], v[196:199], v[124:127]
	v_mfma_f32_16x16x32_bf16 v[120:123], v[170:173], v[196:199], v[120:123]
	v_mfma_f32_16x16x32_bf16 v[108:111], v[162:165], v[204:207], v[108:111]
	v_mfma_f32_16x16x32_bf16 v[104:107], v[170:173], v[204:207], v[104:107]
	v_mfma_f32_16x16x32_bf16 v[92:95], v[162:165], v[212:215], v[92:95]
	v_mfma_f32_16x16x32_bf16 v[88:91], v[170:173], v[212:215], v[88:91]
	v_mfma_f32_16x16x32_bf16 v[76:79], v[162:165], v[220:223], v[76:79]
	v_mfma_f32_16x16x32_bf16 v[72:75], v[170:173], v[220:223], v[72:75]
	v_mfma_f32_16x16x32_bf16 v[116:119], v[174:177], v[190:193], v[116:119]
	v_mfma_f32_16x16x32_bf16 v[112:115], v[182:185], v[190:193], v[112:115]
	v_mfma_f32_16x16x32_bf16 v[100:103], v[174:177], v[200:203], v[100:103]
	v_mfma_f32_16x16x32_bf16 v[96:99], v[182:185], v[200:203], v[96:99]
	v_mfma_f32_16x16x32_bf16 v[84:87], v[174:177], v[208:211], v[84:87]
	v_mfma_f32_16x16x32_bf16 v[80:83], v[182:185], v[208:211], v[80:83]
	v_mfma_f32_16x16x32_bf16 v[68:71], v[174:177], v[216:219], v[68:71]
	v_mfma_f32_16x16x32_bf16 v[64:67], v[182:185], v[216:219], v[64:67]
	v_mfma_f32_16x16x32_bf16 v[116:119], v[178:181], v[196:199], v[116:119]
	v_mfma_f32_16x16x32_bf16 v[112:115], v[186:189], v[196:199], v[112:115]
	v_mfma_f32_16x16x32_bf16 v[100:103], v[178:181], v[204:207], v[100:103]
	v_mfma_f32_16x16x32_bf16 v[96:99], v[186:189], v[204:207], v[96:99]
	v_mfma_f32_16x16x32_bf16 v[84:87], v[178:181], v[212:215], v[84:87]
	v_mfma_f32_16x16x32_bf16 v[80:83], v[186:189], v[212:215], v[80:83]
	v_mfma_f32_16x16x32_bf16 v[68:71], v[178:181], v[220:223], v[68:71]
	v_mfma_f32_16x16x32_bf16 v[64:67], v[186:189], v[220:223], v[64:67]
	s_setprio 0
	s_barrier
	s_add_i32 s81, s65, s54
	v_lshl_add_u64 v[154:155], s[48:49], 0, v[132:133]
	s_mov_b32 m0, s81
	ds_read_b128 v[190:193], v160 offset:16384
	ds_read_b128 v[196:199], v160 offset:17408
	ds_read_b128 v[200:203], v160 offset:18432
	ds_read_b128 v[204:207], v160 offset:19456
	ds_read_b128 v[208:211], v160 offset:20480
	ds_read_b128 v[212:215], v160 offset:21504
	ds_read_b128 v[216:219], v160 offset:22528
	ds_read_b128 v[220:223], v160 offset:23552
	global_load_lds_dwordx4 v[154:155], off
	s_add_i32 m0, s81, 0x2000
	s_add_u32 s82, s48, 0x2b0000
	v_lshl_add_u64 v[224:225], s[48:49], 0, v[136:137]
	s_addc_u32 s83, s49, 0
	s_add_i32 s81, s66, s54
	global_load_lds_dwordx4 v[224:225], off
	v_lshl_add_u64 v[226:227], s[82:83], 0, v[132:133]
	s_mov_b32 m0, s81
	v_lshl_add_u64 v[228:229], s[52:53], 0, v[134:135]
	global_load_lds_dwordx4 v[226:227], off
	v_lshl_add_u64 v[226:227], s[82:83], 0, v[136:137]
	s_add_i32 m0, s81, 0x2000
	s_nop 0
	global_load_lds_dwordx4 v[226:227], off
	v_lshl_add_u64 v[226:227], s[52:53], 0, v[128:129]
	s_mov_b32 m0, s55
	s_nop 0
	global_load_lds_dwordx4 v[226:227], off
	s_mov_b32 m0, s56
	s_nop 0
	global_load_lds_dwordx4 v[228:229], off
	s_branch .Lal64_69
	s_nop 0
.Lal64_69:
	s_waitcnt vmcnt(8)
	s_waitcnt lgkmcnt(0)
	s_barrier
	s_setprio 1
	v_mfma_f32_16x16x32_bf16 v[60:63], v[150:153], v[190:193], v[60:63]
	v_mfma_f32_16x16x32_bf16 v[56:59], v[166:169], v[190:193], v[56:59]
	v_mfma_f32_16x16x32_bf16 v[44:47], v[150:153], v[200:203], v[44:47]
	v_mfma_f32_16x16x32_bf16 v[40:43], v[166:169], v[200:203], v[40:43]
	v_mfma_f32_16x16x32_bf16 v[28:31], v[150:153], v[208:211], v[28:31]
	v_mfma_f32_16x16x32_bf16 v[24:27], v[166:169], v[208:211], v[24:27]
	v_mfma_f32_16x16x32_bf16 v[12:15], v[150:153], v[216:219], v[12:15]
	v_mfma_f32_16x16x32_bf16 v[8:11], v[166:169], v[216:219], v[8:11]
	v_mfma_f32_16x16x32_bf16 v[60:63], v[162:165], v[196:199], v[60:63]
	v_mfma_f32_16x16x32_bf16 v[56:59], v[170:173], v[196:199], v[56:59]
	v_mfma_f32_16x16x32_bf16 v[44:47], v[162:165], v[204:207], v[44:47]
	v_mfma_f32_16x16x32_bf16 v[40:43], v[170:173], v[204:207], v[40:43]
	v_mfma_f32_16x16x32_bf16 v[28:31], v[162:165], v[212:215], v[28:31]
	v_mfma_f32_16x16x32_bf16 v[24:27], v[170:173], v[212:215], v[24:27]
	v_mfma_f32_16x16x32_bf16 v[12:15], v[162:165], v[220:223], v[12:15]
	v_mfma_f32_16x16x32_bf16 v[8:11], v[170:173], v[220:223], v[8:11]
	v_mfma_f32_16x16x32_bf16 v[52:55], v[174:177], v[190:193], v[52:55]
	v_mfma_f32_16x16x32_bf16 v[48:51], v[182:185], v[190:193], v[48:51]
	v_mfma_f32_16x16x32_bf16 v[36:39], v[174:177], v[200:203], v[36:39]
	v_mfma_f32_16x16x32_bf16 v[32:35], v[182:185], v[200:203], v[32:35]
	v_mfma_f32_16x16x32_bf16 v[20:23], v[174:177], v[208:211], v[20:23]
	v_mfma_f32_16x16x32_bf16 v[16:19], v[182:185], v[208:211], v[16:19]
	v_mfma_f32_16x16x32_bf16 v[4:7], v[174:177], v[216:219], v[4:7]
	v_mfma_f32_16x16x32_bf16 v[0:3], v[182:185], v[216:219], v[0:3]
	v_mfma_f32_16x16x32_bf16 v[52:55], v[178:181], v[196:199], v[52:55]
	v_mfma_f32_16x16x32_bf16 v[48:51], v[186:189], v[196:199], v[48:51]
	v_mfma_f32_16x16x32_bf16 v[36:39], v[178:181], v[204:207], v[36:39]
	v_mfma_f32_16x16x32_bf16 v[32:35], v[186:189], v[204:207], v[32:35]
	v_mfma_f32_16x16x32_bf16 v[20:23], v[178:181], v[212:215], v[20:23]
	v_mfma_f32_16x16x32_bf16 v[16:19], v[186:189], v[212:215], v[16:19]
	v_mfma_f32_16x16x32_bf16 v[4:7], v[178:181], v[220:223], v[4:7]
	v_mfma_f32_16x16x32_bf16 v[0:3], v[186:189], v[220:223], v[0:3]
	s_setprio 0
	s_barrier
	s_add_i32 s81, 0, 0x18000
	v_add_u32_e32 v161, s81, v156
	s_add_i32 s82, 0, 0x1c000
	ds_read_b128 v[150:153], v161
	ds_read_b128 v[162:165], v161 offset:1024
	ds_read_b128 v[166:169], v161 offset:2048
	ds_read_b128 v[170:173], v161 offset:3072
	v_add_u32_e32 v161, s82, v156
	ds_read_b128 v[174:177], v161
	ds_read_b128 v[178:181], v161 offset:1024
	ds_read_b128 v[182:185], v161 offset:2048
	ds_read_b128 v[186:189], v161 offset:3072
	s_add_u32 s52, s52, 0x2b0000
	s_addc_u32 s53, s53, 0
	s_mov_b32 m0, s57
	v_lshl_add_u64 v[230:231], s[52:53], 0, v[128:129]
	ds_read_b128 v[190:193], v160 offset:32768
	ds_read_b128 v[196:199], v160 offset:33792
	ds_read_b128 v[200:203], v160 offset:34816
	ds_read_b128 v[204:207], v160 offset:35840
	ds_read_b128 v[208:211], v160 offset:36864
	ds_read_b128 v[212:215], v160 offset:37888
	ds_read_b128 v[216:219], v160 offset:38912
	ds_read_b128 v[220:223], v160 offset:39936
	global_load_lds_dwordx4 v[230:231], off
	v_lshl_add_u64 v[230:231], s[52:53], 0, v[134:135]
	s_mov_b32 m0, s58
	s_nop 0
	global_load_lds_dwordx4 v[230:231], off
	s_branch .Lal64_70
	s_nop 0
	s_nop 0
	s_nop 0
	s_nop 0
	s_nop 0
.Lal64_70:
	s_waitcnt vmcnt(8)
	s_waitcnt lgkmcnt(0)
	s_barrier
	s_setprio 1
	v_mfma_f32_16x16x32_bf16 v[124:127], v[150:153], v[190:193], v[124:127]
	v_mfma_f32_16x16x32_bf16 v[120:123], v[166:169], v[190:193], v[120:123]
	v_mfma_f32_16x16x32_bf16 v[108:111], v[150:153], v[200:203], v[108:111]
	v_mfma_f32_16x16x32_bf16 v[104:107], v[166:169], v[200:203], v[104:107]
	v_mfma_f32_16x16x32_bf16 v[92:95], v[150:153], v[208:211], v[92:95]
	v_mfma_f32_16x16x32_bf16 v[88:91], v[166:169], v[208:211], v[88:91]
	v_mfma_f32_16x16x32_bf16 v[76:79], v[150:153], v[216:219], v[76:79]
	v_mfma_f32_16x16x32_bf16 v[72:75], v[166:169], v[216:219], v[72:75]
	v_mfma_f32_16x16x32_bf16 v[124:127], v[162:165], v[196:199], v[124:127]
	v_mfma_f32_16x16x32_bf16 v[120:123], v[170:173], v[196:199], v[120:123]
	v_mfma_f32_16x16x32_bf16 v[108:111], v[162:165], v[204:207], v[108:111]
	v_mfma_f32_16x16x32_bf16 v[104:107], v[170:173], v[204:207], v[104:107]
	v_mfma_f32_16x16x32_bf16 v[92:95], v[162:165], v[212:215], v[92:95]
	v_mfma_f32_16x16x32_bf16 v[88:91], v[170:173], v[212:215], v[88:91]
	v_mfma_f32_16x16x32_bf16 v[76:79], v[162:165], v[220:223], v[76:79]
	v_mfma_f32_16x16x32_bf16 v[72:75], v[170:173], v[220:223], v[72:75]
	v_mfma_f32_16x16x32_bf16 v[116:119], v[174:177], v[190:193], v[116:119]
	v_mfma_f32_16x16x32_bf16 v[112:115], v[182:185], v[190:193], v[112:115]
	v_mfma_f32_16x16x32_bf16 v[100:103], v[174:177], v[200:203], v[100:103]
	v_mfma_f32_16x16x32_bf16 v[96:99], v[182:185], v[200:203], v[96:99]
	v_mfma_f32_16x16x32_bf16 v[84:87], v[174:177], v[208:211], v[84:87]
	v_mfma_f32_16x16x32_bf16 v[80:83], v[182:185], v[208:211], v[80:83]
	v_mfma_f32_16x16x32_bf16 v[68:71], v[174:177], v[216:219], v[68:71]
	v_mfma_f32_16x16x32_bf16 v[64:67], v[182:185], v[216:219], v[64:67]
	v_mfma_f32_16x16x32_bf16 v[116:119], v[178:181], v[196:199], v[116:119]
	v_mfma_f32_16x16x32_bf16 v[112:115], v[186:189], v[196:199], v[112:115]
	v_mfma_f32_16x16x32_bf16 v[100:103], v[178:181], v[204:207], v[100:103]
	v_mfma_f32_16x16x32_bf16 v[96:99], v[186:189], v[204:207], v[96:99]
	v_mfma_f32_16x16x32_bf16 v[84:87], v[178:181], v[212:215], v[84:87]
	v_mfma_f32_16x16x32_bf16 v[80:83], v[186:189], v[212:215], v[80:83]
	v_mfma_f32_16x16x32_bf16 v[68:71], v[178:181], v[220:223], v[68:71]
	v_mfma_f32_16x16x32_bf16 v[64:67], v[186:189], v[220:223], v[64:67]
	s_setprio 0
	s_barrier
	s_add_i32 s52, s81, s54
	v_lshl_add_u64 v[154:155], v[154:155], 0, s[14:15]
	s_mov_b32 m0, s52
	ds_read_b128 v[190:193], v160 offset:49152
	ds_read_b128 v[196:199], v160 offset:50176
	ds_read_b128 v[200:203], v160 offset:51200
	ds_read_b128 v[204:207], v160 offset:52224
	ds_read_b128 v[208:211], v160 offset:53248
	ds_read_b128 v[212:215], v160 offset:54272
	ds_read_b128 v[216:219], v160 offset:55296
	ds_read_b128 v[220:223], v160 offset:56320
	global_load_lds_dwordx4 v[154:155], off
	s_add_i32 m0, s52, 0x2000
	s_add_u32 s48, s48, 0x2b0080
	v_lshl_add_u64 v[154:155], v[224:225], 0, s[14:15]
	s_addc_u32 s49, s49, 0
	s_add_i32 s52, s82, s54
	global_load_lds_dwordx4 v[154:155], off
	v_lshl_add_u64 v[154:155], s[48:49], 0, v[132:133]
	s_mov_b32 m0, s52
	s_nop 0
	global_load_lds_dwordx4 v[154:155], off
	v_lshl_add_u64 v[154:155], s[48:49], 0, v[136:137]
	s_add_i32 m0, s52, 0x2000
	s_nop 0
	global_load_lds_dwordx4 v[154:155], off
	v_lshl_add_u64 v[154:155], v[226:227], 0, s[14:15]
	s_mov_b32 m0, s62
	s_nop 0
	global_load_lds_dwordx4 v[154:155], off
	v_lshl_add_u64 v[154:155], v[228:229], 0, s[14:15]
	s_mov_b32 m0, s63
	s_nop 0
	global_load_lds_dwordx4 v[154:155], off
	s_branch .Lal64_71
.Lal64_71:
	s_waitcnt vmcnt(8)
	s_waitcnt lgkmcnt(0)
	s_barrier
	s_setprio 1
	v_mfma_f32_16x16x32_bf16 v[60:63], v[150:153], v[190:193], v[60:63]
	v_mfma_f32_16x16x32_bf16 v[56:59], v[166:169], v[190:193], v[56:59]
	v_mfma_f32_16x16x32_bf16 v[44:47], v[150:153], v[200:203], v[44:47]
	v_mfma_f32_16x16x32_bf16 v[40:43], v[166:169], v[200:203], v[40:43]
	v_mfma_f32_16x16x32_bf16 v[28:31], v[150:153], v[208:211], v[28:31]
	v_mfma_f32_16x16x32_bf16 v[24:27], v[166:169], v[208:211], v[24:27]
	v_mfma_f32_16x16x32_bf16 v[12:15], v[150:153], v[216:219], v[12:15]
	v_mfma_f32_16x16x32_bf16 v[8:11], v[166:169], v[216:219], v[8:11]
	v_mfma_f32_16x16x32_bf16 v[60:63], v[162:165], v[196:199], v[60:63]
	v_mfma_f32_16x16x32_bf16 v[56:59], v[170:173], v[196:199], v[56:59]
	v_mfma_f32_16x16x32_bf16 v[44:47], v[162:165], v[204:207], v[44:47]
	v_mfma_f32_16x16x32_bf16 v[40:43], v[170:173], v[204:207], v[40:43]
	v_mfma_f32_16x16x32_bf16 v[28:31], v[162:165], v[212:215], v[28:31]
	v_mfma_f32_16x16x32_bf16 v[24:27], v[170:173], v[212:215], v[24:27]
	v_mfma_f32_16x16x32_bf16 v[12:15], v[162:165], v[220:223], v[12:15]
	v_mfma_f32_16x16x32_bf16 v[8:11], v[170:173], v[220:223], v[8:11]
	v_mfma_f32_16x16x32_bf16 v[52:55], v[174:177], v[190:193], v[52:55]
	v_mfma_f32_16x16x32_bf16 v[48:51], v[182:185], v[190:193], v[48:51]
	v_mfma_f32_16x16x32_bf16 v[36:39], v[174:177], v[200:203], v[36:39]
	v_mfma_f32_16x16x32_bf16 v[32:35], v[182:185], v[200:203], v[32:35]
	v_mfma_f32_16x16x32_bf16 v[20:23], v[174:177], v[208:211], v[20:23]
	v_mfma_f32_16x16x32_bf16 v[16:19], v[182:185], v[208:211], v[16:19]
	v_mfma_f32_16x16x32_bf16 v[4:7], v[174:177], v[216:219], v[4:7]
	v_mfma_f32_16x16x32_bf16 v[0:3], v[182:185], v[216:219], v[0:3]
	v_mfma_f32_16x16x32_bf16 v[52:55], v[178:181], v[196:199], v[52:55]
	v_mfma_f32_16x16x32_bf16 v[48:51], v[186:189], v[196:199], v[48:51]
	v_mfma_f32_16x16x32_bf16 v[36:39], v[178:181], v[204:207], v[36:39]
	v_mfma_f32_16x16x32_bf16 v[32:35], v[186:189], v[204:207], v[32:35]
	v_mfma_f32_16x16x32_bf16 v[20:23], v[178:181], v[212:215], v[20:23]
	v_mfma_f32_16x16x32_bf16 v[16:19], v[186:189], v[212:215], v[16:19]
	v_mfma_f32_16x16x32_bf16 v[4:7], v[178:181], v[220:223], v[4:7]
	v_mfma_f32_16x16x32_bf16 v[0:3], v[186:189], v[220:223], v[0:3]
	s_setprio 0
	s_barrier
	s_add_u32 s50, s50, 0x100
	s_addc_u32 s51, s51, 0
	s_add_u32 s78, s78, 0x100
	s_addc_u32 s79, s79, 0
	s_cmp_ge_i32 s80, s76
	s_mov_b32 s48, s80
	s_cbranch_scc0 .LBB0_4304
	s_and_b64 vcc, exec, s[16:17]
	s_cbranch_vccz .LBB0_4307
	s_barrier
